# v6 plus: redundant post-barrier lgkmcnt wait removed and the two asm waits fused in every K-loop segment
# baseline (speedup 1.0000x reference)
;     __device__ __forceinline__ void a_ready(const Unit& u) const { wait_panel(cnt, u.pm, need, tmo, wave); }
;     __device__ __forceinline__ void a_ready(const Unit& u) const { wait_panel(cnt, u.pm, need, tmo, wave); }
; #define PG8_STAGE(bufoff, gbase, voff) do { _Pragma("unroll") for (int _i = 0; _i < 2; ++_i) \
;         __builtin_amdgcn_global_load_lds((const unsigned*)((const char*)(gbase) + (voff)[_i]), (PG8_LAS unsigned*)(lds + (bufoff) + ldsw + _i * 8192), 16, 0, 0); } while (0)
; #define PG8_LDA(dst, b, h) do { _Pragma("unroll") for (int m = 0; m < 4; ++m) _Pragma("unroll") for (int k = 0; k < 2; ++k) dst[m][k] = *(const PG8_LAS bf16x8*)(lds + PG8_SA(b, h) + aoff + m * 2048 + k * 1024); } while (0)
; #define PG8_LDB(dst, b, h) do { _Pragma("unroll") for (int n = 0; n < 2; ++n) _Pragma("unroll") for (int k = 0; k < 2; ++k) dst[n][k] = *(const PG8_LAS bf16x8*)(lds + PG8_SB(b, h) + boff + n * 2048 + k * 1024); } while (0)
; #define PG8_WAIT_V(n) asm volatile("s_waitcnt vmcnt(" #n ")" ::: "memory")
; #define PG8_WAIT_L(n) asm volatile("s_waitcnt lgkmcnt(" #n ")" ::: "memory")
; #define PG8_BAR __builtin_amdgcn_s_barrier()
; #define PG8_SCHED __builtin_amdgcn_sched_barrier(0)
; template <class Epi, class Sched, bool ALIGN_EPI = false, bool SP2 = false>
; __device__ __forceinline__ void gemm_phase(PG8_LAS unsigned char* lds, const Gemm g, const Sched& S, const Epi& E, const int tid_in) {
;     ...
;         for (int t = 0; t < nt; t += 2) {
;             const bool last = (t == nt - 2);
;             const char* a1 = cA + (size_t)(t + 1) * kstep;
;             const char* a2 = last ? nA : cA + (size_t)(t + 2) * kstep; const char* b2 = last ? nB : cB + (size_t)(t + 2) * kstep;
;             const char* a3 = a2 + kstep; const char* b3 = b2 + kstep;
;             if (last && has_next) S.a_ready(nxt);
;             if constexpr (SP2) {
;             PG8_LDB(B0, 0, 0); PG8_LDB(B1, 0, 1); PG8_SCHED; PG8_LDA(At, 0, 0); PG8_STAGE(PG8_SA(1, 1), a1 + hstepA, voffA);
;             PG8_WAIT_V(8); PG8_WAIT_L(0); PG8_BAR; PG8_MMA(0, 0, At, B0); PG8_MMA(0, 1, At, B1); PG8_BAR; PG8_SCHED;
;             PG8_LDA(At, 0, 1); PG8_STAGE(PG8_SB(0, 0), b2, voffB); PG8_STAGE(PG8_SB(0, 1), b2 + hstepB, voffB); PG8_STAGE(PG8_SA(0, 0), a2, voffA);
;             PG8_WAIT_V(8); PG8_WAIT_L(0); PG8_BAR; PG8_MMA(1, 0, At, B0); PG8_MMA(1, 1, At, B1); PG8_BAR; PG8_SCHED;
.LBB0_476:
	s_add_u32 s22, s52, 0xfff80080
	s_addc_u32 s23, s53, -1
	s_add_i32 s45, 0, 0x10000
	s_cmp_eq_u32 s43, 28
	s_cselect_b32 s55, s6, s23
	s_cselect_b32 s54, s11, s22
	s_cselect_b32 s23, s12, s35
	s_cselect_b32 s22, s33, s34
	s_add_i32 s47, 0, 0x14000
	ds_read_b128 v[138:141], v249
	ds_read_b128 v[150:153], v249 offset:1024
	ds_read_b128 v[154:157], v249 offset:2048
	ds_read_b128 v[158:161], v249 offset:3072
	ds_read_b128 v[162:165], v249 offset:16384
	ds_read_b128 v[166:169], v249 offset:17408
	ds_read_b128 v[190:193], v249 offset:18432
	ds_read_b128 v[194:197], v249 offset:19456
	s_add_i32 m0, s21, 0xc000
	ds_read_b128 v[198:201], v148
	ds_read_b128 v[202:205], v148 offset:1024
	ds_read_b128 v[206:209], v148 offset:2048
	ds_read_b128 v[210:213], v148 offset:3072
	ds_read_b128 v[224:227], v148 offset:4096
	ds_read_b128 v[228:231], v148 offset:5120
	ds_read_b128 v[232:235], v148 offset:6144
	ds_read_b128 v[236:239], v148 offset:7168
	global_load_lds_dwordx4 v134, s[52:53]
	s_add_i32 m0, s21, 0xe000
	s_nop 0
	global_load_lds_dwordx4 v136, s[52:53]
	s_waitcnt vmcnt(8) lgkmcnt(0)
	s_barrier
	v_mfma_f32_16x16x32_bf16 v[124:127], v[138:141], v[198:201], v[124:127]
	v_mfma_f32_16x16x32_bf16 v[120:123], v[154:157], v[198:201], v[120:123]
	v_mfma_f32_16x16x32_bf16 v[108:111], v[138:141], v[206:209], v[108:111]
	v_mfma_f32_16x16x32_bf16 v[104:107], v[154:157], v[206:209], v[104:107]
	v_mfma_f32_16x16x32_bf16 v[92:95], v[138:141], v[224:227], v[92:95]
	v_mfma_f32_16x16x32_bf16 v[88:91], v[154:157], v[224:227], v[88:91]
	v_mfma_f32_16x16x32_bf16 v[76:79], v[138:141], v[232:235], v[76:79]
	v_mfma_f32_16x16x32_bf16 v[72:75], v[154:157], v[232:235], v[72:75]
	v_mfma_f32_16x16x32_bf16 v[124:127], v[150:153], v[202:205], v[124:127]
	v_mfma_f32_16x16x32_bf16 v[120:123], v[158:161], v[202:205], v[120:123]
	v_mfma_f32_16x16x32_bf16 v[108:111], v[150:153], v[210:213], v[108:111]
	v_mfma_f32_16x16x32_bf16 v[104:107], v[158:161], v[210:213], v[104:107]
	v_mfma_f32_16x16x32_bf16 v[92:95], v[150:153], v[228:231], v[92:95]
	v_mfma_f32_16x16x32_bf16 v[88:91], v[158:161], v[228:231], v[88:91]
	v_mfma_f32_16x16x32_bf16 v[76:79], v[150:153], v[236:239], v[76:79]
	v_mfma_f32_16x16x32_bf16 v[72:75], v[158:161], v[236:239], v[72:75]
	v_mfma_f32_16x16x32_bf16 v[116:119], v[162:165], v[198:201], v[116:119]
	v_mfma_f32_16x16x32_bf16 v[112:115], v[190:193], v[198:201], v[112:115]
	v_mfma_f32_16x16x32_bf16 v[100:103], v[162:165], v[206:209], v[100:103]
	v_mfma_f32_16x16x32_bf16 v[96:99], v[190:193], v[206:209], v[96:99]
	v_mfma_f32_16x16x32_bf16 v[84:87], v[162:165], v[224:227], v[84:87]
	v_mfma_f32_16x16x32_bf16 v[80:83], v[190:193], v[224:227], v[80:83]
	v_mfma_f32_16x16x32_bf16 v[68:71], v[162:165], v[232:235], v[68:71]
	v_mfma_f32_16x16x32_bf16 v[64:67], v[190:193], v[232:235], v[64:67]
	v_mfma_f32_16x16x32_bf16 v[116:119], v[166:169], v[202:205], v[116:119]
	v_mfma_f32_16x16x32_bf16 v[112:115], v[194:197], v[202:205], v[112:115]
	v_mfma_f32_16x16x32_bf16 v[100:103], v[166:169], v[210:213], v[100:103]
	v_mfma_f32_16x16x32_bf16 v[96:99], v[194:197], v[210:213], v[96:99]
	v_mfma_f32_16x16x32_bf16 v[84:87], v[166:169], v[228:231], v[84:87]
	v_mfma_f32_16x16x32_bf16 v[80:83], v[194:197], v[228:231], v[80:83]
	v_mfma_f32_16x16x32_bf16 v[68:71], v[166:169], v[236:239], v[68:71]
	v_mfma_f32_16x16x32_bf16 v[64:67], v[194:197], v[236:239], v[64:67]
	s_barrier
	s_add_i32 s45, s45, s20
	s_mov_b32 m0, s45
	ds_read_b128 v[198:201], v148 offset:16384
	ds_read_b128 v[202:205], v148 offset:17408
	ds_read_b128 v[206:209], v148 offset:18432
	ds_read_b128 v[210:213], v148 offset:19456
	ds_read_b128 v[224:227], v148 offset:20480
	ds_read_b128 v[228:231], v148 offset:21504
	ds_read_b128 v[232:235], v148 offset:22528
	ds_read_b128 v[236:239], v148 offset:23552
	global_load_lds_dwordx4 v172, s[22:23]
	s_add_i32 m0, s45, 0x2000
	s_add_u32 s60, s22, 0x80000
	s_addc_u32 s61, s23, 0
	s_add_i32 s45, s47, s20
	global_load_lds_dwordx4 v132, s[22:23]
	s_mov_b32 m0, s45
	s_nop 0
	global_load_lds_dwordx4 v172, s[60:61]
	s_add_i32 m0, s45, 0x2000
	s_nop 0
	global_load_lds_dwordx4 v132, s[60:61]
	s_mov_b32 m0, s21
	s_nop 0
	global_load_lds_dwordx4 v128, s[54:55]
	s_mov_b32 m0, s30
	s_nop 0
	global_load_lds_dwordx4 v130, s[54:55]
	s_waitcnt vmcnt(8) lgkmcnt(0)
	s_barrier
	v_mfma_f32_16x16x32_bf16 v[60:63], v[138:141], v[198:201], v[60:63]
	v_mfma_f32_16x16x32_bf16 v[56:59], v[154:157], v[198:201], v[56:59]
	v_mfma_f32_16x16x32_bf16 v[44:47], v[138:141], v[206:209], v[44:47]
	v_mfma_f32_16x16x32_bf16 v[40:43], v[154:157], v[206:209], v[40:43]
	v_mfma_f32_16x16x32_bf16 v[28:31], v[138:141], v[224:227], v[28:31]
	v_mfma_f32_16x16x32_bf16 v[24:27], v[154:157], v[224:227], v[24:27]
	v_mfma_f32_16x16x32_bf16 v[12:15], v[138:141], v[232:235], v[12:15]
	v_mfma_f32_16x16x32_bf16 v[8:11], v[154:157], v[232:235], v[8:11]
	v_mfma_f32_16x16x32_bf16 v[60:63], v[150:153], v[202:205], v[60:63]
	v_mfma_f32_16x16x32_bf16 v[56:59], v[158:161], v[202:205], v[56:59]
	v_mfma_f32_16x16x32_bf16 v[44:47], v[150:153], v[210:213], v[44:47]
	v_mfma_f32_16x16x32_bf16 v[40:43], v[158:161], v[210:213], v[40:43]
	v_mfma_f32_16x16x32_bf16 v[28:31], v[150:153], v[228:231], v[28:31]
	v_mfma_f32_16x16x32_bf16 v[24:27], v[158:161], v[228:231], v[24:27]
	v_mfma_f32_16x16x32_bf16 v[12:15], v[150:153], v[236:239], v[12:15]
	v_mfma_f32_16x16x32_bf16 v[8:11], v[158:161], v[236:239], v[8:11]
	v_mfma_f32_16x16x32_bf16 v[52:55], v[162:165], v[198:201], v[52:55]
	v_mfma_f32_16x16x32_bf16 v[48:51], v[190:193], v[198:201], v[48:51]
	v_mfma_f32_16x16x32_bf16 v[36:39], v[162:165], v[206:209], v[36:39]
	v_mfma_f32_16x16x32_bf16 v[32:35], v[190:193], v[206:209], v[32:35]
	v_mfma_f32_16x16x32_bf16 v[20:23], v[162:165], v[224:227], v[20:23]
	v_mfma_f32_16x16x32_bf16 v[16:19], v[190:193], v[224:227], v[16:19]
	v_mfma_f32_16x16x32_bf16 v[4:7], v[162:165], v[232:235], v[4:7]
	v_mfma_f32_16x16x32_bf16 v[0:3], v[190:193], v[232:235], v[0:3]
	v_mfma_f32_16x16x32_bf16 v[52:55], v[166:169], v[202:205], v[52:55]
	v_mfma_f32_16x16x32_bf16 v[48:51], v[194:197], v[202:205], v[48:51]
	v_mfma_f32_16x16x32_bf16 v[36:39], v[166:169], v[210:213], v[36:39]
	v_mfma_f32_16x16x32_bf16 v[32:35], v[194:197], v[210:213], v[32:35]
	v_mfma_f32_16x16x32_bf16 v[20:23], v[166:169], v[228:231], v[20:23]
	v_mfma_f32_16x16x32_bf16 v[16:19], v[194:197], v[228:231], v[16:19]
	v_mfma_f32_16x16x32_bf16 v[4:7], v[166:169], v[236:239], v[4:7]
	v_mfma_f32_16x16x32_bf16 v[0:3], v[194:197], v[236:239], v[0:3]
	s_barrier
; #define PG8_STAGE(bufoff, gbase, voff) do { _Pragma("unroll") for (int _i = 0; _i < 2; ++_i) \
;         __builtin_amdgcn_global_load_lds((const unsigned*)((const char*)(gbase) + (voff)[_i]), (PG8_LAS unsigned*)(lds + (bufoff) + ldsw + _i * 8192), 16, 0, 0); } while (0)
; #define PG8_LDA(dst, b, h) do { _Pragma("unroll") for (int m = 0; m < 4; ++m) _Pragma("unroll") for (int k = 0; k < 2; ++k) dst[m][k] = *(const PG8_LAS bf16x8*)(lds + PG8_SA(b, h) + aoff + m * 2048 + k * 1024); } while (0)
; #define PG8_LDB(dst, b, h) do { _Pragma("unroll") for (int n = 0; n < 2; ++n) _Pragma("unroll") for (int k = 0; k < 2; ++k) dst[n][k] = *(const PG8_LAS bf16x8*)(lds + PG8_SB(b, h) + boff + n * 2048 + k * 1024); } while (0)
; #define PG8_MMA(ai, bj, At, Bt) do { __builtin_amdgcn_s_setprio(1); _Pragma("unroll") for (int m = 0; m < 4; ++m) _Pragma("unroll") for (int n = 0; n < 2; ++n) _Pragma("unroll") for (int k = 0; k < 2; ++k) \
;         acc[ai][bj][m][n] = __builtin_amdgcn_mfma_f32_16x16x32_bf16(Bt[n][k], At[m][k], acc[ai][bj][m][n], 0, 0, 0); __builtin_amdgcn_s_setprio(0); } while (0)
; #define PG8_WAIT_V(n) asm volatile("s_waitcnt vmcnt(" #n ")" ::: "memory")
; #define PG8_WAIT_L(n) asm volatile("s_waitcnt lgkmcnt(" #n ")" ::: "memory")
; #define PG8_BAR __builtin_amdgcn_s_barrier()
; #define PG8_SCHED __builtin_amdgcn_sched_barrier(0)
; template <class Epi, class Sched, bool ALIGN_EPI = false, bool SP2 = false>
; __device__ __forceinline__ void gemm_phase(PG8_LAS unsigned char* lds, const Gemm g, const Sched& S, const Epi& E, const int tid_in) {
;     ...
;             PG8_LDB(B0, 1, 0); PG8_LDB(B1, 1, 1); PG8_SCHED; PG8_LDA(At, 1, 0); PG8_STAGE(PG8_SA(0, 1), a2 + hstepA, voffA);
;             PG8_WAIT_V(8); PG8_WAIT_L(0); PG8_BAR; PG8_MMA(0, 0, At, B0); PG8_MMA(0, 1, At, B1); PG8_BAR; PG8_SCHED;
;             PG8_LDA(At, 1, 1); PG8_STAGE(PG8_SB(1, 0), b3, voffB); PG8_STAGE(PG8_SB(1, 1), b3 + hstepB, voffB); PG8_STAGE(PG8_SA(1, 0), a3, voffA);
;             PG8_WAIT_V(8); PG8_WAIT_L(0); PG8_BAR; PG8_MMA(1, 0, At, B0); PG8_MMA(1, 1, At, B1); PG8_BAR; PG8_SCHED;
;     ...
;         if constexpr (ALIGN_EPI) { if (wr == 0) PG8_BAR; }
	s_add_i32 s45, 0, 0x18000
	s_add_i32 s47, 0, 0x1c000
	ds_read_b128 v[138:141], v249 offset:32768
	ds_read_b128 v[150:153], v249 offset:33792
	ds_read_b128 v[154:157], v249 offset:34816
	ds_read_b128 v[158:161], v249 offset:35840
	ds_read_b128 v[162:165], v249 offset:49152
	ds_read_b128 v[166:169], v249 offset:50176
	ds_read_b128 v[190:193], v249 offset:51200
	ds_read_b128 v[194:197], v249 offset:52224
	s_add_u32 s54, s54, 0x80000
	s_addc_u32 s55, s55, 0
	s_mov_b32 m0, s31
	ds_read_b128 v[198:201], v148 offset:32768
	ds_read_b128 v[202:205], v148 offset:33792
	ds_read_b128 v[206:209], v148 offset:34816
	ds_read_b128 v[210:213], v148 offset:35840
	ds_read_b128 v[224:227], v148 offset:36864
	ds_read_b128 v[228:231], v148 offset:37888
	ds_read_b128 v[232:235], v148 offset:38912
	ds_read_b128 v[236:239], v148 offset:39936
	global_load_lds_dwordx4 v128, s[54:55]
	s_mov_b32 m0, s37
	s_nop 0
	global_load_lds_dwordx4 v130, s[54:55]
	s_waitcnt vmcnt(8) lgkmcnt(0)
	s_barrier
	v_mfma_f32_16x16x32_bf16 v[124:127], v[138:141], v[198:201], v[124:127]
	v_mfma_f32_16x16x32_bf16 v[120:123], v[154:157], v[198:201], v[120:123]
	v_mfma_f32_16x16x32_bf16 v[108:111], v[138:141], v[206:209], v[108:111]
	v_mfma_f32_16x16x32_bf16 v[104:107], v[154:157], v[206:209], v[104:107]
	v_mfma_f32_16x16x32_bf16 v[92:95], v[138:141], v[224:227], v[92:95]
	v_mfma_f32_16x16x32_bf16 v[88:91], v[154:157], v[224:227], v[88:91]
	v_mfma_f32_16x16x32_bf16 v[76:79], v[138:141], v[232:235], v[76:79]
	v_mfma_f32_16x16x32_bf16 v[72:75], v[154:157], v[232:235], v[72:75]
	v_mfma_f32_16x16x32_bf16 v[124:127], v[150:153], v[202:205], v[124:127]
	v_mfma_f32_16x16x32_bf16 v[120:123], v[158:161], v[202:205], v[120:123]
	v_mfma_f32_16x16x32_bf16 v[108:111], v[150:153], v[210:213], v[108:111]
	v_mfma_f32_16x16x32_bf16 v[104:107], v[158:161], v[210:213], v[104:107]
	v_mfma_f32_16x16x32_bf16 v[92:95], v[150:153], v[228:231], v[92:95]
	v_mfma_f32_16x16x32_bf16 v[88:91], v[158:161], v[228:231], v[88:91]
	v_mfma_f32_16x16x32_bf16 v[76:79], v[150:153], v[236:239], v[76:79]
	v_mfma_f32_16x16x32_bf16 v[72:75], v[158:161], v[236:239], v[72:75]
	v_mfma_f32_16x16x32_bf16 v[116:119], v[162:165], v[198:201], v[116:119]
	v_mfma_f32_16x16x32_bf16 v[112:115], v[190:193], v[198:201], v[112:115]
	v_mfma_f32_16x16x32_bf16 v[100:103], v[162:165], v[206:209], v[100:103]
	v_mfma_f32_16x16x32_bf16 v[96:99], v[190:193], v[206:209], v[96:99]
	v_mfma_f32_16x16x32_bf16 v[84:87], v[162:165], v[224:227], v[84:87]
	v_mfma_f32_16x16x32_bf16 v[80:83], v[190:193], v[224:227], v[80:83]
	v_mfma_f32_16x16x32_bf16 v[68:71], v[162:165], v[232:235], v[68:71]
	v_mfma_f32_16x16x32_bf16 v[64:67], v[190:193], v[232:235], v[64:67]
	v_mfma_f32_16x16x32_bf16 v[116:119], v[166:169], v[202:205], v[116:119]
	v_mfma_f32_16x16x32_bf16 v[112:115], v[194:197], v[202:205], v[112:115]
	v_mfma_f32_16x16x32_bf16 v[100:103], v[166:169], v[210:213], v[100:103]
	v_mfma_f32_16x16x32_bf16 v[96:99], v[194:197], v[210:213], v[96:99]
	v_mfma_f32_16x16x32_bf16 v[84:87], v[166:169], v[228:231], v[84:87]
	v_mfma_f32_16x16x32_bf16 v[80:83], v[194:197], v[228:231], v[80:83]
	v_mfma_f32_16x16x32_bf16 v[68:71], v[166:169], v[236:239], v[68:71]
	v_mfma_f32_16x16x32_bf16 v[64:67], v[194:197], v[236:239], v[64:67]
	s_barrier
	s_add_i32 s45, s45, s20
	s_mov_b32 m0, s45
	ds_read_b128 v[198:201], v148 offset:49152
	ds_read_b128 v[202:205], v148 offset:50176
	ds_read_b128 v[206:209], v148 offset:51200
	ds_read_b128 v[210:213], v148 offset:52224
	ds_read_b128 v[224:227], v148 offset:53248
	ds_read_b128 v[228:231], v148 offset:54272
	ds_read_b128 v[232:235], v148 offset:55296
	ds_read_b128 v[236:239], v148 offset:56320
	s_add_u32 s100, s22, 0x80
	s_addc_u32 s101, s23, 0
	global_load_lds_dwordx4 v172, s[100:101]
	s_add_i32 m0, s45, 0x2000
	s_add_u32 s22, s22, 0x80080
	s_addc_u32 s23, s23, 0
	s_add_i32 s45, s47, s20
	global_load_lds_dwordx4 v132, s[100:101]
	s_mov_b32 m0, s45
	s_nop 0
	global_load_lds_dwordx4 v172, s[22:23]
	s_add_i32 m0, s45, 0x2000
	s_nop 0
	global_load_lds_dwordx4 v132, s[22:23]
	s_mov_b32 m0, s38
	s_nop 0
	s_add_u32 s100, s54, 0xfff80080
	s_addc_u32 s101, s55, -1
	global_load_lds_dwordx4 v128, s[100:101]
	s_mov_b32 m0, s56
	s_nop 0
	global_load_lds_dwordx4 v130, s[100:101]
	s_waitcnt vmcnt(8) lgkmcnt(0)
	s_barrier
	v_mfma_f32_16x16x32_bf16 v[60:63], v[138:141], v[198:201], v[60:63]
	v_mfma_f32_16x16x32_bf16 v[56:59], v[154:157], v[198:201], v[56:59]
	v_mfma_f32_16x16x32_bf16 v[44:47], v[138:141], v[206:209], v[44:47]
	v_mfma_f32_16x16x32_bf16 v[40:43], v[154:157], v[206:209], v[40:43]
	v_mfma_f32_16x16x32_bf16 v[28:31], v[138:141], v[224:227], v[28:31]
	v_mfma_f32_16x16x32_bf16 v[24:27], v[154:157], v[224:227], v[24:27]
	v_mfma_f32_16x16x32_bf16 v[12:15], v[138:141], v[232:235], v[12:15]
	v_mfma_f32_16x16x32_bf16 v[8:11], v[154:157], v[232:235], v[8:11]
	v_mfma_f32_16x16x32_bf16 v[60:63], v[150:153], v[202:205], v[60:63]
	v_mfma_f32_16x16x32_bf16 v[56:59], v[158:161], v[202:205], v[56:59]
	v_mfma_f32_16x16x32_bf16 v[44:47], v[150:153], v[210:213], v[44:47]
	v_mfma_f32_16x16x32_bf16 v[40:43], v[158:161], v[210:213], v[40:43]
	v_mfma_f32_16x16x32_bf16 v[28:31], v[150:153], v[228:231], v[28:31]
	v_mfma_f32_16x16x32_bf16 v[24:27], v[158:161], v[228:231], v[24:27]
	v_mfma_f32_16x16x32_bf16 v[12:15], v[150:153], v[236:239], v[12:15]
	v_mfma_f32_16x16x32_bf16 v[8:11], v[158:161], v[236:239], v[8:11]
	v_mfma_f32_16x16x32_bf16 v[52:55], v[162:165], v[198:201], v[52:55]
	v_mfma_f32_16x16x32_bf16 v[48:51], v[190:193], v[198:201], v[48:51]
	v_mfma_f32_16x16x32_bf16 v[36:39], v[162:165], v[206:209], v[36:39]
	v_mfma_f32_16x16x32_bf16 v[32:35], v[190:193], v[206:209], v[32:35]
	v_mfma_f32_16x16x32_bf16 v[20:23], v[162:165], v[224:227], v[20:23]
	v_mfma_f32_16x16x32_bf16 v[16:19], v[190:193], v[224:227], v[16:19]
	v_mfma_f32_16x16x32_bf16 v[4:7], v[162:165], v[232:235], v[4:7]
	v_mfma_f32_16x16x32_bf16 v[0:3], v[190:193], v[232:235], v[0:3]
	v_mfma_f32_16x16x32_bf16 v[52:55], v[166:169], v[202:205], v[52:55]
	v_mfma_f32_16x16x32_bf16 v[48:51], v[194:197], v[202:205], v[48:51]
	v_mfma_f32_16x16x32_bf16 v[36:39], v[166:169], v[210:213], v[36:39]
	v_mfma_f32_16x16x32_bf16 v[32:35], v[194:197], v[210:213], v[32:35]
	v_mfma_f32_16x16x32_bf16 v[20:23], v[166:169], v[228:231], v[20:23]
	v_mfma_f32_16x16x32_bf16 v[16:19], v[194:197], v[228:231], v[16:19]
	v_mfma_f32_16x16x32_bf16 v[4:7], v[166:169], v[236:239], v[4:7]
	v_mfma_f32_16x16x32_bf16 v[0:3], v[194:197], v[236:239], v[0:3]
	s_barrier
	s_add_i32 s43, s43, 2
	s_add_u32 s52, s52, 0x100
	s_addc_u32 s53, s53, 0
	s_add_u32 s34, s34, 0x100
	s_addc_u32 s35, s35, 0
	s_cmp_gt_u32 s43, 29
	s_cbranch_scc0 .LBB0_476
	s_and_b64 vcc, exec, s[28:29]
	s_cbranch_vccz .LBB0_479
	s_barrier

;     __device__ __forceinline__ void a_ready(const Unit& u) const { wait_panel(cnt, u.pm, need, tmo, wave); }
;     __device__ __forceinline__ void a_ready(const Unit& u) const { wait_panel(cnt, u.pm, need, tmo, wave); }
; #define PG8_STAGE(bufoff, gbase, voff) do { _Pragma("unroll") for (int _i = 0; _i < 2; ++_i) \
;         __builtin_amdgcn_global_load_lds((const unsigned*)((const char*)(gbase) + (voff)[_i]), (PG8_LAS unsigned*)(lds + (bufoff) + ldsw + _i * 8192), 16, 0, 0); } while (0)
; #define PG8_LDA(dst, b, h) do { _Pragma("unroll") for (int m = 0; m < 4; ++m) _Pragma("unroll") for (int k = 0; k < 2; ++k) dst[m][k] = *(const PG8_LAS bf16x8*)(lds + PG8_SA(b, h) + aoff + m * 2048 + k * 1024); } while (0)
; #define PG8_LDB(dst, b, h) do { _Pragma("unroll") for (int n = 0; n < 2; ++n) _Pragma("unroll") for (int k = 0; k < 2; ++k) dst[n][k] = *(const PG8_LAS bf16x8*)(lds + PG8_SB(b, h) + boff + n * 2048 + k * 1024); } while (0)
; #define PG8_WAIT_V(n) asm volatile("s_waitcnt vmcnt(" #n ")" ::: "memory")
; #define PG8_WAIT_L(n) asm volatile("s_waitcnt lgkmcnt(" #n ")" ::: "memory")
; #define PG8_BAR __builtin_amdgcn_s_barrier()
; #define PG8_SCHED __builtin_amdgcn_sched_barrier(0)
; template <class Epi, class Sched, bool ALIGN_EPI = false, bool SP2 = false>
; __device__ __forceinline__ void gemm_phase(PG8_LAS unsigned char* lds, const Gemm g, const Sched& S, const Epi& E, const int tid_in) {
;     ...
;         for (int t = 0; t < nt; t += 2) {
;             const bool last = (t == nt - 2);
;             const char* a1 = cA + (size_t)(t + 1) * kstep;
;             const char* a2 = last ? nA : cA + (size_t)(t + 2) * kstep; const char* b2 = last ? nB : cB + (size_t)(t + 2) * kstep;
;             const char* a3 = a2 + kstep; const char* b3 = b2 + kstep;
;             if (last && has_next) S.a_ready(nxt);
;             if constexpr (SP2) {
;             PG8_LDB(B0, 0, 0); PG8_LDB(B1, 0, 1); PG8_SCHED; PG8_LDA(At, 0, 0); PG8_STAGE(PG8_SA(1, 1), a1 + hstepA, voffA);
;             PG8_WAIT_V(8); PG8_WAIT_L(0); PG8_BAR; PG8_MMA(0, 0, At, B0); PG8_MMA(0, 1, At, B1); PG8_BAR; PG8_SCHED;
;             PG8_LDA(At, 0, 1); PG8_STAGE(PG8_SB(0, 0), b2, voffB); PG8_STAGE(PG8_SB(0, 1), b2 + hstepB, voffB); PG8_STAGE(PG8_SA(0, 0), a2, voffA);
;             PG8_WAIT_V(8); PG8_WAIT_L(0); PG8_BAR; PG8_MMA(1, 0, At, B0); PG8_MMA(1, 1, At, B1); PG8_BAR; PG8_SCHED;
.LBB0_756:
	s_add_u32 s22, s36, 0x100
	s_addc_u32 s23, s37, 0
	s_add_i32 s34, 0, 0x10000
	s_cmp_eq_u32 s33, 2
	s_cselect_b32 s45, s73, s23
	s_cselect_b32 s44, s72, s22
	s_cselect_b32 s43, s77, s21
	s_cselect_b32 s42, s76, s12
	s_add_i32 s46, 0, 0x14000
	ds_read_b128 v[88:91], v249
	ds_read_b128 v[92:95], v249 offset:1024
	ds_read_b128 v[96:99], v249 offset:2048
	ds_read_b128 v[146:149], v249 offset:3072
	ds_read_b128 v[150:153], v249 offset:16384
	ds_read_b128 v[154:157], v249 offset:17408
	ds_read_b128 v[158:161], v249 offset:18432
	ds_read_b128 v[162:165], v249 offset:19456
	s_add_i32 m0, s74, 0xc000
	ds_read_b128 v[166:169], v192
	ds_read_b128 v[194:197], v192 offset:1024
	ds_read_b128 v[198:201], v192 offset:2048
	ds_read_b128 v[202:205], v192 offset:3072
	ds_read_b128 v[206:209], v192 offset:4096
	ds_read_b128 v[210:213], v192 offset:5120
	ds_read_b128 v[224:227], v192 offset:6144
	ds_read_b128 v[228:231], v192 offset:7168
	global_load_lds_dwordx4 v142, s[36:37]
	s_add_i32 m0, s74, 0xe000
	s_nop 0
	global_load_lds_dwordx4 v144, s[36:37]
	s_waitcnt vmcnt(8) lgkmcnt(0)
	s_barrier
	v_mfma_f32_16x16x32_bf16 v[136:139], v[88:91], v[166:169], v[136:139]
	v_mfma_f32_16x16x32_bf16 v[60:63], v[96:99], v[166:169], v[60:63]
	v_mfma_f32_16x16x32_bf16 v[128:131], v[88:91], v[198:201], v[128:131]
	v_mfma_f32_16x16x32_bf16 v[52:55], v[96:99], v[198:201], v[52:55]
	v_mfma_f32_16x16x32_bf16 v[120:123], v[88:91], v[206:209], v[120:123]
	v_mfma_f32_16x16x32_bf16 v[44:47], v[96:99], v[206:209], v[44:47]
	v_mfma_f32_16x16x32_bf16 v[112:115], v[88:91], v[224:227], v[112:115]
	v_mfma_f32_16x16x32_bf16 v[36:39], v[96:99], v[224:227], v[36:39]
	v_mfma_f32_16x16x32_bf16 v[136:139], v[92:95], v[194:197], v[136:139]
	v_mfma_f32_16x16x32_bf16 v[60:63], v[146:149], v[194:197], v[60:63]
	v_mfma_f32_16x16x32_bf16 v[128:131], v[92:95], v[202:205], v[128:131]
	v_mfma_f32_16x16x32_bf16 v[52:55], v[146:149], v[202:205], v[52:55]
	v_mfma_f32_16x16x32_bf16 v[120:123], v[92:95], v[210:213], v[120:123]
	v_mfma_f32_16x16x32_bf16 v[44:47], v[146:149], v[210:213], v[44:47]
	v_mfma_f32_16x16x32_bf16 v[112:115], v[92:95], v[228:231], v[112:115]
	v_mfma_f32_16x16x32_bf16 v[36:39], v[146:149], v[228:231], v[36:39]
	v_mfma_f32_16x16x32_bf16 v[132:135], v[150:153], v[166:169], v[132:135]
	v_mfma_f32_16x16x32_bf16 v[56:59], v[158:161], v[166:169], v[56:59]
	v_mfma_f32_16x16x32_bf16 v[124:127], v[150:153], v[198:201], v[124:127]
	v_mfma_f32_16x16x32_bf16 v[48:51], v[158:161], v[198:201], v[48:51]
	v_mfma_f32_16x16x32_bf16 v[116:119], v[150:153], v[206:209], v[116:119]
	v_mfma_f32_16x16x32_bf16 v[40:43], v[158:161], v[206:209], v[40:43]
	v_mfma_f32_16x16x32_bf16 v[108:111], v[150:153], v[224:227], v[108:111]
	v_mfma_f32_16x16x32_bf16 v[32:35], v[158:161], v[224:227], v[32:35]
	v_mfma_f32_16x16x32_bf16 v[132:135], v[154:157], v[194:197], v[132:135]
	v_mfma_f32_16x16x32_bf16 v[56:59], v[162:165], v[194:197], v[56:59]
	v_mfma_f32_16x16x32_bf16 v[124:127], v[154:157], v[202:205], v[124:127]
	v_mfma_f32_16x16x32_bf16 v[48:51], v[162:165], v[202:205], v[48:51]
	v_mfma_f32_16x16x32_bf16 v[116:119], v[154:157], v[210:213], v[116:119]
	v_mfma_f32_16x16x32_bf16 v[40:43], v[162:165], v[210:213], v[40:43]
	v_mfma_f32_16x16x32_bf16 v[108:111], v[154:157], v[228:231], v[108:111]
	v_mfma_f32_16x16x32_bf16 v[32:35], v[162:165], v[228:231], v[32:35]
	s_barrier
	s_add_i32 s34, s34, s38
	s_mov_b32 m0, s34
	ds_read_b128 v[166:169], v192 offset:16384
	ds_read_b128 v[194:197], v192 offset:17408
	ds_read_b128 v[198:201], v192 offset:18432
	ds_read_b128 v[202:205], v192 offset:19456
	ds_read_b128 v[206:209], v192 offset:20480
	ds_read_b128 v[210:213], v192 offset:21504
	ds_read_b128 v[224:227], v192 offset:22528
	ds_read_b128 v[228:231], v192 offset:23552
	global_load_lds_dwordx4 v172, s[42:43]
	s_add_i32 m0, s34, 0x2000
	s_add_u32 s34, s42, 0xa0000
	s_addc_u32 s35, s43, 0
	s_add_i32 s36, s46, s38
	global_load_lds_dwordx4 v140, s[42:43]
	s_mov_b32 m0, s36
	s_nop 0
	global_load_lds_dwordx4 v172, s[34:35]
	s_add_i32 m0, s36, 0x2000
	s_nop 0
	global_load_lds_dwordx4 v140, s[34:35]
	s_mov_b32 m0, s74
	s_nop 0
	global_load_lds_dwordx4 v172, s[44:45]
	s_mov_b32 m0, s75
	s_nop 0
	global_load_lds_dwordx4 v140, s[44:45]
	s_waitcnt vmcnt(8) lgkmcnt(0)
	s_barrier
	v_mfma_f32_16x16x32_bf16 v[104:107], v[88:91], v[166:169], v[104:107]
	v_mfma_f32_16x16x32_bf16 v[28:31], v[96:99], v[166:169], v[28:31]
	v_mfma_f32_16x16x32_bf16 v[84:87], v[88:91], v[198:201], v[84:87]
	v_mfma_f32_16x16x32_bf16 v[20:23], v[96:99], v[198:201], v[20:23]
	v_mfma_f32_16x16x32_bf16 v[76:79], v[88:91], v[206:209], v[76:79]
	v_mfma_f32_16x16x32_bf16 v[12:15], v[96:99], v[206:209], v[12:15]
	v_mfma_f32_16x16x32_bf16 v[68:71], v[88:91], v[224:227], v[68:71]
	v_mfma_f32_16x16x32_bf16 v[4:7], v[96:99], v[224:227], v[4:7]
	v_mfma_f32_16x16x32_bf16 v[104:107], v[92:95], v[194:197], v[104:107]
	v_mfma_f32_16x16x32_bf16 v[28:31], v[146:149], v[194:197], v[28:31]
	v_mfma_f32_16x16x32_bf16 v[84:87], v[92:95], v[202:205], v[84:87]
	v_mfma_f32_16x16x32_bf16 v[20:23], v[146:149], v[202:205], v[20:23]
	v_mfma_f32_16x16x32_bf16 v[76:79], v[92:95], v[210:213], v[76:79]
	v_mfma_f32_16x16x32_bf16 v[12:15], v[146:149], v[210:213], v[12:15]
	v_mfma_f32_16x16x32_bf16 v[68:71], v[92:95], v[228:231], v[68:71]
	v_mfma_f32_16x16x32_bf16 v[4:7], v[146:149], v[228:231], v[4:7]
	v_mfma_f32_16x16x32_bf16 v[24:27], v[158:161], v[166:169], v[24:27]
	v_mfma_f32_16x16x32_bf16 v[80:83], v[150:153], v[198:201], v[80:83]
	v_mfma_f32_16x16x32_bf16 v[16:19], v[158:161], v[198:201], v[16:19]
	v_mfma_f32_16x16x32_bf16 v[72:75], v[150:153], v[206:209], v[72:75]
	v_mfma_f32_16x16x32_bf16 v[8:11], v[158:161], v[206:209], v[8:11]
	v_mfma_f32_16x16x32_bf16 v[64:67], v[150:153], v[224:227], v[64:67]
	v_mfma_f32_16x16x32_bf16 v[0:3], v[158:161], v[224:227], v[0:3]
	v_mfma_f32_16x16x32_bf16 v[88:91], v[150:153], v[166:169], v[100:103]
	v_mfma_f32_16x16x32_bf16 v[24:27], v[162:165], v[194:197], v[24:27]
	v_mfma_f32_16x16x32_bf16 v[80:83], v[154:157], v[202:205], v[80:83]
	v_mfma_f32_16x16x32_bf16 v[16:19], v[162:165], v[202:205], v[16:19]
	v_mfma_f32_16x16x32_bf16 v[72:75], v[154:157], v[210:213], v[72:75]
	v_mfma_f32_16x16x32_bf16 v[8:11], v[162:165], v[210:213], v[8:11]
	v_mfma_f32_16x16x32_bf16 v[64:67], v[154:157], v[228:231], v[64:67]
	v_mfma_f32_16x16x32_bf16 v[0:3], v[162:165], v[228:231], v[0:3]
	v_mfma_f32_16x16x32_bf16 v[88:91], v[154:157], v[194:197], v[88:91]
	s_barrier
; #define PG8_STAGE(bufoff, gbase, voff) do { _Pragma("unroll") for (int _i = 0; _i < 2; ++_i) \
;         __builtin_amdgcn_global_load_lds((const unsigned*)((const char*)(gbase) + (voff)[_i]), (PG8_LAS unsigned*)(lds + (bufoff) + ldsw + _i * 8192), 16, 0, 0); } while (0)
; #define PG8_LDA(dst, b, h) do { _Pragma("unroll") for (int m = 0; m < 4; ++m) _Pragma("unroll") for (int k = 0; k < 2; ++k) dst[m][k] = *(const PG8_LAS bf16x8*)(lds + PG8_SA(b, h) + aoff + m * 2048 + k * 1024); } while (0)
; #define PG8_LDB(dst, b, h) do { _Pragma("unroll") for (int n = 0; n < 2; ++n) _Pragma("unroll") for (int k = 0; k < 2; ++k) dst[n][k] = *(const PG8_LAS bf16x8*)(lds + PG8_SB(b, h) + boff + n * 2048 + k * 1024); } while (0)
; #define PG8_MMA(ai, bj, At, Bt) do { __builtin_amdgcn_s_setprio(1); _Pragma("unroll") for (int m = 0; m < 4; ++m) _Pragma("unroll") for (int n = 0; n < 2; ++n) _Pragma("unroll") for (int k = 0; k < 2; ++k) \
;         acc[ai][bj][m][n] = __builtin_amdgcn_mfma_f32_16x16x32_bf16(Bt[n][k], At[m][k], acc[ai][bj][m][n], 0, 0, 0); __builtin_amdgcn_s_setprio(0); } while (0)
; #define PG8_WAIT_V(n) asm volatile("s_waitcnt vmcnt(" #n ")" ::: "memory")
; #define PG8_WAIT_L(n) asm volatile("s_waitcnt lgkmcnt(" #n ")" ::: "memory")
; #define PG8_BAR __builtin_amdgcn_s_barrier()
; #define PG8_SCHED __builtin_amdgcn_sched_barrier(0)
; template <class Epi, class Sched, bool ALIGN_EPI = false, bool SP2 = false>
; __device__ __forceinline__ void gemm_phase(PG8_LAS unsigned char* lds, const Gemm g, const Sched& S, const Epi& E, const int tid_in) {
;     ...
;             PG8_LDB(B0, 1, 0); PG8_LDB(B1, 1, 1); PG8_SCHED; PG8_LDA(At, 1, 0); PG8_STAGE(PG8_SA(0, 1), a2 + hstepA, voffA);
;             PG8_WAIT_V(8); PG8_WAIT_L(0); PG8_BAR; PG8_MMA(0, 0, At, B0); PG8_MMA(0, 1, At, B1); PG8_BAR; PG8_SCHED;
;             PG8_LDA(At, 1, 1); PG8_STAGE(PG8_SB(1, 0), b3, voffB); PG8_STAGE(PG8_SB(1, 1), b3 + hstepB, voffB); PG8_STAGE(PG8_SA(1, 0), a3, voffA);
;             PG8_WAIT_V(8); PG8_WAIT_L(0); PG8_BAR; PG8_MMA(1, 0, At, B0); PG8_MMA(1, 1, At, B1); PG8_BAR; PG8_SCHED;
;     ...
;         if constexpr (ALIGN_EPI) { if (wr == 0) PG8_BAR; }
	s_add_i32 s36, 0, 0x18000
	s_add_i32 s37, 0, 0x1c000
	ds_read_b128 v[92:95], v249 offset:32768
	ds_read_b128 v[96:99], v249 offset:33792
	ds_read_b128 v[100:103], v249 offset:34816
	ds_read_b128 v[146:149], v249 offset:35840
	ds_read_b128 v[150:153], v249 offset:49152
	ds_read_b128 v[154:157], v249 offset:50176
	ds_read_b128 v[158:161], v249 offset:51200
	ds_read_b128 v[162:165], v249 offset:52224
	s_add_u32 s34, s44, 0xa0000
	s_addc_u32 s35, s45, 0
	s_mov_b32 m0, s60
	ds_read_b128 v[166:169], v192 offset:32768
	ds_read_b128 v[194:197], v192 offset:33792
	ds_read_b128 v[198:201], v192 offset:34816
	ds_read_b128 v[202:205], v192 offset:35840
	ds_read_b128 v[206:209], v192 offset:36864
	ds_read_b128 v[210:213], v192 offset:37888
	ds_read_b128 v[224:227], v192 offset:38912
	ds_read_b128 v[228:231], v192 offset:39936
	global_load_lds_dwordx4 v172, s[34:35]
	s_mov_b32 m0, s61
	s_nop 0
	global_load_lds_dwordx4 v140, s[34:35]
	s_waitcnt vmcnt(8) lgkmcnt(0)
	s_barrier
	v_mfma_f32_16x16x32_bf16 v[136:139], v[92:95], v[166:169], v[136:139]
	v_mfma_f32_16x16x32_bf16 v[60:63], v[100:103], v[166:169], v[60:63]
	v_mfma_f32_16x16x32_bf16 v[128:131], v[92:95], v[198:201], v[128:131]
	v_mfma_f32_16x16x32_bf16 v[52:55], v[100:103], v[198:201], v[52:55]
	v_mfma_f32_16x16x32_bf16 v[120:123], v[92:95], v[206:209], v[120:123]
	v_mfma_f32_16x16x32_bf16 v[44:47], v[100:103], v[206:209], v[44:47]
	v_mfma_f32_16x16x32_bf16 v[112:115], v[92:95], v[224:227], v[112:115]
	v_mfma_f32_16x16x32_bf16 v[36:39], v[100:103], v[224:227], v[36:39]
	v_mfma_f32_16x16x32_bf16 v[136:139], v[96:99], v[194:197], v[136:139]
	v_mfma_f32_16x16x32_bf16 v[60:63], v[146:149], v[194:197], v[60:63]
	v_mfma_f32_16x16x32_bf16 v[128:131], v[96:99], v[202:205], v[128:131]
	v_mfma_f32_16x16x32_bf16 v[52:55], v[146:149], v[202:205], v[52:55]
	v_mfma_f32_16x16x32_bf16 v[120:123], v[96:99], v[210:213], v[120:123]
	v_mfma_f32_16x16x32_bf16 v[44:47], v[146:149], v[210:213], v[44:47]
	v_mfma_f32_16x16x32_bf16 v[112:115], v[96:99], v[228:231], v[112:115]
	v_mfma_f32_16x16x32_bf16 v[36:39], v[146:149], v[228:231], v[36:39]
	v_mfma_f32_16x16x32_bf16 v[132:135], v[150:153], v[166:169], v[132:135]
	v_mfma_f32_16x16x32_bf16 v[56:59], v[158:161], v[166:169], v[56:59]
	v_mfma_f32_16x16x32_bf16 v[124:127], v[150:153], v[198:201], v[124:127]
	v_mfma_f32_16x16x32_bf16 v[48:51], v[158:161], v[198:201], v[48:51]
	v_mfma_f32_16x16x32_bf16 v[116:119], v[150:153], v[206:209], v[116:119]
	v_mfma_f32_16x16x32_bf16 v[40:43], v[158:161], v[206:209], v[40:43]
	v_mfma_f32_16x16x32_bf16 v[108:111], v[150:153], v[224:227], v[108:111]
	v_mfma_f32_16x16x32_bf16 v[32:35], v[158:161], v[224:227], v[32:35]
	v_mfma_f32_16x16x32_bf16 v[132:135], v[154:157], v[194:197], v[132:135]
	v_mfma_f32_16x16x32_bf16 v[56:59], v[162:165], v[194:197], v[56:59]
	v_mfma_f32_16x16x32_bf16 v[124:127], v[154:157], v[202:205], v[124:127]
	v_mfma_f32_16x16x32_bf16 v[48:51], v[162:165], v[202:205], v[48:51]
	v_mfma_f32_16x16x32_bf16 v[116:119], v[154:157], v[210:213], v[116:119]
	v_mfma_f32_16x16x32_bf16 v[40:43], v[162:165], v[210:213], v[40:43]
	v_mfma_f32_16x16x32_bf16 v[108:111], v[154:157], v[228:231], v[108:111]
	v_mfma_f32_16x16x32_bf16 v[32:35], v[162:165], v[228:231], v[32:35]
	s_barrier
	s_add_i32 s34, s36, s38
	s_mov_b32 m0, s34
	ds_read_b128 v[166:169], v192 offset:49152
	ds_read_b128 v[194:197], v192 offset:50176
	ds_read_b128 v[198:201], v192 offset:51200
	ds_read_b128 v[202:205], v192 offset:52224
	ds_read_b128 v[206:209], v192 offset:53248
	ds_read_b128 v[210:213], v192 offset:54272
	ds_read_b128 v[224:227], v192 offset:55296
	ds_read_b128 v[228:231], v192 offset:56320
	s_add_u32 s100, s42, 0x80
	s_addc_u32 s101, s43, 0
	global_load_lds_dwordx4 v172, s[100:101]
	s_add_i32 m0, s34, 0x2000
	s_add_u32 s34, s42, 0xa0080
	s_addc_u32 s35, s43, 0
	s_add_i32 s36, s37, s38
	global_load_lds_dwordx4 v140, s[100:101]
	s_mov_b32 m0, s36
	s_nop 0
	global_load_lds_dwordx4 v172, s[34:35]
	s_add_i32 m0, s36, 0x2000
	s_nop 0
	global_load_lds_dwordx4 v140, s[34:35]
	s_mov_b32 m0, s58
	s_nop 0
	s_add_u32 s100, s44, 0x80
	s_addc_u32 s101, s45, 0
	global_load_lds_dwordx4 v172, s[100:101]
	s_mov_b32 m0, s59
	s_nop 0
	global_load_lds_dwordx4 v140, s[100:101]
	s_waitcnt vmcnt(8) lgkmcnt(0)
	s_barrier
	v_mfma_f32_16x16x32_bf16 v[104:107], v[92:95], v[166:169], v[104:107]
	v_mfma_f32_16x16x32_bf16 v[28:31], v[100:103], v[166:169], v[28:31]
	v_mfma_f32_16x16x32_bf16 v[84:87], v[92:95], v[198:201], v[84:87]
	v_mfma_f32_16x16x32_bf16 v[20:23], v[100:103], v[198:201], v[20:23]
	v_mfma_f32_16x16x32_bf16 v[76:79], v[92:95], v[206:209], v[76:79]
	v_mfma_f32_16x16x32_bf16 v[12:15], v[100:103], v[206:209], v[12:15]
	v_mfma_f32_16x16x32_bf16 v[68:71], v[92:95], v[224:227], v[68:71]
	v_mfma_f32_16x16x32_bf16 v[4:7], v[100:103], v[224:227], v[4:7]
	v_mfma_f32_16x16x32_bf16 v[104:107], v[96:99], v[194:197], v[104:107]
	v_mfma_f32_16x16x32_bf16 v[28:31], v[146:149], v[194:197], v[28:31]
	v_mfma_f32_16x16x32_bf16 v[84:87], v[96:99], v[202:205], v[84:87]
	v_mfma_f32_16x16x32_bf16 v[20:23], v[146:149], v[202:205], v[20:23]
	v_mfma_f32_16x16x32_bf16 v[76:79], v[96:99], v[210:213], v[76:79]
	v_mfma_f32_16x16x32_bf16 v[12:15], v[146:149], v[210:213], v[12:15]
	v_mfma_f32_16x16x32_bf16 v[68:71], v[96:99], v[228:231], v[68:71]
	v_mfma_f32_16x16x32_bf16 v[4:7], v[146:149], v[228:231], v[4:7]
	v_mfma_f32_16x16x32_bf16 v[88:91], v[150:153], v[166:169], v[88:91]
	v_mfma_f32_16x16x32_bf16 v[24:27], v[158:161], v[166:169], v[24:27]
	v_mfma_f32_16x16x32_bf16 v[80:83], v[150:153], v[198:201], v[80:83]
	v_mfma_f32_16x16x32_bf16 v[16:19], v[158:161], v[198:201], v[16:19]
	v_mfma_f32_16x16x32_bf16 v[72:75], v[150:153], v[206:209], v[72:75]
	v_mfma_f32_16x16x32_bf16 v[8:11], v[158:161], v[206:209], v[8:11]
	v_mfma_f32_16x16x32_bf16 v[64:67], v[150:153], v[224:227], v[64:67]
	v_mfma_f32_16x16x32_bf16 v[0:3], v[158:161], v[224:227], v[0:3]
	v_mfma_f32_16x16x32_bf16 v[100:103], v[154:157], v[194:197], v[88:91]
	v_mfma_f32_16x16x32_bf16 v[24:27], v[162:165], v[194:197], v[24:27]
	v_mfma_f32_16x16x32_bf16 v[80:83], v[154:157], v[202:205], v[80:83]
	v_mfma_f32_16x16x32_bf16 v[16:19], v[162:165], v[202:205], v[16:19]
	v_mfma_f32_16x16x32_bf16 v[72:75], v[154:157], v[210:213], v[72:75]
	v_mfma_f32_16x16x32_bf16 v[8:11], v[162:165], v[210:213], v[8:11]
	v_mfma_f32_16x16x32_bf16 v[64:67], v[154:157], v[228:231], v[64:67]
	v_mfma_f32_16x16x32_bf16 v[0:3], v[162:165], v[228:231], v[0:3]
	s_barrier
	s_add_i32 s33, s33, 2
	s_add_u32 s12, s12, 0x100
	s_addc_u32 s21, s21, 0
	s_cmp_gt_u32 s33, 3
	s_mov_b64 s[36:37], s[22:23]
	s_cbranch_scc0 .LBB0_756
	s_and_b64 vcc, exec, s[70:71]
	s_cbranch_vccz .LBB0_759
	s_barrier

;     __device__ __forceinline__ void a_ready(const Unit& u) const { wait_panel(cnt, u.pm, need, tmo, wave); }
;     __device__ __forceinline__ void a_ready(const Unit& u) const { wait_panel(cnt, u.pm, need, tmo, wave); }
; #define PG8_STAGE(bufoff, gbase, voff) do { _Pragma("unroll") for (int _i = 0; _i < 2; ++_i) \
;         __builtin_amdgcn_global_load_lds((const unsigned*)((const char*)(gbase) + (voff)[_i]), (PG8_LAS unsigned*)(lds + (bufoff) + ldsw + _i * 8192), 16, 0, 0); } while (0)
; #define PG8_LDA(dst, b, h) do { _Pragma("unroll") for (int m = 0; m < 4; ++m) _Pragma("unroll") for (int k = 0; k < 2; ++k) dst[m][k] = *(const PG8_LAS bf16x8*)(lds + PG8_SA(b, h) + aoff + m * 2048 + k * 1024); } while (0)
; #define PG8_LDB(dst, b, h) do { _Pragma("unroll") for (int n = 0; n < 2; ++n) _Pragma("unroll") for (int k = 0; k < 2; ++k) dst[n][k] = *(const PG8_LAS bf16x8*)(lds + PG8_SB(b, h) + boff + n * 2048 + k * 1024); } while (0)
; #define PG8_WAIT_V(n) asm volatile("s_waitcnt vmcnt(" #n ")" ::: "memory")
; #define PG8_WAIT_L(n) asm volatile("s_waitcnt lgkmcnt(" #n ")" ::: "memory")
; #define PG8_BAR __builtin_amdgcn_s_barrier()
; #define PG8_SCHED __builtin_amdgcn_sched_barrier(0)
; template <class Epi, class Sched, bool ALIGN_EPI = false, bool SP2 = false>
; __device__ __forceinline__ void gemm_phase(PG8_LAS unsigned char* lds, const Gemm g, const Sched& S, const Epi& E, const int tid_in) {
;     ...
;         for (int t = 0; t < nt; t += 2) {
;             const bool last = (t == nt - 2);
;             const char* a1 = cA + (size_t)(t + 1) * kstep;
;             const char* a2 = last ? nA : cA + (size_t)(t + 2) * kstep; const char* b2 = last ? nB : cB + (size_t)(t + 2) * kstep;
;             const char* a3 = a2 + kstep; const char* b3 = b2 + kstep;
;             if (last && has_next) S.a_ready(nxt);
;             if constexpr (SP2) {
;             PG8_LDB(B0, 0, 0); PG8_LDB(B1, 0, 1); PG8_SCHED; PG8_LDA(At, 0, 0); PG8_STAGE(PG8_SA(1, 1), a1 + hstepA, voffA);
;             PG8_WAIT_V(8); PG8_WAIT_L(0); PG8_BAR; PG8_MMA(0, 0, At, B0); PG8_MMA(0, 1, At, B1); PG8_BAR; PG8_SCHED;
;             PG8_LDA(At, 0, 1); PG8_STAGE(PG8_SB(0, 0), b2, voffB); PG8_STAGE(PG8_SB(0, 1), b2 + hstepB, voffB); PG8_STAGE(PG8_SA(0, 0), a2, voffA);
;             PG8_WAIT_V(8); PG8_WAIT_L(0); PG8_BAR; PG8_MMA(1, 0, At, B0); PG8_MMA(1, 1, At, B1); PG8_BAR; PG8_SCHED;
.LBB0_1268:
	s_add_u32 s22, s50, 0x100
	s_addc_u32 s23, s51, 0
	s_add_i32 s63, 0, 0x10000
	s_cmp_eq_u32 s62, 36
	s_cselect_b32 s55, s43, s23
	s_cselect_b32 s54, s42, s22
	s_cselect_b32 s53, s49, s61
	s_cselect_b32 s52, s48, s60
	s_add_i32 s64, 0, 0x14000
	ds_read_b128 v[104:107], v249
	ds_read_b128 v[108:111], v249 offset:1024
	ds_read_b128 v[112:115], v249 offset:2048
	ds_read_b128 v[116:119], v249 offset:3072
	ds_read_b128 v[144:147], v249 offset:16384
	ds_read_b128 v[148:151], v249 offset:17408
	ds_read_b128 v[152:155], v249 offset:18432
	ds_read_b128 v[156:159], v249 offset:19456
	s_add_i32 m0, s30, 0xc000
	ds_read_b128 v[160:163], v204
	ds_read_b128 v[192:195], v204 offset:1024
	ds_read_b128 v[196:199], v204 offset:2048
	ds_read_b128 v[206:209], v204 offset:3072
	ds_read_b128 v[210:213], v204 offset:4096
	ds_read_b128 v[224:227], v204 offset:5120
	ds_read_b128 v[228:231], v204 offset:6144
	ds_read_b128 v[232:235], v204 offset:7168
	global_load_lds_dwordx4 v170, s[50:51]
	s_add_i32 m0, s30, 0xe000
	s_nop 0
	global_load_lds_dwordx4 v190, s[50:51]
	s_waitcnt vmcnt(8) lgkmcnt(0)
	s_barrier
	v_mfma_f32_16x16x32_bf16 v[140:143], v[104:107], v[160:163], v[140:143]
	v_mfma_f32_16x16x32_bf16 v[136:139], v[112:115], v[160:163], v[136:139]
	v_mfma_f32_16x16x32_bf16 v[124:127], v[104:107], v[196:199], v[124:127]
	v_mfma_f32_16x16x32_bf16 v[120:123], v[112:115], v[196:199], v[120:123]
	v_mfma_f32_16x16x32_bf16 v[92:95], v[104:107], v[210:213], v[92:95]
	v_mfma_f32_16x16x32_bf16 v[88:91], v[112:115], v[210:213], v[88:91]
	v_mfma_f32_16x16x32_bf16 v[76:79], v[104:107], v[228:231], v[76:79]
	v_mfma_f32_16x16x32_bf16 v[72:75], v[112:115], v[228:231], v[72:75]
	v_mfma_f32_16x16x32_bf16 v[140:143], v[108:111], v[192:195], v[140:143]
	v_mfma_f32_16x16x32_bf16 v[136:139], v[116:119], v[192:195], v[136:139]
	v_mfma_f32_16x16x32_bf16 v[124:127], v[108:111], v[206:209], v[124:127]
	v_mfma_f32_16x16x32_bf16 v[120:123], v[116:119], v[206:209], v[120:123]
	v_mfma_f32_16x16x32_bf16 v[92:95], v[108:111], v[224:227], v[92:95]
	v_mfma_f32_16x16x32_bf16 v[88:91], v[116:119], v[224:227], v[88:91]
	v_mfma_f32_16x16x32_bf16 v[76:79], v[108:111], v[232:235], v[76:79]
	v_mfma_f32_16x16x32_bf16 v[72:75], v[116:119], v[232:235], v[72:75]
	v_mfma_f32_16x16x32_bf16 v[132:135], v[144:147], v[160:163], v[132:135]
	v_mfma_f32_16x16x32_bf16 v[128:131], v[152:155], v[160:163], v[128:131]
	v_mfma_f32_16x16x32_bf16 v[100:103], v[144:147], v[196:199], v[100:103]
	v_mfma_f32_16x16x32_bf16 v[96:99], v[152:155], v[196:199], v[96:99]
	v_mfma_f32_16x16x32_bf16 v[84:87], v[144:147], v[210:213], v[84:87]
	v_mfma_f32_16x16x32_bf16 v[80:83], v[152:155], v[210:213], v[80:83]
	v_mfma_f32_16x16x32_bf16 v[68:71], v[144:147], v[228:231], v[68:71]
	v_mfma_f32_16x16x32_bf16 v[64:67], v[152:155], v[228:231], v[64:67]
	v_mfma_f32_16x16x32_bf16 v[132:135], v[148:151], v[192:195], v[132:135]
	v_mfma_f32_16x16x32_bf16 v[128:131], v[156:159], v[192:195], v[128:131]
	v_mfma_f32_16x16x32_bf16 v[100:103], v[148:151], v[206:209], v[100:103]
	v_mfma_f32_16x16x32_bf16 v[96:99], v[156:159], v[206:209], v[96:99]
	v_mfma_f32_16x16x32_bf16 v[84:87], v[148:151], v[224:227], v[84:87]
	v_mfma_f32_16x16x32_bf16 v[80:83], v[156:159], v[224:227], v[80:83]
	v_mfma_f32_16x16x32_bf16 v[68:71], v[148:151], v[232:235], v[68:71]
	v_mfma_f32_16x16x32_bf16 v[64:67], v[156:159], v[232:235], v[64:67]
	s_barrier
	s_add_i32 s50, s63, s21
	s_mov_b32 m0, s50
	ds_read_b128 v[160:163], v204 offset:16384
	ds_read_b128 v[192:195], v204 offset:17408
	ds_read_b128 v[196:199], v204 offset:18432
	ds_read_b128 v[206:209], v204 offset:19456
	ds_read_b128 v[210:213], v204 offset:20480
	ds_read_b128 v[224:227], v204 offset:21504
	ds_read_b128 v[228:231], v204 offset:22528
	ds_read_b128 v[232:235], v204 offset:23552
	global_load_lds_dwordx4 v172, s[52:53]
	s_add_i32 m0, s50, 0x2000
	s_add_u32 s50, s52, 0xa0000
	s_addc_u32 s51, s53, 0
	s_add_u32 vcc_lo, s52, 0x80
	s_addc_u32 vcc_hi, s53, 0
	s_add_i32 s63, s64, s21
	global_load_lds_dwordx4 v168, s[52:53]
	s_mov_b32 m0, s63
	s_nop 0
	global_load_lds_dwordx4 v172, s[50:51]
	s_add_i32 m0, s63, 0x2000
	s_nop 0
	global_load_lds_dwordx4 v168, s[50:51]
	s_mov_b32 m0, s30
	s_nop 0
	global_load_lds_dwordx4 v164, s[54:55]
	s_mov_b32 m0, s31
	s_nop 0
	global_load_lds_dwordx4 v166, s[54:55]
	s_waitcnt vmcnt(8) lgkmcnt(0)
	s_barrier
	v_mfma_f32_16x16x32_bf16 v[60:63], v[104:107], v[160:163], v[60:63]
	v_mfma_f32_16x16x32_bf16 v[56:59], v[112:115], v[160:163], v[56:59]
	v_mfma_f32_16x16x32_bf16 v[44:47], v[104:107], v[196:199], v[44:47]
	v_mfma_f32_16x16x32_bf16 v[40:43], v[112:115], v[196:199], v[40:43]
	v_mfma_f32_16x16x32_bf16 v[28:31], v[104:107], v[210:213], v[28:31]
	v_mfma_f32_16x16x32_bf16 v[24:27], v[112:115], v[210:213], v[24:27]
	v_mfma_f32_16x16x32_bf16 v[12:15], v[104:107], v[228:231], v[12:15]
	v_mfma_f32_16x16x32_bf16 v[8:11], v[112:115], v[228:231], v[8:11]
	v_mfma_f32_16x16x32_bf16 v[60:63], v[108:111], v[192:195], v[60:63]
	v_mfma_f32_16x16x32_bf16 v[56:59], v[116:119], v[192:195], v[56:59]
	v_mfma_f32_16x16x32_bf16 v[44:47], v[108:111], v[206:209], v[44:47]
	v_mfma_f32_16x16x32_bf16 v[40:43], v[116:119], v[206:209], v[40:43]
	v_mfma_f32_16x16x32_bf16 v[28:31], v[108:111], v[224:227], v[28:31]
	v_mfma_f32_16x16x32_bf16 v[24:27], v[116:119], v[224:227], v[24:27]
	v_mfma_f32_16x16x32_bf16 v[12:15], v[108:111], v[232:235], v[12:15]
	v_mfma_f32_16x16x32_bf16 v[8:11], v[116:119], v[232:235], v[8:11]
	v_mfma_f32_16x16x32_bf16 v[52:55], v[144:147], v[160:163], v[52:55]
	v_mfma_f32_16x16x32_bf16 v[48:51], v[152:155], v[160:163], v[48:51]
	v_mfma_f32_16x16x32_bf16 v[36:39], v[144:147], v[196:199], v[36:39]
	v_mfma_f32_16x16x32_bf16 v[32:35], v[152:155], v[196:199], v[32:35]
	v_mfma_f32_16x16x32_bf16 v[20:23], v[144:147], v[210:213], v[20:23]
	v_mfma_f32_16x16x32_bf16 v[16:19], v[152:155], v[210:213], v[16:19]
	v_mfma_f32_16x16x32_bf16 v[4:7], v[144:147], v[228:231], v[4:7]
	v_mfma_f32_16x16x32_bf16 v[0:3], v[152:155], v[228:231], v[0:3]
	v_mfma_f32_16x16x32_bf16 v[52:55], v[148:151], v[192:195], v[52:55]
	v_mfma_f32_16x16x32_bf16 v[48:51], v[156:159], v[192:195], v[48:51]
	v_mfma_f32_16x16x32_bf16 v[36:39], v[148:151], v[206:209], v[36:39]
	v_mfma_f32_16x16x32_bf16 v[32:35], v[156:159], v[206:209], v[32:35]
	v_mfma_f32_16x16x32_bf16 v[20:23], v[148:151], v[224:227], v[20:23]
	v_mfma_f32_16x16x32_bf16 v[16:19], v[156:159], v[224:227], v[16:19]
	v_mfma_f32_16x16x32_bf16 v[4:7], v[148:151], v[232:235], v[4:7]
	v_mfma_f32_16x16x32_bf16 v[0:3], v[156:159], v[232:235], v[0:3]
	s_barrier
; #define PG8_STAGE(bufoff, gbase, voff) do { _Pragma("unroll") for (int _i = 0; _i < 2; ++_i) \
;         __builtin_amdgcn_global_load_lds((const unsigned*)((const char*)(gbase) + (voff)[_i]), (PG8_LAS unsigned*)(lds + (bufoff) + ldsw + _i * 8192), 16, 0, 0); } while (0)
; #define PG8_LDA(dst, b, h) do { _Pragma("unroll") for (int m = 0; m < 4; ++m) _Pragma("unroll") for (int k = 0; k < 2; ++k) dst[m][k] = *(const PG8_LAS bf16x8*)(lds + PG8_SA(b, h) + aoff + m * 2048 + k * 1024); } while (0)
; #define PG8_LDB(dst, b, h) do { _Pragma("unroll") for (int n = 0; n < 2; ++n) _Pragma("unroll") for (int k = 0; k < 2; ++k) dst[n][k] = *(const PG8_LAS bf16x8*)(lds + PG8_SB(b, h) + boff + n * 2048 + k * 1024); } while (0)
; #define PG8_MMA(ai, bj, At, Bt) do { __builtin_amdgcn_s_setprio(1); _Pragma("unroll") for (int m = 0; m < 4; ++m) _Pragma("unroll") for (int n = 0; n < 2; ++n) _Pragma("unroll") for (int k = 0; k < 2; ++k) \
;         acc[ai][bj][m][n] = __builtin_amdgcn_mfma_f32_16x16x32_bf16(Bt[n][k], At[m][k], acc[ai][bj][m][n], 0, 0, 0); __builtin_amdgcn_s_setprio(0); } while (0)
; #define PG8_WAIT_V(n) asm volatile("s_waitcnt vmcnt(" #n ")" ::: "memory")
; #define PG8_WAIT_L(n) asm volatile("s_waitcnt lgkmcnt(" #n ")" ::: "memory")
; #define PG8_BAR __builtin_amdgcn_s_barrier()
; #define PG8_SCHED __builtin_amdgcn_sched_barrier(0)
; template <class Epi, class Sched, bool ALIGN_EPI = false, bool SP2 = false>
; __device__ __forceinline__ void gemm_phase(PG8_LAS unsigned char* lds, const Gemm g, const Sched& S, const Epi& E, const int tid_in) {
;     ...
;             PG8_LDB(B0, 1, 0); PG8_LDB(B1, 1, 1); PG8_SCHED; PG8_LDA(At, 1, 0); PG8_STAGE(PG8_SA(0, 1), a2 + hstepA, voffA);
;             PG8_WAIT_V(8); PG8_WAIT_L(0); PG8_BAR; PG8_MMA(0, 0, At, B0); PG8_MMA(0, 1, At, B1); PG8_BAR; PG8_SCHED;
;             PG8_LDA(At, 1, 1); PG8_STAGE(PG8_SB(1, 0), b3, voffB); PG8_STAGE(PG8_SB(1, 1), b3 + hstepB, voffB); PG8_STAGE(PG8_SA(1, 0), a3, voffA);
;             PG8_WAIT_V(8); PG8_WAIT_L(0); PG8_BAR; PG8_MMA(1, 0, At, B0); PG8_MMA(1, 1, At, B1); PG8_BAR; PG8_SCHED;
;     ...
;         if constexpr (ALIGN_EPI) { if (wr == 0) PG8_BAR; }
	s_add_i32 s63, 0, 0x18000
	s_add_i32 s64, 0, 0x1c000
	ds_read_b128 v[104:107], v249 offset:32768
	ds_read_b128 v[108:111], v249 offset:33792
	ds_read_b128 v[112:115], v249 offset:34816
	ds_read_b128 v[116:119], v249 offset:35840
	ds_read_b128 v[144:147], v249 offset:49152
	ds_read_b128 v[148:151], v249 offset:50176
	ds_read_b128 v[152:155], v249 offset:51200
	ds_read_b128 v[156:159], v249 offset:52224
	s_add_u32 s50, s54, 0xa0000
	s_addc_u32 s51, s55, 0
	s_mov_b32 m0, s6
	ds_read_b128 v[160:163], v204 offset:32768
	ds_read_b128 v[192:195], v204 offset:33792
	ds_read_b128 v[196:199], v204 offset:34816
	ds_read_b128 v[206:209], v204 offset:35840
	ds_read_b128 v[210:213], v204 offset:36864
	ds_read_b128 v[224:227], v204 offset:37888
	ds_read_b128 v[228:231], v204 offset:38912
	ds_read_b128 v[232:235], v204 offset:39936
	global_load_lds_dwordx4 v164, s[50:51]
	s_mov_b32 m0, s38
	s_nop 0
	global_load_lds_dwordx4 v166, s[50:51]
	s_waitcnt vmcnt(8) lgkmcnt(0)
	s_barrier
	v_mfma_f32_16x16x32_bf16 v[140:143], v[104:107], v[160:163], v[140:143]
	v_mfma_f32_16x16x32_bf16 v[136:139], v[112:115], v[160:163], v[136:139]
	v_mfma_f32_16x16x32_bf16 v[124:127], v[104:107], v[196:199], v[124:127]
	v_mfma_f32_16x16x32_bf16 v[120:123], v[112:115], v[196:199], v[120:123]
	v_mfma_f32_16x16x32_bf16 v[92:95], v[104:107], v[210:213], v[92:95]
	v_mfma_f32_16x16x32_bf16 v[88:91], v[112:115], v[210:213], v[88:91]
	v_mfma_f32_16x16x32_bf16 v[76:79], v[104:107], v[228:231], v[76:79]
	v_mfma_f32_16x16x32_bf16 v[72:75], v[112:115], v[228:231], v[72:75]
	v_mfma_f32_16x16x32_bf16 v[140:143], v[108:111], v[192:195], v[140:143]
	v_mfma_f32_16x16x32_bf16 v[136:139], v[116:119], v[192:195], v[136:139]
	v_mfma_f32_16x16x32_bf16 v[124:127], v[108:111], v[206:209], v[124:127]
	v_mfma_f32_16x16x32_bf16 v[120:123], v[116:119], v[206:209], v[120:123]
	v_mfma_f32_16x16x32_bf16 v[92:95], v[108:111], v[224:227], v[92:95]
	v_mfma_f32_16x16x32_bf16 v[88:91], v[116:119], v[224:227], v[88:91]
	v_mfma_f32_16x16x32_bf16 v[76:79], v[108:111], v[232:235], v[76:79]
	v_mfma_f32_16x16x32_bf16 v[72:75], v[116:119], v[232:235], v[72:75]
	v_mfma_f32_16x16x32_bf16 v[132:135], v[144:147], v[160:163], v[132:135]
	v_mfma_f32_16x16x32_bf16 v[128:131], v[152:155], v[160:163], v[128:131]
	v_mfma_f32_16x16x32_bf16 v[100:103], v[144:147], v[196:199], v[100:103]
	v_mfma_f32_16x16x32_bf16 v[96:99], v[152:155], v[196:199], v[96:99]
	v_mfma_f32_16x16x32_bf16 v[84:87], v[144:147], v[210:213], v[84:87]
	v_mfma_f32_16x16x32_bf16 v[80:83], v[152:155], v[210:213], v[80:83]
	v_mfma_f32_16x16x32_bf16 v[68:71], v[144:147], v[228:231], v[68:71]
	v_mfma_f32_16x16x32_bf16 v[64:67], v[152:155], v[228:231], v[64:67]
	v_mfma_f32_16x16x32_bf16 v[132:135], v[148:151], v[192:195], v[132:135]
	v_mfma_f32_16x16x32_bf16 v[128:131], v[156:159], v[192:195], v[128:131]
	v_mfma_f32_16x16x32_bf16 v[100:103], v[148:151], v[206:209], v[100:103]
	v_mfma_f32_16x16x32_bf16 v[96:99], v[156:159], v[206:209], v[96:99]
	v_mfma_f32_16x16x32_bf16 v[84:87], v[148:151], v[224:227], v[84:87]
	v_mfma_f32_16x16x32_bf16 v[80:83], v[156:159], v[224:227], v[80:83]
	v_mfma_f32_16x16x32_bf16 v[68:71], v[148:151], v[232:235], v[68:71]
	v_mfma_f32_16x16x32_bf16 v[64:67], v[156:159], v[232:235], v[64:67]
	s_barrier
	s_add_i32 s50, s63, s21
	s_mov_b32 m0, s50
	ds_read_b128 v[160:163], v204 offset:49152
	ds_read_b128 v[192:195], v204 offset:50176
	ds_read_b128 v[196:199], v204 offset:51200
	ds_read_b128 v[206:209], v204 offset:52224
	ds_read_b128 v[210:213], v204 offset:53248
	ds_read_b128 v[224:227], v204 offset:54272
	ds_read_b128 v[228:231], v204 offset:55296
	ds_read_b128 v[232:235], v204 offset:56320
	s_add_u32 s100, s52, 0x80
	s_addc_u32 s101, s53, 0
	global_load_lds_dwordx4 v172, s[100:101]
	s_add_i32 m0, s50, 0x2000
	s_add_u32 s50, s52, 0xa0080
	s_addc_u32 s51, s53, 0
	s_add_i32 s52, s64, s21
	global_load_lds_dwordx4 v168, vcc
	s_mov_b32 m0, s52
	s_nop 0
	global_load_lds_dwordx4 v172, s[50:51]
	s_add_i32 m0, s52, 0x2000
	s_nop 0
	global_load_lds_dwordx4 v168, s[50:51]
	s_mov_b32 m0, s33
	s_nop 0
	s_add_u32 s100, s54, 0x80
	s_addc_u32 s101, s55, 0
	global_load_lds_dwordx4 v164, s[100:101]
	s_mov_b32 m0, s35
	s_nop 0
	global_load_lds_dwordx4 v166, s[100:101]
	s_waitcnt vmcnt(8) lgkmcnt(0)
	s_barrier
	v_mfma_f32_16x16x32_bf16 v[60:63], v[104:107], v[160:163], v[60:63]
	v_mfma_f32_16x16x32_bf16 v[56:59], v[112:115], v[160:163], v[56:59]
	v_mfma_f32_16x16x32_bf16 v[44:47], v[104:107], v[196:199], v[44:47]
	v_mfma_f32_16x16x32_bf16 v[40:43], v[112:115], v[196:199], v[40:43]
	v_mfma_f32_16x16x32_bf16 v[28:31], v[104:107], v[210:213], v[28:31]
	v_mfma_f32_16x16x32_bf16 v[24:27], v[112:115], v[210:213], v[24:27]
	v_mfma_f32_16x16x32_bf16 v[12:15], v[104:107], v[228:231], v[12:15]
	v_mfma_f32_16x16x32_bf16 v[8:11], v[112:115], v[228:231], v[8:11]
	v_mfma_f32_16x16x32_bf16 v[60:63], v[108:111], v[192:195], v[60:63]
	v_mfma_f32_16x16x32_bf16 v[56:59], v[116:119], v[192:195], v[56:59]
	v_mfma_f32_16x16x32_bf16 v[44:47], v[108:111], v[206:209], v[44:47]
	v_mfma_f32_16x16x32_bf16 v[40:43], v[116:119], v[206:209], v[40:43]
	v_mfma_f32_16x16x32_bf16 v[28:31], v[108:111], v[224:227], v[28:31]
	v_mfma_f32_16x16x32_bf16 v[24:27], v[116:119], v[224:227], v[24:27]
	v_mfma_f32_16x16x32_bf16 v[12:15], v[108:111], v[232:235], v[12:15]
	v_mfma_f32_16x16x32_bf16 v[8:11], v[116:119], v[232:235], v[8:11]
	v_mfma_f32_16x16x32_bf16 v[52:55], v[144:147], v[160:163], v[52:55]
	v_mfma_f32_16x16x32_bf16 v[48:51], v[152:155], v[160:163], v[48:51]
	v_mfma_f32_16x16x32_bf16 v[36:39], v[144:147], v[196:199], v[36:39]
	v_mfma_f32_16x16x32_bf16 v[32:35], v[152:155], v[196:199], v[32:35]
	v_mfma_f32_16x16x32_bf16 v[20:23], v[144:147], v[210:213], v[20:23]
	v_mfma_f32_16x16x32_bf16 v[16:19], v[152:155], v[210:213], v[16:19]
	v_mfma_f32_16x16x32_bf16 v[4:7], v[144:147], v[228:231], v[4:7]
	v_mfma_f32_16x16x32_bf16 v[0:3], v[152:155], v[228:231], v[0:3]
	v_mfma_f32_16x16x32_bf16 v[52:55], v[148:151], v[192:195], v[52:55]
	v_mfma_f32_16x16x32_bf16 v[48:51], v[156:159], v[192:195], v[48:51]
	v_mfma_f32_16x16x32_bf16 v[36:39], v[148:151], v[206:209], v[36:39]
	v_mfma_f32_16x16x32_bf16 v[32:35], v[156:159], v[206:209], v[32:35]
	v_mfma_f32_16x16x32_bf16 v[20:23], v[148:151], v[224:227], v[20:23]
	v_mfma_f32_16x16x32_bf16 v[16:19], v[156:159], v[224:227], v[16:19]
	v_mfma_f32_16x16x32_bf16 v[4:7], v[148:151], v[232:235], v[4:7]
	v_mfma_f32_16x16x32_bf16 v[0:3], v[156:159], v[232:235], v[0:3]
	s_barrier
	s_add_i32 s62, s62, 2
	s_add_u32 s60, s60, 0x100
	s_addc_u32 s61, s61, 0
	s_cmp_gt_u32 s62, 37
	s_mov_b64 s[50:51], s[22:23]
	s_cbranch_scc0 .LBB0_1268
	s_and_b64 vcc, exec, s[46:47]
	s_cbranch_vccz .LBB0_1271
	s_barrier

;     __device__ __forceinline__ void a_ready(const Unit& u) const { wait_panel(cnt, u.pm, need, tmo, wave); }
;     __device__ __forceinline__ void a_ready(const Unit& u) const { wait_panel(cnt, u.pm, need, tmo, wave); }
; #define PG8_STAGE(bufoff, gbase, voff) do { _Pragma("unroll") for (int _i = 0; _i < 2; ++_i) \
;         __builtin_amdgcn_global_load_lds((const unsigned*)((const char*)(gbase) + (voff)[_i]), (PG8_LAS unsigned*)(lds + (bufoff) + ldsw + _i * 8192), 16, 0, 0); } while (0)
; #define PG8_LDA(dst, b, h) do { _Pragma("unroll") for (int m = 0; m < 4; ++m) _Pragma("unroll") for (int k = 0; k < 2; ++k) dst[m][k] = *(const PG8_LAS bf16x8*)(lds + PG8_SA(b, h) + aoff + m * 2048 + k * 1024); } while (0)
; #define PG8_LDB(dst, b, h) do { _Pragma("unroll") for (int n = 0; n < 2; ++n) _Pragma("unroll") for (int k = 0; k < 2; ++k) dst[n][k] = *(const PG8_LAS bf16x8*)(lds + PG8_SB(b, h) + boff + n * 2048 + k * 1024); } while (0)
; #define PG8_WAIT_V(n) asm volatile("s_waitcnt vmcnt(" #n ")" ::: "memory")
; #define PG8_WAIT_L(n) asm volatile("s_waitcnt lgkmcnt(" #n ")" ::: "memory")
; #define PG8_BAR __builtin_amdgcn_s_barrier()
; #define PG8_SCHED __builtin_amdgcn_sched_barrier(0)
; template <class Epi, class Sched, bool ALIGN_EPI = false, bool SP2 = false>
; __device__ __forceinline__ void gemm_phase(PG8_LAS unsigned char* lds, const Gemm g, const Sched& S, const Epi& E, const int tid_in) {
;     ...
;         for (int t = 0; t < nt; t += 2) {
;             const bool last = (t == nt - 2);
;             const char* a1 = cA + (size_t)(t + 1) * kstep;
;             const char* a2 = last ? nA : cA + (size_t)(t + 2) * kstep; const char* b2 = last ? nB : cB + (size_t)(t + 2) * kstep;
;             const char* a3 = a2 + kstep; const char* b3 = b2 + kstep;
;             if (last && has_next) S.a_ready(nxt);
;             if constexpr (SP2) {
;             PG8_LDB(B0, 0, 0); PG8_LDB(B1, 0, 1); PG8_SCHED; PG8_LDA(At, 0, 0); PG8_STAGE(PG8_SA(1, 1), a1 + hstepA, voffA);
;             PG8_WAIT_V(8); PG8_WAIT_L(0); PG8_BAR; PG8_MMA(0, 0, At, B0); PG8_MMA(0, 1, At, B1); PG8_BAR; PG8_SCHED;
;             PG8_LDA(At, 0, 1); PG8_STAGE(PG8_SB(0, 0), b2, voffB); PG8_STAGE(PG8_SB(0, 1), b2 + hstepB, voffB); PG8_STAGE(PG8_SA(0, 0), a2, voffA);
;             PG8_WAIT_V(8); PG8_WAIT_L(0); PG8_BAR; PG8_MMA(1, 0, At, B0); PG8_MMA(1, 1, At, B1); PG8_BAR; PG8_SCHED;
.LBB0_1286:
	s_add_u32 s22, s62, 0x100
	s_addc_u32 s23, s63, 0
	s_add_i32 s68, 0, 0x10000
	s_cmp_eq_u32 s61, 4
	s_cselect_b32 s67, s57, s23
	s_cselect_b32 s66, s56, s22
	s_cselect_b32 s65, s55, s60
	s_cselect_b32 s64, s54, s59
	s_add_i32 s69, 0, 0x14000
	ds_read_b128 v[64:67], v249
	ds_read_b128 v[68:71], v249 offset:1024
	ds_read_b128 v[72:75], v249 offset:2048
	ds_read_b128 v[76:79], v249 offset:3072
	ds_read_b128 v[80:83], v249 offset:16384
	ds_read_b128 v[84:87], v249 offset:17408
	ds_read_b128 v[88:91], v249 offset:18432
	ds_read_b128 v[92:95], v249 offset:19456
	s_add_i32 m0, s12, 0xc000
	ds_read_b128 v[96:99], v154
	ds_read_b128 v[100:103], v154 offset:1024
	ds_read_b128 v[104:107], v154 offset:2048
	ds_read_b128 v[108:111], v154 offset:3072
	ds_read_b128 v[112:115], v154 offset:4096
	ds_read_b128 v[116:119], v154 offset:5120
	ds_read_b128 v[120:123], v154 offset:6144
	ds_read_b128 v[124:127], v154 offset:7168
	global_load_lds_dwordx4 v148, s[62:63]
	s_add_i32 m0, s12, 0xe000
	s_nop 0
	global_load_lds_dwordx4 v146, s[62:63]
	s_waitcnt vmcnt(8) lgkmcnt(0)
	s_barrier
	v_mfma_f32_16x16x32_bf16 v[60:63], v[64:67], v[96:99], v[60:63]
	v_mfma_f32_16x16x32_bf16 v[56:59], v[72:75], v[96:99], v[56:59]
	v_mfma_f32_16x16x32_bf16 v[48:51], v[64:67], v[104:107], v[48:51]
	v_mfma_f32_16x16x32_bf16 v[40:43], v[72:75], v[104:107], v[40:43]
	v_mfma_f32_16x16x32_bf16 v[32:35], v[64:67], v[112:115], v[32:35]
	v_mfma_f32_16x16x32_bf16 v[24:27], v[72:75], v[112:115], v[24:27]
	v_mfma_f32_16x16x32_bf16 v[16:19], v[64:67], v[120:123], v[16:19]
	v_mfma_f32_16x16x32_bf16 v[8:11], v[72:75], v[120:123], v[8:11]
	v_mfma_f32_16x16x32_bf16 v[60:63], v[68:71], v[100:103], v[60:63]
	v_mfma_f32_16x16x32_bf16 v[56:59], v[76:79], v[100:103], v[56:59]
	v_mfma_f32_16x16x32_bf16 v[48:51], v[68:71], v[108:111], v[48:51]
	v_mfma_f32_16x16x32_bf16 v[40:43], v[76:79], v[108:111], v[40:43]
	v_mfma_f32_16x16x32_bf16 v[32:35], v[68:71], v[116:119], v[32:35]
	v_mfma_f32_16x16x32_bf16 v[24:27], v[76:79], v[116:119], v[24:27]
	v_mfma_f32_16x16x32_bf16 v[16:19], v[68:71], v[124:127], v[16:19]
	v_mfma_f32_16x16x32_bf16 v[8:11], v[76:79], v[124:127], v[8:11]
	v_mfma_f32_16x16x32_bf16 v[52:55], v[80:83], v[96:99], v[52:55]
	v_mfma_f32_16x16x32_bf16 v[44:47], v[88:91], v[96:99], v[44:47]
	v_mfma_f32_16x16x32_bf16 v[36:39], v[80:83], v[104:107], v[36:39]
	v_mfma_f32_16x16x32_bf16 v[28:31], v[88:91], v[104:107], v[28:31]
	v_mfma_f32_16x16x32_bf16 v[20:23], v[80:83], v[112:115], v[20:23]
	v_mfma_f32_16x16x32_bf16 v[12:15], v[88:91], v[112:115], v[12:15]
	v_mfma_f32_16x16x32_bf16 v[4:7], v[80:83], v[120:123], v[4:7]
	v_mfma_f32_16x16x32_bf16 v[0:3], v[88:91], v[120:123], v[0:3]
	v_mfma_f32_16x16x32_bf16 v[52:55], v[84:87], v[100:103], v[52:55]
	v_mfma_f32_16x16x32_bf16 v[44:47], v[92:95], v[100:103], v[44:47]
	v_mfma_f32_16x16x32_bf16 v[36:39], v[84:87], v[108:111], v[36:39]
	v_mfma_f32_16x16x32_bf16 v[28:31], v[92:95], v[108:111], v[28:31]
	v_mfma_f32_16x16x32_bf16 v[20:23], v[84:87], v[116:119], v[20:23]
	v_mfma_f32_16x16x32_bf16 v[12:15], v[92:95], v[116:119], v[12:15]
	v_mfma_f32_16x16x32_bf16 v[4:7], v[84:87], v[124:127], v[4:7]
	v_mfma_f32_16x16x32_bf16 v[0:3], v[92:95], v[124:127], v[0:3]
	s_barrier
	s_add_i32 s62, s68, s6
	s_mov_b32 m0, s62
	s_add_u32 vcc_lo, s64, 0x80
	s_addc_u32 vcc_hi, s65, 0
	global_load_lds_dwordx4 v172, s[64:65]
	s_add_i32 m0, s62, 0x2000
	s_add_u32 s62, s64, 0xa0000
	s_addc_u32 s63, s65, 0
	s_add_i32 s68, s69, s6
	global_load_lds_dwordx4 v128, s[64:65]
	s_mov_b32 m0, s68
	s_nop 0
	global_load_lds_dwordx4 v172, s[62:63]
	s_add_i32 m0, s68, 0x2000
	s_nop 0
	global_load_lds_dwordx4 v128, s[62:63]
	s_mov_b32 m0, s12
	s_nop 0
	global_load_lds_dwordx4 v172, s[66:67]
	s_mov_b32 m0, s20
	s_nop 0
	global_load_lds_dwordx4 v128, s[66:67]
	s_waitcnt vmcnt(8) lgkmcnt(0)
	s_barrier
	s_barrier
; #define PG8_STAGE(bufoff, gbase, voff) do { _Pragma("unroll") for (int _i = 0; _i < 2; ++_i) \
;         __builtin_amdgcn_global_load_lds((const unsigned*)((const char*)(gbase) + (voff)[_i]), (PG8_LAS unsigned*)(lds + (bufoff) + ldsw + _i * 8192), 16, 0, 0); } while (0)
; #define PG8_LDA(dst, b, h) do { _Pragma("unroll") for (int m = 0; m < 4; ++m) _Pragma("unroll") for (int k = 0; k < 2; ++k) dst[m][k] = *(const PG8_LAS bf16x8*)(lds + PG8_SA(b, h) + aoff + m * 2048 + k * 1024); } while (0)
; #define PG8_LDB(dst, b, h) do { _Pragma("unroll") for (int n = 0; n < 2; ++n) _Pragma("unroll") for (int k = 0; k < 2; ++k) dst[n][k] = *(const PG8_LAS bf16x8*)(lds + PG8_SB(b, h) + boff + n * 2048 + k * 1024); } while (0)
; #define PG8_MMA(ai, bj, At, Bt) do { __builtin_amdgcn_s_setprio(1); _Pragma("unroll") for (int m = 0; m < 4; ++m) _Pragma("unroll") for (int n = 0; n < 2; ++n) _Pragma("unroll") for (int k = 0; k < 2; ++k) \
;         acc[ai][bj][m][n] = __builtin_amdgcn_mfma_f32_16x16x32_bf16(Bt[n][k], At[m][k], acc[ai][bj][m][n], 0, 0, 0); __builtin_amdgcn_s_setprio(0); } while (0)
; #define PG8_WAIT_V(n) asm volatile("s_waitcnt vmcnt(" #n ")" ::: "memory")
; #define PG8_WAIT_L(n) asm volatile("s_waitcnt lgkmcnt(" #n ")" ::: "memory")
; #define PG8_BAR __builtin_amdgcn_s_barrier()
; #define PG8_SCHED __builtin_amdgcn_sched_barrier(0)
; template <class Epi, class Sched, bool ALIGN_EPI = false, bool SP2 = false>
; __device__ __forceinline__ void gemm_phase(PG8_LAS unsigned char* lds, const Gemm g, const Sched& S, const Epi& E, const int tid_in) {
;     ...
;             PG8_LDB(B0, 1, 0); PG8_LDB(B1, 1, 1); PG8_SCHED; PG8_LDA(At, 1, 0); PG8_STAGE(PG8_SA(0, 1), a2 + hstepA, voffA);
;             PG8_WAIT_V(8); PG8_WAIT_L(0); PG8_BAR; PG8_MMA(0, 0, At, B0); PG8_MMA(0, 1, At, B1); PG8_BAR; PG8_SCHED;
;             PG8_LDA(At, 1, 1); PG8_STAGE(PG8_SB(1, 0), b3, voffB); PG8_STAGE(PG8_SB(1, 1), b3 + hstepB, voffB); PG8_STAGE(PG8_SA(1, 0), a3, voffA);
;             PG8_WAIT_V(8); PG8_WAIT_L(0); PG8_BAR; PG8_MMA(1, 0, At, B0); PG8_MMA(1, 1, At, B1); PG8_BAR; PG8_SCHED;
;     ...
;         if constexpr (ALIGN_EPI) { if (wr == 0) PG8_BAR; }
	s_add_i32 s68, 0, 0x18000
	s_add_i32 s69, 0, 0x1c000
	ds_read_b128 v[64:67], v249 offset:32768
	ds_read_b128 v[68:71], v249 offset:33792
	ds_read_b128 v[72:75], v249 offset:34816
	ds_read_b128 v[76:79], v249 offset:35840
	ds_read_b128 v[80:83], v249 offset:49152
	ds_read_b128 v[84:87], v249 offset:50176
	ds_read_b128 v[88:91], v249 offset:51200
	ds_read_b128 v[92:95], v249 offset:52224
	s_add_u32 s62, s66, 0xa0000
	s_addc_u32 s63, s67, 0
	s_mov_b32 m0, s21
	ds_read_b128 v[96:99], v154 offset:32768
	ds_read_b128 v[100:103], v154 offset:33792
	ds_read_b128 v[104:107], v154 offset:34816
	ds_read_b128 v[108:111], v154 offset:35840
	ds_read_b128 v[112:115], v154 offset:36864
	ds_read_b128 v[116:119], v154 offset:37888
	ds_read_b128 v[120:123], v154 offset:38912
	ds_read_b128 v[124:127], v154 offset:39936
	global_load_lds_dwordx4 v172, s[62:63]
	s_mov_b32 m0, s30
	s_nop 0
	global_load_lds_dwordx4 v128, s[62:63]
	s_waitcnt vmcnt(8) lgkmcnt(0)
	s_barrier
	v_mfma_f32_16x16x32_bf16 v[60:63], v[64:67], v[96:99], v[60:63]
	v_mfma_f32_16x16x32_bf16 v[56:59], v[72:75], v[96:99], v[56:59]
	v_mfma_f32_16x16x32_bf16 v[48:51], v[64:67], v[104:107], v[48:51]
	v_mfma_f32_16x16x32_bf16 v[40:43], v[72:75], v[104:107], v[40:43]
	v_mfma_f32_16x16x32_bf16 v[32:35], v[64:67], v[112:115], v[32:35]
	v_mfma_f32_16x16x32_bf16 v[24:27], v[72:75], v[112:115], v[24:27]
	v_mfma_f32_16x16x32_bf16 v[16:19], v[64:67], v[120:123], v[16:19]
	v_mfma_f32_16x16x32_bf16 v[8:11], v[72:75], v[120:123], v[8:11]
	v_mfma_f32_16x16x32_bf16 v[60:63], v[68:71], v[100:103], v[60:63]
	v_mfma_f32_16x16x32_bf16 v[56:59], v[76:79], v[100:103], v[56:59]
	v_mfma_f32_16x16x32_bf16 v[48:51], v[68:71], v[108:111], v[48:51]
	v_mfma_f32_16x16x32_bf16 v[40:43], v[76:79], v[108:111], v[40:43]
	v_mfma_f32_16x16x32_bf16 v[32:35], v[68:71], v[116:119], v[32:35]
	v_mfma_f32_16x16x32_bf16 v[24:27], v[76:79], v[116:119], v[24:27]
	v_mfma_f32_16x16x32_bf16 v[16:19], v[68:71], v[124:127], v[16:19]
	v_mfma_f32_16x16x32_bf16 v[8:11], v[76:79], v[124:127], v[8:11]
	v_mfma_f32_16x16x32_bf16 v[52:55], v[80:83], v[96:99], v[52:55]
	v_mfma_f32_16x16x32_bf16 v[44:47], v[88:91], v[96:99], v[44:47]
	v_mfma_f32_16x16x32_bf16 v[36:39], v[80:83], v[104:107], v[36:39]
	v_mfma_f32_16x16x32_bf16 v[28:31], v[88:91], v[104:107], v[28:31]
	v_mfma_f32_16x16x32_bf16 v[20:23], v[80:83], v[112:115], v[20:23]
	v_mfma_f32_16x16x32_bf16 v[12:15], v[88:91], v[112:115], v[12:15]
	v_mfma_f32_16x16x32_bf16 v[4:7], v[80:83], v[120:123], v[4:7]
	v_mfma_f32_16x16x32_bf16 v[0:3], v[88:91], v[120:123], v[0:3]
	v_mfma_f32_16x16x32_bf16 v[52:55], v[84:87], v[100:103], v[52:55]
	v_mfma_f32_16x16x32_bf16 v[44:47], v[92:95], v[100:103], v[44:47]
	v_mfma_f32_16x16x32_bf16 v[36:39], v[84:87], v[108:111], v[36:39]
	v_mfma_f32_16x16x32_bf16 v[28:31], v[92:95], v[108:111], v[28:31]
	v_mfma_f32_16x16x32_bf16 v[20:23], v[84:87], v[116:119], v[20:23]
	v_mfma_f32_16x16x32_bf16 v[12:15], v[92:95], v[116:119], v[12:15]
	v_mfma_f32_16x16x32_bf16 v[4:7], v[84:87], v[124:127], v[4:7]
	v_mfma_f32_16x16x32_bf16 v[0:3], v[92:95], v[124:127], v[0:3]
	s_barrier
	s_add_i32 s62, s68, s6
	s_mov_b32 m0, s62
	s_nop 0
	s_add_u32 s100, s64, 0x80
	s_addc_u32 s101, s65, 0
	global_load_lds_dwordx4 v172, s[100:101]
	s_add_i32 m0, s62, 0x2000
	s_add_u32 s62, s64, 0xa0080
	s_addc_u32 s63, s65, 0
	s_add_i32 s64, s69, s6
	global_load_lds_dwordx4 v128, vcc
	s_mov_b32 m0, s64
	s_nop 0
	global_load_lds_dwordx4 v172, s[62:63]
	s_add_i32 m0, s64, 0x2000
	s_nop 0
	global_load_lds_dwordx4 v128, s[62:63]
	s_mov_b32 m0, s31
	s_nop 0
	s_add_u32 s100, s66, 0x80
	s_addc_u32 s101, s67, 0
	global_load_lds_dwordx4 v172, s[100:101]
	s_mov_b32 m0, s33
	s_nop 0
	global_load_lds_dwordx4 v128, s[100:101]
	s_waitcnt vmcnt(8) lgkmcnt(0)
	s_barrier
	s_barrier
	s_add_i32 s61, s61, 2
	s_add_u32 s59, s59, 0x100
	s_addc_u32 s60, s60, 0
	s_cmp_gt_u32 s61, 5
	s_mov_b64 s[62:63], s[22:23]
	s_cbranch_scc0 .LBB0_1286
	s_and_b64 vcc, exec, s[28:29]
	s_cbranch_vccz .LBB0_1289
	s_barrier

;     __device__ __forceinline__ void a_ready(const Unit& u) const { wait_panel(cnt, u.pm, need, tmo, wave); }
;     __device__ __forceinline__ void a_ready(const Unit& u) const { wait_panel(cnt, u.pm, need, tmo, wave); }
; #define PG8_STAGE(bufoff, gbase, voff) do { _Pragma("unroll") for (int _i = 0; _i < 2; ++_i) \
;         __builtin_amdgcn_global_load_lds((const unsigned*)((const char*)(gbase) + (voff)[_i]), (PG8_LAS unsigned*)(lds + (bufoff) + ldsw + _i * 8192), 16, 0, 0); } while (0)
; #define PG8_LDA(dst, b, h) do { _Pragma("unroll") for (int m = 0; m < 4; ++m) _Pragma("unroll") for (int k = 0; k < 2; ++k) dst[m][k] = *(const PG8_LAS bf16x8*)(lds + PG8_SA(b, h) + aoff + m * 2048 + k * 1024); } while (0)
; #define PG8_LDB(dst, b, h) do { _Pragma("unroll") for (int n = 0; n < 2; ++n) _Pragma("unroll") for (int k = 0; k < 2; ++k) dst[n][k] = *(const PG8_LAS bf16x8*)(lds + PG8_SB(b, h) + boff + n * 2048 + k * 1024); } while (0)
; #define PG8_WAIT_V(n) asm volatile("s_waitcnt vmcnt(" #n ")" ::: "memory")
; #define PG8_WAIT_L(n) asm volatile("s_waitcnt lgkmcnt(" #n ")" ::: "memory")
; #define PG8_BAR __builtin_amdgcn_s_barrier()
; #define PG8_SCHED __builtin_amdgcn_sched_barrier(0)
; template <class Epi, class Sched, bool ALIGN_EPI = false, bool SP2 = false>
; __device__ __forceinline__ void gemm_phase(PG8_LAS unsigned char* lds, const Gemm g, const Sched& S, const Epi& E, const int tid_in) {
;     ...
;         for (int t = 0; t < nt; t += 2) {
;             const bool last = (t == nt - 2);
;             const char* a1 = cA + (size_t)(t + 1) * kstep;
;             const char* a2 = last ? nA : cA + (size_t)(t + 2) * kstep; const char* b2 = last ? nB : cB + (size_t)(t + 2) * kstep;
;             const char* a3 = a2 + kstep; const char* b3 = b2 + kstep;
;             if (last && has_next) S.a_ready(nxt);
;             if constexpr (SP2) {
;             PG8_LDB(B0, 0, 0); PG8_LDB(B1, 0, 1); PG8_SCHED; PG8_LDA(At, 0, 0); PG8_STAGE(PG8_SA(1, 1), a1 + hstepA, voffA);
;             PG8_WAIT_V(8); PG8_WAIT_L(0); PG8_BAR; PG8_MMA(0, 0, At, B0); PG8_MMA(0, 1, At, B1); PG8_BAR; PG8_SCHED;
;             PG8_LDA(At, 0, 1); PG8_STAGE(PG8_SB(0, 0), b2, voffB); PG8_STAGE(PG8_SB(0, 1), b2 + hstepB, voffB); PG8_STAGE(PG8_SA(0, 0), a2, voffA);
;             PG8_WAIT_V(8); PG8_WAIT_L(0); PG8_BAR; PG8_MMA(1, 0, At, B0); PG8_MMA(1, 1, At, B1); PG8_BAR; PG8_SCHED;
.LBB0_1444:
	s_add_u32 s22, s52, 0xfff80080
	s_addc_u32 s23, s53, -1
	s_add_i32 s58, 0, 0x10000
	s_cmp_eq_u32 s57, 28
	s_cselect_b32 s55, s35, s23
	s_cselect_b32 s54, s38, s22
	s_cselect_b32 s23, s43, s56
	s_cselect_b32 s22, s45, s51
	s_add_i32 s60, 0, 0x14000
	ds_read_b128 v[140:143], v249
	ds_read_b128 v[148:151], v249 offset:1024
	ds_read_b128 v[152:155], v249 offset:2048
	ds_read_b128 v[156:159], v249 offset:3072
	ds_read_b128 v[160:163], v249 offset:16384
	ds_read_b128 v[164:167], v249 offset:17408
	ds_read_b128 v[168:171], v249 offset:18432
	ds_read_b128 v[190:193], v249 offset:19456
	s_add_i32 m0, s18, 0xc000
	ds_read_b128 v[194:197], v147
	ds_read_b128 v[198:201], v147 offset:1024
	ds_read_b128 v[202:205], v147 offset:2048
	ds_read_b128 v[206:209], v147 offset:3072
	ds_read_b128 v[210:213], v147 offset:4096
	ds_read_b128 v[224:227], v147 offset:5120
	ds_read_b128 v[228:231], v147 offset:6144
	ds_read_b128 v[232:235], v147 offset:7168
	global_load_lds_dwordx4 v134, s[52:53]
	s_add_i32 m0, s18, 0xe000
	s_nop 0
	global_load_lds_dwordx4 v136, s[52:53]
	s_waitcnt vmcnt(8) lgkmcnt(0)
	s_barrier
	v_mfma_f32_16x16x32_bf16 v[124:127], v[140:143], v[194:197], v[124:127]
	v_mfma_f32_16x16x32_bf16 v[120:123], v[152:155], v[194:197], v[120:123]
	v_mfma_f32_16x16x32_bf16 v[112:115], v[140:143], v[202:205], v[112:115]
	v_mfma_f32_16x16x32_bf16 v[104:107], v[152:155], v[202:205], v[104:107]
	v_mfma_f32_16x16x32_bf16 v[96:99], v[140:143], v[210:213], v[96:99]
	v_mfma_f32_16x16x32_bf16 v[88:91], v[152:155], v[210:213], v[88:91]
	v_mfma_f32_16x16x32_bf16 v[80:83], v[140:143], v[228:231], v[80:83]
	v_mfma_f32_16x16x32_bf16 v[72:75], v[152:155], v[228:231], v[72:75]
	v_mfma_f32_16x16x32_bf16 v[124:127], v[148:151], v[198:201], v[124:127]
	v_mfma_f32_16x16x32_bf16 v[120:123], v[156:159], v[198:201], v[120:123]
	v_mfma_f32_16x16x32_bf16 v[112:115], v[148:151], v[206:209], v[112:115]
	v_mfma_f32_16x16x32_bf16 v[104:107], v[156:159], v[206:209], v[104:107]
	v_mfma_f32_16x16x32_bf16 v[96:99], v[148:151], v[224:227], v[96:99]
	v_mfma_f32_16x16x32_bf16 v[88:91], v[156:159], v[224:227], v[88:91]
	v_mfma_f32_16x16x32_bf16 v[80:83], v[148:151], v[232:235], v[80:83]
	v_mfma_f32_16x16x32_bf16 v[72:75], v[156:159], v[232:235], v[72:75]
	v_mfma_f32_16x16x32_bf16 v[116:119], v[160:163], v[194:197], v[116:119]
	v_mfma_f32_16x16x32_bf16 v[108:111], v[168:171], v[194:197], v[108:111]
	v_mfma_f32_16x16x32_bf16 v[100:103], v[160:163], v[202:205], v[100:103]
	v_mfma_f32_16x16x32_bf16 v[92:95], v[168:171], v[202:205], v[92:95]
	v_mfma_f32_16x16x32_bf16 v[84:87], v[160:163], v[210:213], v[84:87]
	v_mfma_f32_16x16x32_bf16 v[76:79], v[168:171], v[210:213], v[76:79]
	v_mfma_f32_16x16x32_bf16 v[68:71], v[160:163], v[228:231], v[68:71]
	v_mfma_f32_16x16x32_bf16 v[64:67], v[168:171], v[228:231], v[64:67]
	v_mfma_f32_16x16x32_bf16 v[116:119], v[164:167], v[198:201], v[116:119]
	v_mfma_f32_16x16x32_bf16 v[108:111], v[190:193], v[198:201], v[108:111]
	v_mfma_f32_16x16x32_bf16 v[100:103], v[164:167], v[206:209], v[100:103]
	v_mfma_f32_16x16x32_bf16 v[92:95], v[190:193], v[206:209], v[92:95]
	v_mfma_f32_16x16x32_bf16 v[84:87], v[164:167], v[224:227], v[84:87]
	v_mfma_f32_16x16x32_bf16 v[76:79], v[190:193], v[224:227], v[76:79]
	v_mfma_f32_16x16x32_bf16 v[68:71], v[164:167], v[232:235], v[68:71]
	v_mfma_f32_16x16x32_bf16 v[64:67], v[190:193], v[232:235], v[64:67]
	s_barrier
	s_add_i32 s58, s58, s17
	s_mov_b32 m0, s58
	ds_read_b128 v[194:197], v147 offset:16384
	ds_read_b128 v[198:201], v147 offset:17408
	ds_read_b128 v[202:205], v147 offset:18432
	ds_read_b128 v[206:209], v147 offset:19456
	ds_read_b128 v[210:213], v147 offset:20480
	ds_read_b128 v[224:227], v147 offset:21504
	ds_read_b128 v[228:231], v147 offset:22528
	ds_read_b128 v[232:235], v147 offset:23552
	global_load_lds_dwordx4 v172, s[22:23]
	s_add_i32 m0, s58, 0x2000
	s_add_u32 s58, s22, 0x80000
	s_addc_u32 s59, s23, 0
	s_add_i32 s60, s60, s17
	global_load_lds_dwordx4 v132, s[22:23]
	s_mov_b32 m0, s60
	s_nop 0
	global_load_lds_dwordx4 v172, s[58:59]
	s_add_i32 m0, s60, 0x2000
	s_nop 0
	global_load_lds_dwordx4 v132, s[58:59]
	s_add_u32 vcc_lo, s54, 0x80
	s_addc_u32 vcc_hi, s55, 0
	s_mov_b32 m0, s18
	s_nop 0
	global_load_lds_dwordx4 v128, s[54:55]
	s_mov_b32 m0, s19
	s_nop 0
	global_load_lds_dwordx4 v130, s[54:55]
	s_waitcnt vmcnt(8) lgkmcnt(0)
	s_barrier
	v_mfma_f32_16x16x32_bf16 v[60:63], v[140:143], v[194:197], v[60:63]
	v_mfma_f32_16x16x32_bf16 v[56:59], v[152:155], v[194:197], v[56:59]
	v_mfma_f32_16x16x32_bf16 v[48:51], v[140:143], v[202:205], v[48:51]
	v_mfma_f32_16x16x32_bf16 v[40:43], v[152:155], v[202:205], v[40:43]
	v_mfma_f32_16x16x32_bf16 v[32:35], v[140:143], v[210:213], v[32:35]
	v_mfma_f32_16x16x32_bf16 v[24:27], v[152:155], v[210:213], v[24:27]
	v_mfma_f32_16x16x32_bf16 v[16:19], v[140:143], v[228:231], v[16:19]
	v_mfma_f32_16x16x32_bf16 v[8:11], v[152:155], v[228:231], v[8:11]
	v_mfma_f32_16x16x32_bf16 v[60:63], v[148:151], v[198:201], v[60:63]
	v_mfma_f32_16x16x32_bf16 v[56:59], v[156:159], v[198:201], v[56:59]
	v_mfma_f32_16x16x32_bf16 v[48:51], v[148:151], v[206:209], v[48:51]
	v_mfma_f32_16x16x32_bf16 v[40:43], v[156:159], v[206:209], v[40:43]
	v_mfma_f32_16x16x32_bf16 v[32:35], v[148:151], v[224:227], v[32:35]
	v_mfma_f32_16x16x32_bf16 v[24:27], v[156:159], v[224:227], v[24:27]
	v_mfma_f32_16x16x32_bf16 v[16:19], v[148:151], v[232:235], v[16:19]
	v_mfma_f32_16x16x32_bf16 v[8:11], v[156:159], v[232:235], v[8:11]
	v_mfma_f32_16x16x32_bf16 v[52:55], v[160:163], v[194:197], v[52:55]
	v_mfma_f32_16x16x32_bf16 v[44:47], v[168:171], v[194:197], v[44:47]
	v_mfma_f32_16x16x32_bf16 v[36:39], v[160:163], v[202:205], v[36:39]
	v_mfma_f32_16x16x32_bf16 v[28:31], v[168:171], v[202:205], v[28:31]
	v_mfma_f32_16x16x32_bf16 v[20:23], v[160:163], v[210:213], v[20:23]
	v_mfma_f32_16x16x32_bf16 v[12:15], v[168:171], v[210:213], v[12:15]
	v_mfma_f32_16x16x32_bf16 v[4:7], v[160:163], v[228:231], v[4:7]
	v_mfma_f32_16x16x32_bf16 v[0:3], v[168:171], v[228:231], v[0:3]
	v_mfma_f32_16x16x32_bf16 v[52:55], v[164:167], v[198:201], v[52:55]
	v_mfma_f32_16x16x32_bf16 v[44:47], v[190:193], v[198:201], v[44:47]
	v_mfma_f32_16x16x32_bf16 v[36:39], v[164:167], v[206:209], v[36:39]
	v_mfma_f32_16x16x32_bf16 v[28:31], v[190:193], v[206:209], v[28:31]
	v_mfma_f32_16x16x32_bf16 v[20:23], v[164:167], v[224:227], v[20:23]
	v_mfma_f32_16x16x32_bf16 v[12:15], v[190:193], v[224:227], v[12:15]
	v_mfma_f32_16x16x32_bf16 v[4:7], v[164:167], v[232:235], v[4:7]
	v_mfma_f32_16x16x32_bf16 v[0:3], v[190:193], v[232:235], v[0:3]
	s_barrier
; #define PG8_STAGE(bufoff, gbase, voff) do { _Pragma("unroll") for (int _i = 0; _i < 2; ++_i) \
;         __builtin_amdgcn_global_load_lds((const unsigned*)((const char*)(gbase) + (voff)[_i]), (PG8_LAS unsigned*)(lds + (bufoff) + ldsw + _i * 8192), 16, 0, 0); } while (0)
; #define PG8_LDA(dst, b, h) do { _Pragma("unroll") for (int m = 0; m < 4; ++m) _Pragma("unroll") for (int k = 0; k < 2; ++k) dst[m][k] = *(const PG8_LAS bf16x8*)(lds + PG8_SA(b, h) + aoff + m * 2048 + k * 1024); } while (0)
; #define PG8_LDB(dst, b, h) do { _Pragma("unroll") for (int n = 0; n < 2; ++n) _Pragma("unroll") for (int k = 0; k < 2; ++k) dst[n][k] = *(const PG8_LAS bf16x8*)(lds + PG8_SB(b, h) + boff + n * 2048 + k * 1024); } while (0)
; #define PG8_MMA(ai, bj, At, Bt) do { __builtin_amdgcn_s_setprio(1); _Pragma("unroll") for (int m = 0; m < 4; ++m) _Pragma("unroll") for (int n = 0; n < 2; ++n) _Pragma("unroll") for (int k = 0; k < 2; ++k) \
;         acc[ai][bj][m][n] = __builtin_amdgcn_mfma_f32_16x16x32_bf16(Bt[n][k], At[m][k], acc[ai][bj][m][n], 0, 0, 0); __builtin_amdgcn_s_setprio(0); } while (0)
; #define PG8_WAIT_V(n) asm volatile("s_waitcnt vmcnt(" #n ")" ::: "memory")
; #define PG8_WAIT_L(n) asm volatile("s_waitcnt lgkmcnt(" #n ")" ::: "memory")
; #define PG8_BAR __builtin_amdgcn_s_barrier()
; #define PG8_SCHED __builtin_amdgcn_sched_barrier(0)
; template <class Epi, class Sched, bool ALIGN_EPI = false, bool SP2 = false>
; __device__ __forceinline__ void gemm_phase(PG8_LAS unsigned char* lds, const Gemm g, const Sched& S, const Epi& E, const int tid_in) {
;     ...
;             PG8_LDB(B0, 1, 0); PG8_LDB(B1, 1, 1); PG8_SCHED; PG8_LDA(At, 1, 0); PG8_STAGE(PG8_SA(0, 1), a2 + hstepA, voffA);
;             PG8_WAIT_V(8); PG8_WAIT_L(0); PG8_BAR; PG8_MMA(0, 0, At, B0); PG8_MMA(0, 1, At, B1); PG8_BAR; PG8_SCHED;
;             PG8_LDA(At, 1, 1); PG8_STAGE(PG8_SB(1, 0), b3, voffB); PG8_STAGE(PG8_SB(1, 1), b3 + hstepB, voffB); PG8_STAGE(PG8_SA(1, 0), a3, voffA);
;             PG8_WAIT_V(8); PG8_WAIT_L(0); PG8_BAR; PG8_MMA(1, 0, At, B0); PG8_MMA(1, 1, At, B1); PG8_BAR; PG8_SCHED;
;     ...
;         if constexpr (ALIGN_EPI) { if (wr == 0) PG8_BAR; }
	s_add_i32 s58, 0, 0x18000
	s_add_i32 s59, 0, 0x1c000
	ds_read_b128 v[140:143], v249 offset:32768
	ds_read_b128 v[148:151], v249 offset:33792
	ds_read_b128 v[152:155], v249 offset:34816
	ds_read_b128 v[156:159], v249 offset:35840
	ds_read_b128 v[160:163], v249 offset:49152
	ds_read_b128 v[164:167], v249 offset:50176
	ds_read_b128 v[168:171], v249 offset:51200
	ds_read_b128 v[190:193], v249 offset:52224
	s_add_u32 s54, s54, 0x80000
	s_addc_u32 s55, s55, 0
	s_mov_b32 m0, s20
	ds_read_b128 v[194:197], v147 offset:32768
	ds_read_b128 v[198:201], v147 offset:33792
	ds_read_b128 v[202:205], v147 offset:34816
	ds_read_b128 v[206:209], v147 offset:35840
	ds_read_b128 v[210:213], v147 offset:36864
	ds_read_b128 v[224:227], v147 offset:37888
	ds_read_b128 v[228:231], v147 offset:38912
	ds_read_b128 v[232:235], v147 offset:39936
	global_load_lds_dwordx4 v128, s[54:55]
	s_mov_b32 m0, s21
	s_nop 0
	global_load_lds_dwordx4 v130, s[54:55]
	s_waitcnt vmcnt(8) lgkmcnt(0)
	s_barrier
	v_mfma_f32_16x16x32_bf16 v[124:127], v[140:143], v[194:197], v[124:127]
	v_mfma_f32_16x16x32_bf16 v[120:123], v[152:155], v[194:197], v[120:123]
	v_mfma_f32_16x16x32_bf16 v[112:115], v[140:143], v[202:205], v[112:115]
	v_mfma_f32_16x16x32_bf16 v[104:107], v[152:155], v[202:205], v[104:107]
	v_mfma_f32_16x16x32_bf16 v[96:99], v[140:143], v[210:213], v[96:99]
	v_mfma_f32_16x16x32_bf16 v[88:91], v[152:155], v[210:213], v[88:91]
	v_mfma_f32_16x16x32_bf16 v[80:83], v[140:143], v[228:231], v[80:83]
	v_mfma_f32_16x16x32_bf16 v[72:75], v[152:155], v[228:231], v[72:75]
	v_mfma_f32_16x16x32_bf16 v[124:127], v[148:151], v[198:201], v[124:127]
	v_mfma_f32_16x16x32_bf16 v[120:123], v[156:159], v[198:201], v[120:123]
	v_mfma_f32_16x16x32_bf16 v[112:115], v[148:151], v[206:209], v[112:115]
	v_mfma_f32_16x16x32_bf16 v[104:107], v[156:159], v[206:209], v[104:107]
	v_mfma_f32_16x16x32_bf16 v[96:99], v[148:151], v[224:227], v[96:99]
	v_mfma_f32_16x16x32_bf16 v[88:91], v[156:159], v[224:227], v[88:91]
	v_mfma_f32_16x16x32_bf16 v[80:83], v[148:151], v[232:235], v[80:83]
	v_mfma_f32_16x16x32_bf16 v[72:75], v[156:159], v[232:235], v[72:75]
	v_mfma_f32_16x16x32_bf16 v[116:119], v[160:163], v[194:197], v[116:119]
	v_mfma_f32_16x16x32_bf16 v[108:111], v[168:171], v[194:197], v[108:111]
	v_mfma_f32_16x16x32_bf16 v[100:103], v[160:163], v[202:205], v[100:103]
	v_mfma_f32_16x16x32_bf16 v[92:95], v[168:171], v[202:205], v[92:95]
	v_mfma_f32_16x16x32_bf16 v[84:87], v[160:163], v[210:213], v[84:87]
	v_mfma_f32_16x16x32_bf16 v[76:79], v[168:171], v[210:213], v[76:79]
	v_mfma_f32_16x16x32_bf16 v[68:71], v[160:163], v[228:231], v[68:71]
	v_mfma_f32_16x16x32_bf16 v[64:67], v[168:171], v[228:231], v[64:67]
	v_mfma_f32_16x16x32_bf16 v[116:119], v[164:167], v[198:201], v[116:119]
	v_mfma_f32_16x16x32_bf16 v[108:111], v[190:193], v[198:201], v[108:111]
	v_mfma_f32_16x16x32_bf16 v[100:103], v[164:167], v[206:209], v[100:103]
	v_mfma_f32_16x16x32_bf16 v[92:95], v[190:193], v[206:209], v[92:95]
	v_mfma_f32_16x16x32_bf16 v[84:87], v[164:167], v[224:227], v[84:87]
	v_mfma_f32_16x16x32_bf16 v[76:79], v[190:193], v[224:227], v[76:79]
	v_mfma_f32_16x16x32_bf16 v[68:71], v[164:167], v[232:235], v[68:71]
	v_mfma_f32_16x16x32_bf16 v[64:67], v[190:193], v[232:235], v[64:67]
	s_barrier
	s_add_i32 s54, s58, s17
	s_mov_b32 m0, s54
	ds_read_b128 v[194:197], v147 offset:49152
	ds_read_b128 v[198:201], v147 offset:50176
	ds_read_b128 v[202:205], v147 offset:51200
	ds_read_b128 v[206:209], v147 offset:52224
	ds_read_b128 v[210:213], v147 offset:53248
	ds_read_b128 v[224:227], v147 offset:54272
	ds_read_b128 v[228:231], v147 offset:55296
	ds_read_b128 v[232:235], v147 offset:56320
	s_add_u32 s100, s22, 0x80
	s_addc_u32 s101, s23, 0
	global_load_lds_dwordx4 v172, s[100:101]
	s_add_i32 m0, s54, 0x2000
	s_add_u32 s22, s22, 0x80080
	s_addc_u32 s23, s23, 0
	s_add_i32 s54, s59, s17
	global_load_lds_dwordx4 v132, s[100:101]
	s_mov_b32 m0, s54
	s_nop 0
	global_load_lds_dwordx4 v172, s[22:23]
	s_add_i32 m0, s54, 0x2000
	s_nop 0
	global_load_lds_dwordx4 v132, s[22:23]
	s_mov_b32 m0, s29
	s_nop 0
	global_load_lds_dwordx4 v128, vcc
	s_mov_b32 m0, s30
	s_nop 0
	global_load_lds_dwordx4 v130, vcc
	s_waitcnt vmcnt(8) lgkmcnt(0)
	s_barrier
	v_mfma_f32_16x16x32_bf16 v[60:63], v[140:143], v[194:197], v[60:63]
	v_mfma_f32_16x16x32_bf16 v[56:59], v[152:155], v[194:197], v[56:59]
	v_mfma_f32_16x16x32_bf16 v[48:51], v[140:143], v[202:205], v[48:51]
	v_mfma_f32_16x16x32_bf16 v[40:43], v[152:155], v[202:205], v[40:43]
	v_mfma_f32_16x16x32_bf16 v[32:35], v[140:143], v[210:213], v[32:35]
	v_mfma_f32_16x16x32_bf16 v[24:27], v[152:155], v[210:213], v[24:27]
	v_mfma_f32_16x16x32_bf16 v[16:19], v[140:143], v[228:231], v[16:19]
	v_mfma_f32_16x16x32_bf16 v[8:11], v[152:155], v[228:231], v[8:11]
	v_mfma_f32_16x16x32_bf16 v[60:63], v[148:151], v[198:201], v[60:63]
	v_mfma_f32_16x16x32_bf16 v[56:59], v[156:159], v[198:201], v[56:59]
	v_mfma_f32_16x16x32_bf16 v[48:51], v[148:151], v[206:209], v[48:51]
	v_mfma_f32_16x16x32_bf16 v[40:43], v[156:159], v[206:209], v[40:43]
	v_mfma_f32_16x16x32_bf16 v[32:35], v[148:151], v[224:227], v[32:35]
	v_mfma_f32_16x16x32_bf16 v[24:27], v[156:159], v[224:227], v[24:27]
	v_mfma_f32_16x16x32_bf16 v[16:19], v[148:151], v[232:235], v[16:19]
	v_mfma_f32_16x16x32_bf16 v[8:11], v[156:159], v[232:235], v[8:11]
	v_mfma_f32_16x16x32_bf16 v[52:55], v[160:163], v[194:197], v[52:55]
	v_mfma_f32_16x16x32_bf16 v[44:47], v[168:171], v[194:197], v[44:47]
	v_mfma_f32_16x16x32_bf16 v[36:39], v[160:163], v[202:205], v[36:39]
	v_mfma_f32_16x16x32_bf16 v[28:31], v[168:171], v[202:205], v[28:31]
	v_mfma_f32_16x16x32_bf16 v[20:23], v[160:163], v[210:213], v[20:23]
	v_mfma_f32_16x16x32_bf16 v[12:15], v[168:171], v[210:213], v[12:15]
	v_mfma_f32_16x16x32_bf16 v[4:7], v[160:163], v[228:231], v[4:7]
	v_mfma_f32_16x16x32_bf16 v[0:3], v[168:171], v[228:231], v[0:3]
	v_mfma_f32_16x16x32_bf16 v[52:55], v[164:167], v[198:201], v[52:55]
	v_mfma_f32_16x16x32_bf16 v[44:47], v[190:193], v[198:201], v[44:47]
	v_mfma_f32_16x16x32_bf16 v[36:39], v[164:167], v[206:209], v[36:39]
	v_mfma_f32_16x16x32_bf16 v[28:31], v[190:193], v[206:209], v[28:31]
	v_mfma_f32_16x16x32_bf16 v[20:23], v[164:167], v[224:227], v[20:23]
	v_mfma_f32_16x16x32_bf16 v[12:15], v[190:193], v[224:227], v[12:15]
	v_mfma_f32_16x16x32_bf16 v[4:7], v[164:167], v[232:235], v[4:7]
	v_mfma_f32_16x16x32_bf16 v[0:3], v[190:193], v[232:235], v[0:3]
	s_barrier
	s_add_i32 s57, s57, 2
	s_add_u32 s52, s52, 0x100
	s_addc_u32 s53, s53, 0
	s_add_u32 s51, s51, 0x100
	s_addc_u32 s56, s56, 0
	s_cmp_gt_u32 s57, 29
	s_cbranch_scc0 .LBB0_1444
	s_and_b64 vcc, exec, s[36:37]
	s_cbranch_vccz .LBB0_1447
	s_barrier

;     __device__ __forceinline__ void a_ready(const Unit& u) const { wait_panel(cnt, u.pm, need, tmo, wave); }
;     __device__ __forceinline__ void a_ready(const Unit& u) const { wait_panel(cnt, u.pm, need, tmo, wave); }
; #define PG8_STAGE(bufoff, gbase, voff) do { _Pragma("unroll") for (int _i = 0; _i < 2; ++_i) \
;         __builtin_amdgcn_global_load_lds((const unsigned*)((const char*)(gbase) + (voff)[_i]), (PG8_LAS unsigned*)(lds + (bufoff) + ldsw + _i * 8192), 16, 0, 0); } while (0)
; #define PG8_LDA(dst, b, h) do { _Pragma("unroll") for (int m = 0; m < 4; ++m) _Pragma("unroll") for (int k = 0; k < 2; ++k) dst[m][k] = *(const PG8_LAS bf16x8*)(lds + PG8_SA(b, h) + aoff + m * 2048 + k * 1024); } while (0)
; #define PG8_LDB(dst, b, h) do { _Pragma("unroll") for (int n = 0; n < 2; ++n) _Pragma("unroll") for (int k = 0; k < 2; ++k) dst[n][k] = *(const PG8_LAS bf16x8*)(lds + PG8_SB(b, h) + boff + n * 2048 + k * 1024); } while (0)
; #define PG8_WAIT_V(n) asm volatile("s_waitcnt vmcnt(" #n ")" ::: "memory")
; #define PG8_WAIT_L(n) asm volatile("s_waitcnt lgkmcnt(" #n ")" ::: "memory")
; #define PG8_BAR __builtin_amdgcn_s_barrier()
; #define PG8_SCHED __builtin_amdgcn_sched_barrier(0)
; template <class Epi, class Sched, bool ALIGN_EPI = false, bool SP2 = false>
; __device__ __forceinline__ void gemm_phase(PG8_LAS unsigned char* lds, const Gemm g, const Sched& S, const Epi& E, const int tid_in) {
;     ...
;         for (int t = 0; t < nt; t += 2) {
;             const bool last = (t == nt - 2);
;             const char* a1 = cA + (size_t)(t + 1) * kstep;
;             const char* a2 = last ? nA : cA + (size_t)(t + 2) * kstep; const char* b2 = last ? nB : cB + (size_t)(t + 2) * kstep;
;             const char* a3 = a2 + kstep; const char* b3 = b2 + kstep;
;             if (last && has_next) S.a_ready(nxt);
;             if constexpr (SP2) {
;             PG8_LDB(B0, 0, 0); PG8_LDB(B1, 0, 1); PG8_SCHED; PG8_LDA(At, 0, 0); PG8_STAGE(PG8_SA(1, 1), a1 + hstepA, voffA);
;             PG8_WAIT_V(8); PG8_WAIT_L(0); PG8_BAR; PG8_MMA(0, 0, At, B0); PG8_MMA(0, 1, At, B1); PG8_BAR; PG8_SCHED;
;             PG8_LDA(At, 0, 1); PG8_STAGE(PG8_SB(0, 0), b2, voffB); PG8_STAGE(PG8_SB(0, 1), b2 + hstepB, voffB); PG8_STAGE(PG8_SA(0, 0), a2, voffA);
;             PG8_WAIT_V(8); PG8_WAIT_L(0); PG8_BAR; PG8_MMA(1, 0, At, B0); PG8_MMA(1, 1, At, B1); PG8_BAR; PG8_SCHED;
.LBB0_1960:
	s_add_u32 s22, s58, 0xfffc0080
	s_addc_u32 s23, s59, -1
	s_add_i32 s62, 0, 0x10000
	s_cmp_eq_u32 s53, 12
	s_cselect_b32 s61, s11, s23
	s_cselect_b32 s60, s12, s22
	s_cselect_b32 s23, s33, s51
	s_cselect_b32 s22, s34, s35
	s_add_i32 s64, 0, 0x14000
	ds_read_b128 v[32:35], v249
	ds_read_b128 v[36:39], v249 offset:1024
	ds_read_b128 v[48:51], v249 offset:2048
	ds_read_b128 v[52:55], v249 offset:3072
	ds_read_b128 v[104:107], v249 offset:16384
	ds_read_b128 v[116:119], v249 offset:17408
	ds_read_b128 v[128:131], v249 offset:18432
	ds_read_b128 v[140:143], v249 offset:19456
	s_add_i32 m0, s17, 0xc000
	ds_read_b128 v[144:147], v225
	ds_read_b128 v[156:159], v225 offset:1024
	ds_read_b128 v[160:163], v225 offset:2048
	ds_read_b128 v[200:203], v225 offset:3072
	ds_read_b128 v[204:207], v225 offset:4096
	ds_read_b128 v[208:211], v225 offset:5120
	ds_read_b128 v[226:229], v225 offset:6144
	ds_read_b128 v[230:233], v225 offset:7168
	global_load_lds_dwordx4 v196, s[58:59]
	s_add_i32 m0, s17, 0xe000
	s_nop 0
	global_load_lds_dwordx4 v198, s[58:59]
	s_waitcnt vmcnt(8) lgkmcnt(0)
	s_barrier
	v_mfma_f32_16x16x32_bf16 v[168:171], v[32:35], v[144:147], v[168:171]
	v_mfma_f32_16x16x32_bf16 v[164:167], v[48:51], v[144:147], v[164:167]
	v_mfma_f32_16x16x32_bf16 v[136:139], v[32:35], v[160:163], v[136:139]
	v_mfma_f32_16x16x32_bf16 v[132:135], v[48:51], v[160:163], v[132:135]
	v_mfma_f32_16x16x32_bf16 v[112:115], v[32:35], v[204:207], v[112:115]
	v_mfma_f32_16x16x32_bf16 v[108:111], v[48:51], v[204:207], v[108:111]
	v_mfma_f32_16x16x32_bf16 v[92:95], v[32:35], v[226:229], v[92:95]
	v_mfma_f32_16x16x32_bf16 v[88:91], v[48:51], v[226:229], v[88:91]
	v_mfma_f32_16x16x32_bf16 v[168:171], v[36:39], v[156:159], v[168:171]
	v_mfma_f32_16x16x32_bf16 v[164:167], v[52:55], v[156:159], v[164:167]
	v_mfma_f32_16x16x32_bf16 v[136:139], v[36:39], v[200:203], v[136:139]
	v_mfma_f32_16x16x32_bf16 v[132:135], v[52:55], v[200:203], v[132:135]
	v_mfma_f32_16x16x32_bf16 v[112:115], v[36:39], v[208:211], v[112:115]
	v_mfma_f32_16x16x32_bf16 v[108:111], v[52:55], v[208:211], v[108:111]
	v_mfma_f32_16x16x32_bf16 v[92:95], v[36:39], v[230:233], v[92:95]
	v_mfma_f32_16x16x32_bf16 v[88:91], v[52:55], v[230:233], v[88:91]
	v_mfma_f32_16x16x32_bf16 v[152:155], v[104:107], v[144:147], v[152:155]
	v_mfma_f32_16x16x32_bf16 v[124:127], v[104:107], v[160:163], v[124:127]
	v_mfma_f32_16x16x32_bf16 v[120:123], v[128:131], v[160:163], v[120:123]
	v_mfma_f32_16x16x32_bf16 v[100:103], v[104:107], v[204:207], v[100:103]
	v_mfma_f32_16x16x32_bf16 v[96:99], v[128:131], v[204:207], v[96:99]
	v_mfma_f32_16x16x32_bf16 v[84:87], v[104:107], v[226:229], v[84:87]
	v_mfma_f32_16x16x32_bf16 v[80:83], v[128:131], v[226:229], v[80:83]
	v_mfma_f32_16x16x32_bf16 v[152:155], v[116:119], v[156:159], v[152:155]
	v_mfma_f32_16x16x32_bf16 v[144:147], v[128:131], v[144:147], v[148:151]
	v_mfma_f32_16x16x32_bf16 v[124:127], v[116:119], v[200:203], v[124:127]
	v_mfma_f32_16x16x32_bf16 v[120:123], v[140:143], v[200:203], v[120:123]
	v_mfma_f32_16x16x32_bf16 v[100:103], v[116:119], v[208:211], v[100:103]
	v_mfma_f32_16x16x32_bf16 v[96:99], v[140:143], v[208:211], v[96:99]
	v_mfma_f32_16x16x32_bf16 v[84:87], v[116:119], v[230:233], v[84:87]
	v_mfma_f32_16x16x32_bf16 v[80:83], v[140:143], v[230:233], v[80:83]
	v_mfma_f32_16x16x32_bf16 v[144:147], v[140:143], v[156:159], v[144:147]
	s_barrier
	s_add_i32 s62, s62, s16
	s_mov_b32 m0, s62
	ds_read_b128 v[148:151], v225 offset:16384
	ds_read_b128 v[156:159], v225 offset:17408
	ds_read_b128 v[160:163], v225 offset:18432
	ds_read_b128 v[200:203], v225 offset:19456
	ds_read_b128 v[204:207], v225 offset:20480
	ds_read_b128 v[208:211], v225 offset:21504
	ds_read_b128 v[226:229], v225 offset:22528
	ds_read_b128 v[230:233], v225 offset:23552
	global_load_lds_dwordx4 v172, s[22:23]
	s_add_i32 m0, s62, 0x2000
	s_add_u32 s62, s22, 0x40000
	s_addc_u32 s63, s23, 0
	s_add_i32 s64, s64, s16
	global_load_lds_dwordx4 v194, s[22:23]
	s_mov_b32 m0, s64
	s_nop 0
	global_load_lds_dwordx4 v172, s[62:63]
	s_add_i32 m0, s64, 0x2000
	s_nop 0
	global_load_lds_dwordx4 v194, s[62:63]
	s_add_u32 vcc_lo, s60, 0x80
	s_addc_u32 vcc_hi, s61, 0
	s_mov_b32 m0, s17
	s_nop 0
	global_load_lds_dwordx4 v190, s[60:61]
	s_mov_b32 m0, s18
	s_nop 0
	global_load_lds_dwordx4 v192, s[60:61]
	s_waitcnt vmcnt(8) lgkmcnt(0)
	s_barrier
	v_mfma_f32_16x16x32_bf16 v[76:79], v[32:35], v[148:151], v[76:79]
	v_mfma_f32_16x16x32_bf16 v[72:75], v[48:51], v[148:151], v[72:75]
	v_mfma_f32_16x16x32_bf16 v[60:63], v[32:35], v[160:163], v[60:63]
	v_mfma_f32_16x16x32_bf16 v[56:59], v[48:51], v[160:163], v[56:59]
	v_mfma_f32_16x16x32_bf16 v[28:31], v[32:35], v[204:207], v[28:31]
	v_mfma_f32_16x16x32_bf16 v[24:27], v[48:51], v[204:207], v[24:27]
	v_mfma_f32_16x16x32_bf16 v[12:15], v[32:35], v[226:229], v[12:15]
	v_mfma_f32_16x16x32_bf16 v[8:11], v[48:51], v[226:229], v[8:11]
	v_mfma_f32_16x16x32_bf16 v[76:79], v[36:39], v[156:159], v[76:79]
	v_mfma_f32_16x16x32_bf16 v[72:75], v[52:55], v[156:159], v[72:75]
	v_mfma_f32_16x16x32_bf16 v[60:63], v[36:39], v[200:203], v[60:63]
	v_mfma_f32_16x16x32_bf16 v[56:59], v[52:55], v[200:203], v[56:59]
	v_mfma_f32_16x16x32_bf16 v[28:31], v[36:39], v[208:211], v[28:31]
	v_mfma_f32_16x16x32_bf16 v[24:27], v[52:55], v[208:211], v[24:27]
	v_mfma_f32_16x16x32_bf16 v[12:15], v[36:39], v[230:233], v[12:15]
	v_mfma_f32_16x16x32_bf16 v[8:11], v[52:55], v[230:233], v[8:11]
	v_mfma_f32_16x16x32_bf16 v[44:47], v[104:107], v[160:163], v[44:47]
	v_mfma_f32_16x16x32_bf16 v[40:43], v[128:131], v[160:163], v[40:43]
	v_mfma_f32_16x16x32_bf16 v[20:23], v[104:107], v[204:207], v[20:23]
	v_mfma_f32_16x16x32_bf16 v[16:19], v[128:131], v[204:207], v[16:19]
	v_mfma_f32_16x16x32_bf16 v[4:7], v[104:107], v[226:229], v[4:7]
	v_mfma_f32_16x16x32_bf16 v[0:3], v[128:131], v[226:229], v[0:3]
	v_mfma_f32_16x16x32_bf16 v[32:35], v[104:107], v[148:151], v[68:71]
	v_mfma_f32_16x16x32_bf16 v[36:39], v[128:131], v[148:151], v[64:67]
	v_mfma_f32_16x16x32_bf16 v[44:47], v[116:119], v[200:203], v[44:47]
	v_mfma_f32_16x16x32_bf16 v[40:43], v[140:143], v[200:203], v[40:43]
	v_mfma_f32_16x16x32_bf16 v[20:23], v[116:119], v[208:211], v[20:23]
	v_mfma_f32_16x16x32_bf16 v[16:19], v[140:143], v[208:211], v[16:19]
	v_mfma_f32_16x16x32_bf16 v[4:7], v[116:119], v[230:233], v[4:7]
	v_mfma_f32_16x16x32_bf16 v[0:3], v[140:143], v[230:233], v[0:3]
	v_mfma_f32_16x16x32_bf16 v[32:35], v[116:119], v[156:159], v[32:35]
	v_mfma_f32_16x16x32_bf16 v[36:39], v[140:143], v[156:159], v[36:39]
	s_barrier
; #define PG8_STAGE(bufoff, gbase, voff) do { _Pragma("unroll") for (int _i = 0; _i < 2; ++_i) \
;         __builtin_amdgcn_global_load_lds((const unsigned*)((const char*)(gbase) + (voff)[_i]), (PG8_LAS unsigned*)(lds + (bufoff) + ldsw + _i * 8192), 16, 0, 0); } while (0)
; #define PG8_LDA(dst, b, h) do { _Pragma("unroll") for (int m = 0; m < 4; ++m) _Pragma("unroll") for (int k = 0; k < 2; ++k) dst[m][k] = *(const PG8_LAS bf16x8*)(lds + PG8_SA(b, h) + aoff + m * 2048 + k * 1024); } while (0)
; #define PG8_LDB(dst, b, h) do { _Pragma("unroll") for (int n = 0; n < 2; ++n) _Pragma("unroll") for (int k = 0; k < 2; ++k) dst[n][k] = *(const PG8_LAS bf16x8*)(lds + PG8_SB(b, h) + boff + n * 2048 + k * 1024); } while (0)
; #define PG8_MMA(ai, bj, At, Bt) do { __builtin_amdgcn_s_setprio(1); _Pragma("unroll") for (int m = 0; m < 4; ++m) _Pragma("unroll") for (int n = 0; n < 2; ++n) _Pragma("unroll") for (int k = 0; k < 2; ++k) \
;         acc[ai][bj][m][n] = __builtin_amdgcn_mfma_f32_16x16x32_bf16(Bt[n][k], At[m][k], acc[ai][bj][m][n], 0, 0, 0); __builtin_amdgcn_s_setprio(0); } while (0)
; #define PG8_WAIT_V(n) asm volatile("s_waitcnt vmcnt(" #n ")" ::: "memory")
; #define PG8_WAIT_L(n) asm volatile("s_waitcnt lgkmcnt(" #n ")" ::: "memory")
; #define PG8_BAR __builtin_amdgcn_s_barrier()
; #define PG8_SCHED __builtin_amdgcn_sched_barrier(0)
; template <class Epi, class Sched, bool ALIGN_EPI = false, bool SP2 = false>
; __device__ __forceinline__ void gemm_phase(PG8_LAS unsigned char* lds, const Gemm g, const Sched& S, const Epi& E, const int tid_in) {
;     ...
;             PG8_LDB(B0, 1, 0); PG8_LDB(B1, 1, 1); PG8_SCHED; PG8_LDA(At, 1, 0); PG8_STAGE(PG8_SA(0, 1), a2 + hstepA, voffA);
;             PG8_WAIT_V(8); PG8_WAIT_L(0); PG8_BAR; PG8_MMA(0, 0, At, B0); PG8_MMA(0, 1, At, B1); PG8_BAR; PG8_SCHED;
;             PG8_LDA(At, 1, 1); PG8_STAGE(PG8_SB(1, 0), b3, voffB); PG8_STAGE(PG8_SB(1, 1), b3 + hstepB, voffB); PG8_STAGE(PG8_SA(1, 0), a3, voffA);
;             PG8_WAIT_V(8); PG8_WAIT_L(0); PG8_BAR; PG8_MMA(1, 0, At, B0); PG8_MMA(1, 1, At, B1); PG8_BAR; PG8_SCHED;
;     ...
;         if constexpr (ALIGN_EPI) { if (wr == 0) PG8_BAR; }
	s_add_i32 s62, 0, 0x18000
	s_add_i32 s63, 0, 0x1c000
	ds_read_b128 v[48:51], v249 offset:32768
	ds_read_b128 v[52:55], v249 offset:33792
	ds_read_b128 v[64:67], v249 offset:34816
	ds_read_b128 v[68:71], v249 offset:35840
	ds_read_b128 v[104:107], v249 offset:49152
	ds_read_b128 v[116:119], v249 offset:50176
	ds_read_b128 v[128:131], v249 offset:51200
	ds_read_b128 v[140:143], v249 offset:52224
	s_add_u32 s60, s60, 0x40000
	s_addc_u32 s61, s61, 0
	s_mov_b32 m0, s19
	ds_read_b128 v[148:151], v225 offset:32768
	ds_read_b128 v[156:159], v225 offset:33792
	ds_read_b128 v[160:163], v225 offset:34816
	ds_read_b128 v[200:203], v225 offset:35840
	ds_read_b128 v[204:207], v225 offset:36864
	ds_read_b128 v[208:211], v225 offset:37888
	ds_read_b128 v[226:229], v225 offset:38912
	ds_read_b128 v[230:233], v225 offset:39936
	global_load_lds_dwordx4 v190, s[60:61]
	s_mov_b32 m0, s20
	s_nop 0
	global_load_lds_dwordx4 v192, s[60:61]
	s_waitcnt vmcnt(8) lgkmcnt(0)
	s_barrier
	v_mfma_f32_16x16x32_bf16 v[168:171], v[48:51], v[148:151], v[168:171]
	v_mfma_f32_16x16x32_bf16 v[164:167], v[64:67], v[148:151], v[164:167]
	v_mfma_f32_16x16x32_bf16 v[136:139], v[48:51], v[160:163], v[136:139]
	v_mfma_f32_16x16x32_bf16 v[132:135], v[64:67], v[160:163], v[132:135]
	v_mfma_f32_16x16x32_bf16 v[112:115], v[48:51], v[204:207], v[112:115]
	v_mfma_f32_16x16x32_bf16 v[108:111], v[64:67], v[204:207], v[108:111]
	v_mfma_f32_16x16x32_bf16 v[92:95], v[48:51], v[226:229], v[92:95]
	v_mfma_f32_16x16x32_bf16 v[88:91], v[64:67], v[226:229], v[88:91]
	v_mfma_f32_16x16x32_bf16 v[168:171], v[52:55], v[156:159], v[168:171]
	v_mfma_f32_16x16x32_bf16 v[164:167], v[68:71], v[156:159], v[164:167]
	v_mfma_f32_16x16x32_bf16 v[136:139], v[52:55], v[200:203], v[136:139]
	v_mfma_f32_16x16x32_bf16 v[132:135], v[68:71], v[200:203], v[132:135]
	v_mfma_f32_16x16x32_bf16 v[112:115], v[52:55], v[208:211], v[112:115]
	v_mfma_f32_16x16x32_bf16 v[108:111], v[68:71], v[208:211], v[108:111]
	v_mfma_f32_16x16x32_bf16 v[92:95], v[52:55], v[230:233], v[92:95]
	v_mfma_f32_16x16x32_bf16 v[88:91], v[68:71], v[230:233], v[88:91]
	v_mfma_f32_16x16x32_bf16 v[152:155], v[104:107], v[148:151], v[152:155]
	v_mfma_f32_16x16x32_bf16 v[144:147], v[128:131], v[148:151], v[144:147]
	v_mfma_f32_16x16x32_bf16 v[124:127], v[104:107], v[160:163], v[124:127]
	v_mfma_f32_16x16x32_bf16 v[120:123], v[128:131], v[160:163], v[120:123]
	v_mfma_f32_16x16x32_bf16 v[100:103], v[104:107], v[204:207], v[100:103]
	v_mfma_f32_16x16x32_bf16 v[96:99], v[128:131], v[204:207], v[96:99]
	v_mfma_f32_16x16x32_bf16 v[84:87], v[104:107], v[226:229], v[84:87]
	v_mfma_f32_16x16x32_bf16 v[80:83], v[128:131], v[226:229], v[80:83]
	v_mfma_f32_16x16x32_bf16 v[152:155], v[116:119], v[156:159], v[152:155]
	v_mfma_f32_16x16x32_bf16 v[148:151], v[140:143], v[156:159], v[144:147]
	v_mfma_f32_16x16x32_bf16 v[124:127], v[116:119], v[200:203], v[124:127]
	v_mfma_f32_16x16x32_bf16 v[120:123], v[140:143], v[200:203], v[120:123]
	v_mfma_f32_16x16x32_bf16 v[100:103], v[116:119], v[208:211], v[100:103]
	v_mfma_f32_16x16x32_bf16 v[96:99], v[140:143], v[208:211], v[96:99]
	v_mfma_f32_16x16x32_bf16 v[84:87], v[116:119], v[230:233], v[84:87]
	v_mfma_f32_16x16x32_bf16 v[80:83], v[140:143], v[230:233], v[80:83]
	s_barrier
	s_add_i32 s60, s62, s16
	s_mov_b32 m0, s60
	ds_read_b128 v[144:147], v225 offset:49152
	ds_read_b128 v[156:159], v225 offset:50176
	ds_read_b128 v[160:163], v225 offset:51200
	ds_read_b128 v[200:203], v225 offset:52224
	ds_read_b128 v[204:207], v225 offset:53248
	ds_read_b128 v[208:211], v225 offset:54272
	ds_read_b128 v[226:229], v225 offset:55296
	ds_read_b128 v[230:233], v225 offset:56320
	s_add_u32 s100, s22, 0x80
	s_addc_u32 s101, s23, 0
	global_load_lds_dwordx4 v172, s[100:101]
	s_add_i32 m0, s60, 0x2000
	s_add_u32 s22, s22, 0x40080
	s_addc_u32 s23, s23, 0
	s_add_i32 s60, s63, s16
	global_load_lds_dwordx4 v194, s[100:101]
	s_mov_b32 m0, s60
	s_nop 0
	global_load_lds_dwordx4 v172, s[22:23]
	s_add_i32 m0, s60, 0x2000
	s_nop 0
	global_load_lds_dwordx4 v194, s[22:23]
	s_mov_b32 m0, s30
	s_nop 0
	global_load_lds_dwordx4 v190, vcc
	s_mov_b32 m0, s31
	s_nop 0
	global_load_lds_dwordx4 v192, vcc
	s_waitcnt vmcnt(8) lgkmcnt(0)
	s_barrier
	v_mfma_f32_16x16x32_bf16 v[76:79], v[48:51], v[144:147], v[76:79]
	v_mfma_f32_16x16x32_bf16 v[72:75], v[64:67], v[144:147], v[72:75]
	v_mfma_f32_16x16x32_bf16 v[60:63], v[48:51], v[160:163], v[60:63]
	v_mfma_f32_16x16x32_bf16 v[56:59], v[64:67], v[160:163], v[56:59]
	v_mfma_f32_16x16x32_bf16 v[28:31], v[48:51], v[204:207], v[28:31]
	v_mfma_f32_16x16x32_bf16 v[24:27], v[64:67], v[204:207], v[24:27]
	v_mfma_f32_16x16x32_bf16 v[12:15], v[48:51], v[226:229], v[12:15]
	v_mfma_f32_16x16x32_bf16 v[8:11], v[64:67], v[226:229], v[8:11]
	v_mfma_f32_16x16x32_bf16 v[76:79], v[52:55], v[156:159], v[76:79]
	v_mfma_f32_16x16x32_bf16 v[72:75], v[68:71], v[156:159], v[72:75]
	v_mfma_f32_16x16x32_bf16 v[60:63], v[52:55], v[200:203], v[60:63]
	v_mfma_f32_16x16x32_bf16 v[56:59], v[68:71], v[200:203], v[56:59]
	v_mfma_f32_16x16x32_bf16 v[28:31], v[52:55], v[208:211], v[28:31]
	v_mfma_f32_16x16x32_bf16 v[24:27], v[68:71], v[208:211], v[24:27]
	v_mfma_f32_16x16x32_bf16 v[12:15], v[52:55], v[230:233], v[12:15]
	v_mfma_f32_16x16x32_bf16 v[8:11], v[68:71], v[230:233], v[8:11]
	v_mfma_f32_16x16x32_bf16 v[32:35], v[104:107], v[144:147], v[32:35]
	v_mfma_f32_16x16x32_bf16 v[68:71], v[116:119], v[156:159], v[32:35]
	v_mfma_f32_16x16x32_bf16 v[32:35], v[128:131], v[144:147], v[36:39]
	v_mfma_f32_16x16x32_bf16 v[64:67], v[140:143], v[156:159], v[32:35]
	v_mfma_f32_16x16x32_bf16 v[32:35], v[104:107], v[160:163], v[44:47]
	v_mfma_f32_16x16x32_bf16 v[44:47], v[116:119], v[200:203], v[32:35]
	v_mfma_f32_16x16x32_bf16 v[32:35], v[128:131], v[160:163], v[40:43]
	v_mfma_f32_16x16x32_bf16 v[20:23], v[104:107], v[204:207], v[20:23]
	v_mfma_f32_16x16x32_bf16 v[16:19], v[128:131], v[204:207], v[16:19]
	v_mfma_f32_16x16x32_bf16 v[4:7], v[104:107], v[226:229], v[4:7]
	v_mfma_f32_16x16x32_bf16 v[0:3], v[128:131], v[226:229], v[0:3]
	v_mfma_f32_16x16x32_bf16 v[40:43], v[140:143], v[200:203], v[32:35]
	v_mfma_f32_16x16x32_bf16 v[20:23], v[116:119], v[208:211], v[20:23]
	v_mfma_f32_16x16x32_bf16 v[16:19], v[140:143], v[208:211], v[16:19]
	v_mfma_f32_16x16x32_bf16 v[4:7], v[116:119], v[230:233], v[4:7]
	v_mfma_f32_16x16x32_bf16 v[0:3], v[140:143], v[230:233], v[0:3]
	s_barrier
	s_add_i32 s53, s53, 2
	s_add_u32 s58, s58, 0x100
	s_addc_u32 s59, s59, 0
	s_add_u32 s35, s35, 0x100
	s_addc_u32 s51, s51, 0
	s_cmp_gt_u32 s53, 13
	s_cbranch_scc0 .LBB0_1960
	s_and_b64 vcc, exec, s[48:49]
	s_cbranch_vccz .LBB0_1963
	s_barrier

;     __device__ __forceinline__ void a_ready(const Unit& u) const { wait_panel(cnt, u.pm, need, tmo, wave); }
;     __device__ __forceinline__ void a_ready(const Unit& u) const { wait_panel(cnt, u.pm, need, tmo, wave); }
; #define PG8_STAGE(bufoff, gbase, voff) do { _Pragma("unroll") for (int _i = 0; _i < 2; ++_i) \
;         __builtin_amdgcn_global_load_lds((const unsigned*)((const char*)(gbase) + (voff)[_i]), (PG8_LAS unsigned*)(lds + (bufoff) + ldsw + _i * 8192), 16, 0, 0); } while (0)
; #define PG8_LDA(dst, b, h) do { _Pragma("unroll") for (int m = 0; m < 4; ++m) _Pragma("unroll") for (int k = 0; k < 2; ++k) dst[m][k] = *(const PG8_LAS bf16x8*)(lds + PG8_SA(b, h) + aoff + m * 2048 + k * 1024); } while (0)
; #define PG8_LDB(dst, b, h) do { _Pragma("unroll") for (int n = 0; n < 2; ++n) _Pragma("unroll") for (int k = 0; k < 2; ++k) dst[n][k] = *(const PG8_LAS bf16x8*)(lds + PG8_SB(b, h) + boff + n * 2048 + k * 1024); } while (0)
; #define PG8_WAIT_V(n) asm volatile("s_waitcnt vmcnt(" #n ")" ::: "memory")
; #define PG8_WAIT_L(n) asm volatile("s_waitcnt lgkmcnt(" #n ")" ::: "memory")
; #define PG8_BAR __builtin_amdgcn_s_barrier()
; #define PG8_SCHED __builtin_amdgcn_sched_barrier(0)
; template <class Epi, class Sched, bool ALIGN_EPI = false, bool SP2 = false>
; __device__ __forceinline__ void gemm_phase(PG8_LAS unsigned char* lds, const Gemm g, const Sched& S, const Epi& E, const int tid_in) {
;     ...
;         for (int t = 0; t < nt; t += 2) {
;             const bool last = (t == nt - 2);
;             const char* a1 = cA + (size_t)(t + 1) * kstep;
;             const char* a2 = last ? nA : cA + (size_t)(t + 2) * kstep; const char* b2 = last ? nB : cB + (size_t)(t + 2) * kstep;
;             const char* a3 = a2 + kstep; const char* b3 = b2 + kstep;
;             if (last && has_next) S.a_ready(nxt);
;             if constexpr (SP2) {
;             PG8_LDB(B0, 0, 0); PG8_LDB(B1, 0, 1); PG8_SCHED; PG8_LDA(At, 0, 0); PG8_STAGE(PG8_SA(1, 1), a1 + hstepA, voffA);
;             PG8_WAIT_V(8); PG8_WAIT_L(0); PG8_BAR; PG8_MMA(0, 0, At, B0); PG8_MMA(0, 1, At, B1); PG8_BAR; PG8_SCHED;
;             PG8_LDA(At, 0, 1); PG8_STAGE(PG8_SB(0, 0), b2, voffB); PG8_STAGE(PG8_SB(0, 1), b2 + hstepB, voffB); PG8_STAGE(PG8_SA(0, 0), a2, voffA);
;             PG8_WAIT_V(8); PG8_WAIT_L(0); PG8_BAR; PG8_MMA(1, 0, At, B0); PG8_MMA(1, 1, At, B1); PG8_BAR; PG8_SCHED;
.LBB0_2041:
	s_add_u32 s22, s58, 0xfff80080
	s_addc_u32 s23, s59, -1
	s_add_i32 s65, 0, 0x10000
	s_cmp_eq_u32 s64, 28
	s_cselect_b32 s61, s38, s23
	s_cselect_b32 s60, s51, s22
	s_cselect_b32 s23, s49, s63
	s_cselect_b32 s22, s57, s62
	s_add_i32 s68, 0, 0x14000
	ds_read_b128 v[104:107], v249
	ds_read_b128 v[108:111], v249 offset:1024
	ds_read_b128 v[112:115], v249 offset:2048
	ds_read_b128 v[116:119], v249 offset:3072
	ds_read_b128 v[144:147], v249 offset:16384
	ds_read_b128 v[148:151], v249 offset:17408
	ds_read_b128 v[152:155], v249 offset:18432
	ds_read_b128 v[156:159], v249 offset:19456
	s_add_i32 m0, s28, 0xc000
	ds_read_b128 v[160:163], v204
	ds_read_b128 v[192:195], v204 offset:1024
	ds_read_b128 v[196:199], v204 offset:2048
	ds_read_b128 v[206:209], v204 offset:3072
	ds_read_b128 v[210:213], v204 offset:4096
	ds_read_b128 v[224:227], v204 offset:5120
	ds_read_b128 v[228:231], v204 offset:6144
	ds_read_b128 v[232:235], v204 offset:7168
	global_load_lds_dwordx4 v170, s[58:59]
	s_add_i32 m0, s28, 0xe000
	s_nop 0
	global_load_lds_dwordx4 v190, s[58:59]
	s_waitcnt vmcnt(8) lgkmcnt(0)
	s_barrier
	v_mfma_f32_16x16x32_bf16 v[140:143], v[104:107], v[160:163], v[140:143]
	v_mfma_f32_16x16x32_bf16 v[136:139], v[112:115], v[160:163], v[136:139]
	v_mfma_f32_16x16x32_bf16 v[124:127], v[104:107], v[196:199], v[124:127]
	v_mfma_f32_16x16x32_bf16 v[120:123], v[112:115], v[196:199], v[120:123]
	v_mfma_f32_16x16x32_bf16 v[92:95], v[104:107], v[210:213], v[92:95]
	v_mfma_f32_16x16x32_bf16 v[88:91], v[112:115], v[210:213], v[88:91]
	v_mfma_f32_16x16x32_bf16 v[76:79], v[104:107], v[228:231], v[76:79]
	v_mfma_f32_16x16x32_bf16 v[72:75], v[112:115], v[228:231], v[72:75]
	v_mfma_f32_16x16x32_bf16 v[140:143], v[108:111], v[192:195], v[140:143]
	v_mfma_f32_16x16x32_bf16 v[136:139], v[116:119], v[192:195], v[136:139]
	v_mfma_f32_16x16x32_bf16 v[124:127], v[108:111], v[206:209], v[124:127]
	v_mfma_f32_16x16x32_bf16 v[120:123], v[116:119], v[206:209], v[120:123]
	v_mfma_f32_16x16x32_bf16 v[92:95], v[108:111], v[224:227], v[92:95]
	v_mfma_f32_16x16x32_bf16 v[88:91], v[116:119], v[224:227], v[88:91]
	v_mfma_f32_16x16x32_bf16 v[76:79], v[108:111], v[232:235], v[76:79]
	v_mfma_f32_16x16x32_bf16 v[72:75], v[116:119], v[232:235], v[72:75]
	v_mfma_f32_16x16x32_bf16 v[132:135], v[144:147], v[160:163], v[132:135]
	v_mfma_f32_16x16x32_bf16 v[128:131], v[152:155], v[160:163], v[128:131]
	v_mfma_f32_16x16x32_bf16 v[100:103], v[144:147], v[196:199], v[100:103]
	v_mfma_f32_16x16x32_bf16 v[96:99], v[152:155], v[196:199], v[96:99]
	v_mfma_f32_16x16x32_bf16 v[84:87], v[144:147], v[210:213], v[84:87]
	v_mfma_f32_16x16x32_bf16 v[80:83], v[152:155], v[210:213], v[80:83]
	v_mfma_f32_16x16x32_bf16 v[68:71], v[144:147], v[228:231], v[68:71]
	v_mfma_f32_16x16x32_bf16 v[64:67], v[152:155], v[228:231], v[64:67]
	v_mfma_f32_16x16x32_bf16 v[132:135], v[148:151], v[192:195], v[132:135]
	v_mfma_f32_16x16x32_bf16 v[128:131], v[156:159], v[192:195], v[128:131]
	v_mfma_f32_16x16x32_bf16 v[100:103], v[148:151], v[206:209], v[100:103]
	v_mfma_f32_16x16x32_bf16 v[96:99], v[156:159], v[206:209], v[96:99]
	v_mfma_f32_16x16x32_bf16 v[84:87], v[148:151], v[224:227], v[84:87]
	v_mfma_f32_16x16x32_bf16 v[80:83], v[156:159], v[224:227], v[80:83]
	v_mfma_f32_16x16x32_bf16 v[68:71], v[148:151], v[232:235], v[68:71]
	v_mfma_f32_16x16x32_bf16 v[64:67], v[156:159], v[232:235], v[64:67]
	s_barrier
	s_add_i32 s65, s65, s21
	s_mov_b32 m0, s65
	ds_read_b128 v[160:163], v204 offset:16384
	ds_read_b128 v[192:195], v204 offset:17408
	ds_read_b128 v[196:199], v204 offset:18432
	ds_read_b128 v[206:209], v204 offset:19456
	ds_read_b128 v[210:213], v204 offset:20480
	ds_read_b128 v[224:227], v204 offset:21504
	ds_read_b128 v[228:231], v204 offset:22528
	ds_read_b128 v[232:235], v204 offset:23552
	global_load_lds_dwordx4 v172, s[22:23]
	s_add_i32 m0, s65, 0x2000
	s_add_u32 s66, s22, 0x80000
	s_addc_u32 s67, s23, 0
	s_add_i32 s65, s68, s21
	global_load_lds_dwordx4 v168, s[22:23]
	s_mov_b32 m0, s65
	s_nop 0
	global_load_lds_dwordx4 v172, s[66:67]
	s_add_i32 m0, s65, 0x2000
	s_nop 0
	global_load_lds_dwordx4 v168, s[66:67]
	s_add_u32 vcc_lo, s60, 0x80
	s_addc_u32 vcc_hi, s61, 0
	s_mov_b32 m0, s28
	s_nop 0
	global_load_lds_dwordx4 v164, s[60:61]
	s_mov_b32 m0, s29
	s_nop 0
	global_load_lds_dwordx4 v166, s[60:61]
	s_waitcnt vmcnt(8) lgkmcnt(0)
	s_barrier
	v_mfma_f32_16x16x32_bf16 v[60:63], v[104:107], v[160:163], v[60:63]
	v_mfma_f32_16x16x32_bf16 v[56:59], v[112:115], v[160:163], v[56:59]
	v_mfma_f32_16x16x32_bf16 v[44:47], v[104:107], v[196:199], v[44:47]
	v_mfma_f32_16x16x32_bf16 v[40:43], v[112:115], v[196:199], v[40:43]
	v_mfma_f32_16x16x32_bf16 v[28:31], v[104:107], v[210:213], v[28:31]
	v_mfma_f32_16x16x32_bf16 v[24:27], v[112:115], v[210:213], v[24:27]
	v_mfma_f32_16x16x32_bf16 v[12:15], v[104:107], v[228:231], v[12:15]
	v_mfma_f32_16x16x32_bf16 v[8:11], v[112:115], v[228:231], v[8:11]
	v_mfma_f32_16x16x32_bf16 v[60:63], v[108:111], v[192:195], v[60:63]
	v_mfma_f32_16x16x32_bf16 v[56:59], v[116:119], v[192:195], v[56:59]
	v_mfma_f32_16x16x32_bf16 v[44:47], v[108:111], v[206:209], v[44:47]
	v_mfma_f32_16x16x32_bf16 v[40:43], v[116:119], v[206:209], v[40:43]
	v_mfma_f32_16x16x32_bf16 v[28:31], v[108:111], v[224:227], v[28:31]
	v_mfma_f32_16x16x32_bf16 v[24:27], v[116:119], v[224:227], v[24:27]
	v_mfma_f32_16x16x32_bf16 v[12:15], v[108:111], v[232:235], v[12:15]
	v_mfma_f32_16x16x32_bf16 v[8:11], v[116:119], v[232:235], v[8:11]
	v_mfma_f32_16x16x32_bf16 v[52:55], v[144:147], v[160:163], v[52:55]
	v_mfma_f32_16x16x32_bf16 v[48:51], v[152:155], v[160:163], v[48:51]
	v_mfma_f32_16x16x32_bf16 v[36:39], v[144:147], v[196:199], v[36:39]
	v_mfma_f32_16x16x32_bf16 v[32:35], v[152:155], v[196:199], v[32:35]
	v_mfma_f32_16x16x32_bf16 v[20:23], v[144:147], v[210:213], v[20:23]
	v_mfma_f32_16x16x32_bf16 v[16:19], v[152:155], v[210:213], v[16:19]
	v_mfma_f32_16x16x32_bf16 v[4:7], v[144:147], v[228:231], v[4:7]
	v_mfma_f32_16x16x32_bf16 v[0:3], v[152:155], v[228:231], v[0:3]
	v_mfma_f32_16x16x32_bf16 v[52:55], v[148:151], v[192:195], v[52:55]
	v_mfma_f32_16x16x32_bf16 v[48:51], v[156:159], v[192:195], v[48:51]
	v_mfma_f32_16x16x32_bf16 v[36:39], v[148:151], v[206:209], v[36:39]
	v_mfma_f32_16x16x32_bf16 v[32:35], v[156:159], v[206:209], v[32:35]
	v_mfma_f32_16x16x32_bf16 v[20:23], v[148:151], v[224:227], v[20:23]
	v_mfma_f32_16x16x32_bf16 v[16:19], v[156:159], v[224:227], v[16:19]
	v_mfma_f32_16x16x32_bf16 v[4:7], v[148:151], v[232:235], v[4:7]
	v_mfma_f32_16x16x32_bf16 v[0:3], v[156:159], v[232:235], v[0:3]
	s_barrier
; #define PG8_STAGE(bufoff, gbase, voff) do { _Pragma("unroll") for (int _i = 0; _i < 2; ++_i) \
;         __builtin_amdgcn_global_load_lds((const unsigned*)((const char*)(gbase) + (voff)[_i]), (PG8_LAS unsigned*)(lds + (bufoff) + ldsw + _i * 8192), 16, 0, 0); } while (0)
; #define PG8_LDA(dst, b, h) do { _Pragma("unroll") for (int m = 0; m < 4; ++m) _Pragma("unroll") for (int k = 0; k < 2; ++k) dst[m][k] = *(const PG8_LAS bf16x8*)(lds + PG8_SA(b, h) + aoff + m * 2048 + k * 1024); } while (0)
; #define PG8_LDB(dst, b, h) do { _Pragma("unroll") for (int n = 0; n < 2; ++n) _Pragma("unroll") for (int k = 0; k < 2; ++k) dst[n][k] = *(const PG8_LAS bf16x8*)(lds + PG8_SB(b, h) + boff + n * 2048 + k * 1024); } while (0)
; #define PG8_MMA(ai, bj, At, Bt) do { __builtin_amdgcn_s_setprio(1); _Pragma("unroll") for (int m = 0; m < 4; ++m) _Pragma("unroll") for (int n = 0; n < 2; ++n) _Pragma("unroll") for (int k = 0; k < 2; ++k) \
;         acc[ai][bj][m][n] = __builtin_amdgcn_mfma_f32_16x16x32_bf16(Bt[n][k], At[m][k], acc[ai][bj][m][n], 0, 0, 0); __builtin_amdgcn_s_setprio(0); } while (0)
; #define PG8_WAIT_V(n) asm volatile("s_waitcnt vmcnt(" #n ")" ::: "memory")
; #define PG8_WAIT_L(n) asm volatile("s_waitcnt lgkmcnt(" #n ")" ::: "memory")
; #define PG8_BAR __builtin_amdgcn_s_barrier()
; #define PG8_SCHED __builtin_amdgcn_sched_barrier(0)
; template <class Epi, class Sched, bool ALIGN_EPI = false, bool SP2 = false>
; __device__ __forceinline__ void gemm_phase(PG8_LAS unsigned char* lds, const Gemm g, const Sched& S, const Epi& E, const int tid_in) {
;     ...
;             PG8_LDB(B0, 1, 0); PG8_LDB(B1, 1, 1); PG8_SCHED; PG8_LDA(At, 1, 0); PG8_STAGE(PG8_SA(0, 1), a2 + hstepA, voffA);
;             PG8_WAIT_V(8); PG8_WAIT_L(0); PG8_BAR; PG8_MMA(0, 0, At, B0); PG8_MMA(0, 1, At, B1); PG8_BAR; PG8_SCHED;
;             PG8_LDA(At, 1, 1); PG8_STAGE(PG8_SB(1, 0), b3, voffB); PG8_STAGE(PG8_SB(1, 1), b3 + hstepB, voffB); PG8_STAGE(PG8_SA(1, 0), a3, voffA);
;             PG8_WAIT_V(8); PG8_WAIT_L(0); PG8_BAR; PG8_MMA(1, 0, At, B0); PG8_MMA(1, 1, At, B1); PG8_BAR; PG8_SCHED;
;     ...
;         if constexpr (ALIGN_EPI) { if (wr == 0) PG8_BAR; }
	s_add_i32 s65, 0, 0x18000
	s_add_i32 s66, 0, 0x1c000
	ds_read_b128 v[104:107], v249 offset:32768
	ds_read_b128 v[108:111], v249 offset:33792
	ds_read_b128 v[112:115], v249 offset:34816
	ds_read_b128 v[116:119], v249 offset:35840
	ds_read_b128 v[144:147], v249 offset:49152
	ds_read_b128 v[148:151], v249 offset:50176
	ds_read_b128 v[152:155], v249 offset:51200
	ds_read_b128 v[156:159], v249 offset:52224
	s_add_u32 s60, s60, 0x80000
	s_addc_u32 s61, s61, 0
	s_mov_b32 m0, s30
	ds_read_b128 v[160:163], v204 offset:32768
	ds_read_b128 v[192:195], v204 offset:33792
	ds_read_b128 v[196:199], v204 offset:34816
	ds_read_b128 v[206:209], v204 offset:35840
	ds_read_b128 v[210:213], v204 offset:36864
	ds_read_b128 v[224:227], v204 offset:37888
	ds_read_b128 v[228:231], v204 offset:38912
	ds_read_b128 v[232:235], v204 offset:39936
	global_load_lds_dwordx4 v164, s[60:61]
	s_mov_b32 m0, s6
	s_nop 0
	global_load_lds_dwordx4 v166, s[60:61]
	s_waitcnt vmcnt(8) lgkmcnt(0)
	s_barrier
	v_mfma_f32_16x16x32_bf16 v[140:143], v[104:107], v[160:163], v[140:143]
	v_mfma_f32_16x16x32_bf16 v[136:139], v[112:115], v[160:163], v[136:139]
	v_mfma_f32_16x16x32_bf16 v[124:127], v[104:107], v[196:199], v[124:127]
	v_mfma_f32_16x16x32_bf16 v[120:123], v[112:115], v[196:199], v[120:123]
	v_mfma_f32_16x16x32_bf16 v[92:95], v[104:107], v[210:213], v[92:95]
	v_mfma_f32_16x16x32_bf16 v[88:91], v[112:115], v[210:213], v[88:91]
	v_mfma_f32_16x16x32_bf16 v[76:79], v[104:107], v[228:231], v[76:79]
	v_mfma_f32_16x16x32_bf16 v[72:75], v[112:115], v[228:231], v[72:75]
	v_mfma_f32_16x16x32_bf16 v[140:143], v[108:111], v[192:195], v[140:143]
	v_mfma_f32_16x16x32_bf16 v[136:139], v[116:119], v[192:195], v[136:139]
	v_mfma_f32_16x16x32_bf16 v[124:127], v[108:111], v[206:209], v[124:127]
	v_mfma_f32_16x16x32_bf16 v[120:123], v[116:119], v[206:209], v[120:123]
	v_mfma_f32_16x16x32_bf16 v[92:95], v[108:111], v[224:227], v[92:95]
	v_mfma_f32_16x16x32_bf16 v[88:91], v[116:119], v[224:227], v[88:91]
	v_mfma_f32_16x16x32_bf16 v[76:79], v[108:111], v[232:235], v[76:79]
	v_mfma_f32_16x16x32_bf16 v[72:75], v[116:119], v[232:235], v[72:75]
	v_mfma_f32_16x16x32_bf16 v[132:135], v[144:147], v[160:163], v[132:135]
	v_mfma_f32_16x16x32_bf16 v[128:131], v[152:155], v[160:163], v[128:131]
	v_mfma_f32_16x16x32_bf16 v[100:103], v[144:147], v[196:199], v[100:103]
	v_mfma_f32_16x16x32_bf16 v[96:99], v[152:155], v[196:199], v[96:99]
	v_mfma_f32_16x16x32_bf16 v[84:87], v[144:147], v[210:213], v[84:87]
	v_mfma_f32_16x16x32_bf16 v[80:83], v[152:155], v[210:213], v[80:83]
	v_mfma_f32_16x16x32_bf16 v[68:71], v[144:147], v[228:231], v[68:71]
	v_mfma_f32_16x16x32_bf16 v[64:67], v[152:155], v[228:231], v[64:67]
	v_mfma_f32_16x16x32_bf16 v[132:135], v[148:151], v[192:195], v[132:135]
	v_mfma_f32_16x16x32_bf16 v[128:131], v[156:159], v[192:195], v[128:131]
	v_mfma_f32_16x16x32_bf16 v[100:103], v[148:151], v[206:209], v[100:103]
	v_mfma_f32_16x16x32_bf16 v[96:99], v[156:159], v[206:209], v[96:99]
	v_mfma_f32_16x16x32_bf16 v[84:87], v[148:151], v[224:227], v[84:87]
	v_mfma_f32_16x16x32_bf16 v[80:83], v[156:159], v[224:227], v[80:83]
	v_mfma_f32_16x16x32_bf16 v[68:71], v[148:151], v[232:235], v[68:71]
	v_mfma_f32_16x16x32_bf16 v[64:67], v[156:159], v[232:235], v[64:67]
	s_barrier
	s_add_i32 s60, s65, s21
	s_mov_b32 m0, s60
	ds_read_b128 v[160:163], v204 offset:49152
	ds_read_b128 v[192:195], v204 offset:50176
	ds_read_b128 v[196:199], v204 offset:51200
	ds_read_b128 v[206:209], v204 offset:52224
	ds_read_b128 v[210:213], v204 offset:53248
	ds_read_b128 v[224:227], v204 offset:54272
	ds_read_b128 v[228:231], v204 offset:55296
	ds_read_b128 v[232:235], v204 offset:56320
	s_add_u32 s100, s22, 0x80
	s_addc_u32 s101, s23, 0
	global_load_lds_dwordx4 v172, s[100:101]
	s_add_i32 m0, s60, 0x2000
	s_add_u32 s22, s22, 0x80080
	s_addc_u32 s23, s23, 0
	s_add_i32 s60, s66, s21
	global_load_lds_dwordx4 v168, s[100:101]
	s_mov_b32 m0, s60
	s_nop 0
	global_load_lds_dwordx4 v172, s[22:23]
	s_add_i32 m0, s60, 0x2000
	s_nop 0
	global_load_lds_dwordx4 v168, s[22:23]
	s_mov_b32 m0, s33
	s_nop 0
	global_load_lds_dwordx4 v164, vcc
	s_mov_b32 m0, s34
	s_nop 0
	global_load_lds_dwordx4 v166, vcc
	s_waitcnt vmcnt(8) lgkmcnt(0)
	s_barrier
	v_mfma_f32_16x16x32_bf16 v[60:63], v[104:107], v[160:163], v[60:63]
	v_mfma_f32_16x16x32_bf16 v[56:59], v[112:115], v[160:163], v[56:59]
	v_mfma_f32_16x16x32_bf16 v[44:47], v[104:107], v[196:199], v[44:47]
	v_mfma_f32_16x16x32_bf16 v[40:43], v[112:115], v[196:199], v[40:43]
	v_mfma_f32_16x16x32_bf16 v[28:31], v[104:107], v[210:213], v[28:31]
	v_mfma_f32_16x16x32_bf16 v[24:27], v[112:115], v[210:213], v[24:27]
	v_mfma_f32_16x16x32_bf16 v[12:15], v[104:107], v[228:231], v[12:15]
	v_mfma_f32_16x16x32_bf16 v[8:11], v[112:115], v[228:231], v[8:11]
	v_mfma_f32_16x16x32_bf16 v[60:63], v[108:111], v[192:195], v[60:63]
	v_mfma_f32_16x16x32_bf16 v[56:59], v[116:119], v[192:195], v[56:59]
	v_mfma_f32_16x16x32_bf16 v[44:47], v[108:111], v[206:209], v[44:47]
	v_mfma_f32_16x16x32_bf16 v[40:43], v[116:119], v[206:209], v[40:43]
	v_mfma_f32_16x16x32_bf16 v[28:31], v[108:111], v[224:227], v[28:31]
	v_mfma_f32_16x16x32_bf16 v[24:27], v[116:119], v[224:227], v[24:27]
	v_mfma_f32_16x16x32_bf16 v[12:15], v[108:111], v[232:235], v[12:15]
	v_mfma_f32_16x16x32_bf16 v[8:11], v[116:119], v[232:235], v[8:11]
	v_mfma_f32_16x16x32_bf16 v[52:55], v[144:147], v[160:163], v[52:55]
	v_mfma_f32_16x16x32_bf16 v[48:51], v[152:155], v[160:163], v[48:51]
	v_mfma_f32_16x16x32_bf16 v[36:39], v[144:147], v[196:199], v[36:39]
	v_mfma_f32_16x16x32_bf16 v[32:35], v[152:155], v[196:199], v[32:35]
	v_mfma_f32_16x16x32_bf16 v[20:23], v[144:147], v[210:213], v[20:23]
	v_mfma_f32_16x16x32_bf16 v[16:19], v[152:155], v[210:213], v[16:19]
	v_mfma_f32_16x16x32_bf16 v[4:7], v[144:147], v[228:231], v[4:7]
	v_mfma_f32_16x16x32_bf16 v[0:3], v[152:155], v[228:231], v[0:3]
	v_mfma_f32_16x16x32_bf16 v[52:55], v[148:151], v[192:195], v[52:55]
	v_mfma_f32_16x16x32_bf16 v[48:51], v[156:159], v[192:195], v[48:51]
	v_mfma_f32_16x16x32_bf16 v[36:39], v[148:151], v[206:209], v[36:39]
	v_mfma_f32_16x16x32_bf16 v[32:35], v[156:159], v[206:209], v[32:35]
	v_mfma_f32_16x16x32_bf16 v[20:23], v[148:151], v[224:227], v[20:23]
	v_mfma_f32_16x16x32_bf16 v[16:19], v[156:159], v[224:227], v[16:19]
	v_mfma_f32_16x16x32_bf16 v[4:7], v[148:151], v[232:235], v[4:7]
	v_mfma_f32_16x16x32_bf16 v[0:3], v[156:159], v[232:235], v[0:3]
	s_barrier
	s_add_i32 s64, s64, 2
	s_add_u32 s58, s58, 0x100
	s_addc_u32 s59, s59, 0
	s_add_u32 s62, s62, 0x100
	s_addc_u32 s63, s63, 0
	s_cmp_gt_u32 s64, 29
	s_cbranch_scc0 .LBB0_2041
	s_and_b64 vcc, exec, s[46:47]
	s_cbranch_vccz .LBB0_2044
	s_barrier

;     __device__ __forceinline__ void a_ready(const Unit& u) const { wait_panel(cnt, u.pm, need, tmo, wave); }
;     __device__ __forceinline__ void a_ready(const Unit& u) const { wait_panel(cnt, u.pm, need, tmo, wave); }
; #define PG8_STAGE(bufoff, gbase, voff) do { _Pragma("unroll") for (int _i = 0; _i < 2; ++_i) \
;         __builtin_amdgcn_global_load_lds((const unsigned*)((const char*)(gbase) + (voff)[_i]), (PG8_LAS unsigned*)(lds + (bufoff) + ldsw + _i * 8192), 16, 0, 0); } while (0)
; #define PG8_LDA(dst, b, h) do { _Pragma("unroll") for (int m = 0; m < 4; ++m) _Pragma("unroll") for (int k = 0; k < 2; ++k) dst[m][k] = *(const PG8_LAS bf16x8*)(lds + PG8_SA(b, h) + aoff + m * 2048 + k * 1024); } while (0)
; #define PG8_LDB(dst, b, h) do { _Pragma("unroll") for (int n = 0; n < 2; ++n) _Pragma("unroll") for (int k = 0; k < 2; ++k) dst[n][k] = *(const PG8_LAS bf16x8*)(lds + PG8_SB(b, h) + boff + n * 2048 + k * 1024); } while (0)
; #define PG8_WAIT_V(n) asm volatile("s_waitcnt vmcnt(" #n ")" ::: "memory")
; #define PG8_WAIT_L(n) asm volatile("s_waitcnt lgkmcnt(" #n ")" ::: "memory")
; #define PG8_BAR __builtin_amdgcn_s_barrier()
; #define PG8_SCHED __builtin_amdgcn_sched_barrier(0)
; template <class Epi, class Sched, bool ALIGN_EPI = false, bool SP2 = false>
; __device__ __forceinline__ void gemm_phase(PG8_LAS unsigned char* lds, const Gemm g, const Sched& S, const Epi& E, const int tid_in) {
;     ...
;         for (int t = 0; t < nt; t += 2) {
;             const bool last = (t == nt - 2);
;             const char* a1 = cA + (size_t)(t + 1) * kstep;
;             const char* a2 = last ? nA : cA + (size_t)(t + 2) * kstep; const char* b2 = last ? nB : cB + (size_t)(t + 2) * kstep;
;             const char* a3 = a2 + kstep; const char* b3 = b2 + kstep;
;             if (last && has_next) S.a_ready(nxt);
;             if constexpr (SP2) {
;             PG8_LDB(B0, 0, 0); PG8_LDB(B1, 0, 1); PG8_SCHED; PG8_LDA(At, 0, 0); PG8_STAGE(PG8_SA(1, 1), a1 + hstepA, voffA);
;             PG8_WAIT_V(8); PG8_WAIT_L(0); PG8_BAR; PG8_MMA(0, 0, At, B0); PG8_MMA(0, 1, At, B1); PG8_BAR; PG8_SCHED;
;             PG8_LDA(At, 0, 1); PG8_STAGE(PG8_SB(0, 0), b2, voffB); PG8_STAGE(PG8_SB(0, 1), b2 + hstepB, voffB); PG8_STAGE(PG8_SA(0, 0), a2, voffA);
;             PG8_WAIT_V(8); PG8_WAIT_L(0); PG8_BAR; PG8_MMA(1, 0, At, B0); PG8_MMA(1, 1, At, B1); PG8_BAR; PG8_SCHED;
.LBB0_2059:
	s_add_u32 s22, s62, 0xfff80080
	s_addc_u32 s23, s63, -1
	s_add_i32 s55, 0, 0x10000
	s_cmp_eq_u32 s53, 4
	s_cselect_b32 s65, s61, s23
	s_cselect_b32 s64, s60, s22
	s_cselect_b32 s23, s59, s38
	s_cselect_b32 s22, s58, s35
	s_add_i32 s57, 0, 0x14000
	ds_read_b128 v[64:67], v249
	ds_read_b128 v[68:71], v249 offset:1024
	ds_read_b128 v[72:75], v249 offset:2048
	ds_read_b128 v[76:79], v249 offset:3072
	ds_read_b128 v[80:83], v249 offset:16384
	ds_read_b128 v[84:87], v249 offset:17408
	ds_read_b128 v[88:91], v249 offset:18432
	ds_read_b128 v[92:95], v249 offset:19456
	s_add_i32 m0, s12, 0xc000
	ds_read_b128 v[96:99], v154
	ds_read_b128 v[100:103], v154 offset:1024
	ds_read_b128 v[104:107], v154 offset:2048
	ds_read_b128 v[108:111], v154 offset:3072
	ds_read_b128 v[112:115], v154 offset:4096
	ds_read_b128 v[116:119], v154 offset:5120
	ds_read_b128 v[120:123], v154 offset:6144
	ds_read_b128 v[124:127], v154 offset:7168
	global_load_lds_dwordx4 v148, s[62:63]
	s_add_i32 m0, s12, 0xe000
	s_nop 0
	global_load_lds_dwordx4 v146, s[62:63]
	s_waitcnt vmcnt(8) lgkmcnt(0)
	s_barrier
	v_mfma_f32_16x16x32_bf16 v[60:63], v[64:67], v[96:99], v[60:63]
	v_mfma_f32_16x16x32_bf16 v[56:59], v[72:75], v[96:99], v[56:59]
	v_mfma_f32_16x16x32_bf16 v[48:51], v[64:67], v[104:107], v[48:51]
	v_mfma_f32_16x16x32_bf16 v[40:43], v[72:75], v[104:107], v[40:43]
	v_mfma_f32_16x16x32_bf16 v[32:35], v[64:67], v[112:115], v[32:35]
	v_mfma_f32_16x16x32_bf16 v[24:27], v[72:75], v[112:115], v[24:27]
	v_mfma_f32_16x16x32_bf16 v[16:19], v[64:67], v[120:123], v[16:19]
	v_mfma_f32_16x16x32_bf16 v[8:11], v[72:75], v[120:123], v[8:11]
	v_mfma_f32_16x16x32_bf16 v[60:63], v[68:71], v[100:103], v[60:63]
	v_mfma_f32_16x16x32_bf16 v[56:59], v[76:79], v[100:103], v[56:59]
	v_mfma_f32_16x16x32_bf16 v[48:51], v[68:71], v[108:111], v[48:51]
	v_mfma_f32_16x16x32_bf16 v[40:43], v[76:79], v[108:111], v[40:43]
	v_mfma_f32_16x16x32_bf16 v[32:35], v[68:71], v[116:119], v[32:35]
	v_mfma_f32_16x16x32_bf16 v[24:27], v[76:79], v[116:119], v[24:27]
	v_mfma_f32_16x16x32_bf16 v[16:19], v[68:71], v[124:127], v[16:19]
	v_mfma_f32_16x16x32_bf16 v[8:11], v[76:79], v[124:127], v[8:11]
	v_mfma_f32_16x16x32_bf16 v[52:55], v[80:83], v[96:99], v[52:55]
	v_mfma_f32_16x16x32_bf16 v[44:47], v[88:91], v[96:99], v[44:47]
	v_mfma_f32_16x16x32_bf16 v[36:39], v[80:83], v[104:107], v[36:39]
	v_mfma_f32_16x16x32_bf16 v[28:31], v[88:91], v[104:107], v[28:31]
	v_mfma_f32_16x16x32_bf16 v[20:23], v[80:83], v[112:115], v[20:23]
	v_mfma_f32_16x16x32_bf16 v[12:15], v[88:91], v[112:115], v[12:15]
	v_mfma_f32_16x16x32_bf16 v[4:7], v[80:83], v[120:123], v[4:7]
	v_mfma_f32_16x16x32_bf16 v[0:3], v[88:91], v[120:123], v[0:3]
	v_mfma_f32_16x16x32_bf16 v[52:55], v[84:87], v[100:103], v[52:55]
	v_mfma_f32_16x16x32_bf16 v[44:47], v[92:95], v[100:103], v[44:47]
	v_mfma_f32_16x16x32_bf16 v[36:39], v[84:87], v[108:111], v[36:39]
	v_mfma_f32_16x16x32_bf16 v[28:31], v[92:95], v[108:111], v[28:31]
	v_mfma_f32_16x16x32_bf16 v[20:23], v[84:87], v[116:119], v[20:23]
	v_mfma_f32_16x16x32_bf16 v[12:15], v[92:95], v[116:119], v[12:15]
	v_mfma_f32_16x16x32_bf16 v[4:7], v[84:87], v[124:127], v[4:7]
	v_mfma_f32_16x16x32_bf16 v[0:3], v[92:95], v[124:127], v[0:3]
	s_barrier
	s_add_i32 s55, s55, s6
	s_mov_b32 m0, s55
	s_nop 0
	global_load_lds_dwordx4 v172, s[22:23]
	s_add_i32 m0, s55, 0x2000
	s_add_u32 s66, s22, 0x80000
	s_addc_u32 s67, s23, 0
	s_add_i32 s55, s57, s6
	global_load_lds_dwordx4 v128, s[22:23]
	s_mov_b32 m0, s55
	s_nop 0
	global_load_lds_dwordx4 v172, s[66:67]
	s_add_i32 m0, s55, 0x2000
	s_nop 0
	global_load_lds_dwordx4 v128, s[66:67]
	s_mov_b32 m0, s12
	s_nop 0
	global_load_lds_dwordx4 v172, s[64:65]
	s_mov_b32 m0, s20
	s_nop 0
	global_load_lds_dwordx4 v128, s[64:65]
	s_waitcnt vmcnt(8) lgkmcnt(0)
	s_barrier
	s_barrier
; #define PG8_STAGE(bufoff, gbase, voff) do { _Pragma("unroll") for (int _i = 0; _i < 2; ++_i) \
;         __builtin_amdgcn_global_load_lds((const unsigned*)((const char*)(gbase) + (voff)[_i]), (PG8_LAS unsigned*)(lds + (bufoff) + ldsw + _i * 8192), 16, 0, 0); } while (0)
; #define PG8_LDA(dst, b, h) do { _Pragma("unroll") for (int m = 0; m < 4; ++m) _Pragma("unroll") for (int k = 0; k < 2; ++k) dst[m][k] = *(const PG8_LAS bf16x8*)(lds + PG8_SA(b, h) + aoff + m * 2048 + k * 1024); } while (0)
; #define PG8_LDB(dst, b, h) do { _Pragma("unroll") for (int n = 0; n < 2; ++n) _Pragma("unroll") for (int k = 0; k < 2; ++k) dst[n][k] = *(const PG8_LAS bf16x8*)(lds + PG8_SB(b, h) + boff + n * 2048 + k * 1024); } while (0)
; #define PG8_MMA(ai, bj, At, Bt) do { __builtin_amdgcn_s_setprio(1); _Pragma("unroll") for (int m = 0; m < 4; ++m) _Pragma("unroll") for (int n = 0; n < 2; ++n) _Pragma("unroll") for (int k = 0; k < 2; ++k) \
;         acc[ai][bj][m][n] = __builtin_amdgcn_mfma_f32_16x16x32_bf16(Bt[n][k], At[m][k], acc[ai][bj][m][n], 0, 0, 0); __builtin_amdgcn_s_setprio(0); } while (0)
; #define PG8_WAIT_V(n) asm volatile("s_waitcnt vmcnt(" #n ")" ::: "memory")
; #define PG8_WAIT_L(n) asm volatile("s_waitcnt lgkmcnt(" #n ")" ::: "memory")
; #define PG8_BAR __builtin_amdgcn_s_barrier()
; #define PG8_SCHED __builtin_amdgcn_sched_barrier(0)
; template <class Epi, class Sched, bool ALIGN_EPI = false, bool SP2 = false>
; __device__ __forceinline__ void gemm_phase(PG8_LAS unsigned char* lds, const Gemm g, const Sched& S, const Epi& E, const int tid_in) {
;     ...
;             PG8_LDB(B0, 1, 0); PG8_LDB(B1, 1, 1); PG8_SCHED; PG8_LDA(At, 1, 0); PG8_STAGE(PG8_SA(0, 1), a2 + hstepA, voffA);
;             PG8_WAIT_V(8); PG8_WAIT_L(0); PG8_BAR; PG8_MMA(0, 0, At, B0); PG8_MMA(0, 1, At, B1); PG8_BAR; PG8_SCHED;
;             PG8_LDA(At, 1, 1); PG8_STAGE(PG8_SB(1, 0), b3, voffB); PG8_STAGE(PG8_SB(1, 1), b3 + hstepB, voffB); PG8_STAGE(PG8_SA(1, 0), a3, voffA);
;             PG8_WAIT_V(8); PG8_WAIT_L(0); PG8_BAR; PG8_MMA(1, 0, At, B0); PG8_MMA(1, 1, At, B1); PG8_BAR; PG8_SCHED;
;     ...
;         if constexpr (ALIGN_EPI) { if (wr == 0) PG8_BAR; }
	s_add_i32 s55, 0, 0x18000
	s_add_i32 s57, 0, 0x1c000
	ds_read_b128 v[64:67], v249 offset:32768
	ds_read_b128 v[68:71], v249 offset:33792
	ds_read_b128 v[72:75], v249 offset:34816
	ds_read_b128 v[76:79], v249 offset:35840
	ds_read_b128 v[80:83], v249 offset:49152
	ds_read_b128 v[84:87], v249 offset:50176
	ds_read_b128 v[88:91], v249 offset:51200
	ds_read_b128 v[92:95], v249 offset:52224
	s_add_u32 s64, s64, 0x80000
	s_addc_u32 s65, s65, 0
	s_mov_b32 m0, s21
	ds_read_b128 v[96:99], v154 offset:32768
	ds_read_b128 v[100:103], v154 offset:33792
	ds_read_b128 v[104:107], v154 offset:34816
	ds_read_b128 v[108:111], v154 offset:35840
	ds_read_b128 v[112:115], v154 offset:36864
	ds_read_b128 v[116:119], v154 offset:37888
	ds_read_b128 v[120:123], v154 offset:38912
	ds_read_b128 v[124:127], v154 offset:39936
	global_load_lds_dwordx4 v172, s[64:65]
	s_mov_b32 m0, s28
	s_nop 0
	global_load_lds_dwordx4 v128, s[64:65]
	s_waitcnt vmcnt(8) lgkmcnt(0)
	s_barrier
	v_mfma_f32_16x16x32_bf16 v[60:63], v[64:67], v[96:99], v[60:63]
	v_mfma_f32_16x16x32_bf16 v[56:59], v[72:75], v[96:99], v[56:59]
	v_mfma_f32_16x16x32_bf16 v[48:51], v[64:67], v[104:107], v[48:51]
	v_mfma_f32_16x16x32_bf16 v[40:43], v[72:75], v[104:107], v[40:43]
	v_mfma_f32_16x16x32_bf16 v[32:35], v[64:67], v[112:115], v[32:35]
	v_mfma_f32_16x16x32_bf16 v[24:27], v[72:75], v[112:115], v[24:27]
	v_mfma_f32_16x16x32_bf16 v[16:19], v[64:67], v[120:123], v[16:19]
	v_mfma_f32_16x16x32_bf16 v[8:11], v[72:75], v[120:123], v[8:11]
	v_mfma_f32_16x16x32_bf16 v[60:63], v[68:71], v[100:103], v[60:63]
	v_mfma_f32_16x16x32_bf16 v[56:59], v[76:79], v[100:103], v[56:59]
	v_mfma_f32_16x16x32_bf16 v[48:51], v[68:71], v[108:111], v[48:51]
	v_mfma_f32_16x16x32_bf16 v[40:43], v[76:79], v[108:111], v[40:43]
	v_mfma_f32_16x16x32_bf16 v[32:35], v[68:71], v[116:119], v[32:35]
	v_mfma_f32_16x16x32_bf16 v[24:27], v[76:79], v[116:119], v[24:27]
	v_mfma_f32_16x16x32_bf16 v[16:19], v[68:71], v[124:127], v[16:19]
	v_mfma_f32_16x16x32_bf16 v[8:11], v[76:79], v[124:127], v[8:11]
	v_mfma_f32_16x16x32_bf16 v[52:55], v[80:83], v[96:99], v[52:55]
	v_mfma_f32_16x16x32_bf16 v[44:47], v[88:91], v[96:99], v[44:47]
	v_mfma_f32_16x16x32_bf16 v[36:39], v[80:83], v[104:107], v[36:39]
	v_mfma_f32_16x16x32_bf16 v[28:31], v[88:91], v[104:107], v[28:31]
	v_mfma_f32_16x16x32_bf16 v[20:23], v[80:83], v[112:115], v[20:23]
	v_mfma_f32_16x16x32_bf16 v[12:15], v[88:91], v[112:115], v[12:15]
	v_mfma_f32_16x16x32_bf16 v[4:7], v[80:83], v[120:123], v[4:7]
	v_mfma_f32_16x16x32_bf16 v[0:3], v[88:91], v[120:123], v[0:3]
	v_mfma_f32_16x16x32_bf16 v[52:55], v[84:87], v[100:103], v[52:55]
	v_mfma_f32_16x16x32_bf16 v[44:47], v[92:95], v[100:103], v[44:47]
	v_mfma_f32_16x16x32_bf16 v[36:39], v[84:87], v[108:111], v[36:39]
	v_mfma_f32_16x16x32_bf16 v[28:31], v[92:95], v[108:111], v[28:31]
	v_mfma_f32_16x16x32_bf16 v[20:23], v[84:87], v[116:119], v[20:23]
	v_mfma_f32_16x16x32_bf16 v[12:15], v[92:95], v[116:119], v[12:15]
	v_mfma_f32_16x16x32_bf16 v[4:7], v[84:87], v[124:127], v[4:7]
	v_mfma_f32_16x16x32_bf16 v[0:3], v[92:95], v[124:127], v[0:3]
	s_barrier
	s_add_i32 s55, s55, s6
	s_mov_b32 m0, s55
	s_nop 0
	s_add_u32 s100, s22, 0x80
	s_addc_u32 s101, s23, 0
	global_load_lds_dwordx4 v172, s[100:101]
	s_add_i32 m0, s55, 0x2000
	s_add_u32 s22, s22, 0x80080
	s_addc_u32 s23, s23, 0
	s_add_i32 s55, s57, s6
	global_load_lds_dwordx4 v128, s[100:101]
	s_mov_b32 m0, s55
	s_nop 0
	global_load_lds_dwordx4 v172, s[22:23]
	s_add_i32 m0, s55, 0x2000
	s_nop 0
	global_load_lds_dwordx4 v128, s[22:23]
	s_mov_b32 m0, s29
	s_nop 0
	s_add_u32 s100, s64, 0xfff80080
	s_addc_u32 s101, s65, -1
	global_load_lds_dwordx4 v172, s[100:101]
	s_mov_b32 m0, s30
	s_nop 0
	global_load_lds_dwordx4 v128, s[100:101]
	s_waitcnt vmcnt(8) lgkmcnt(0)
	s_barrier
	s_barrier
	s_add_i32 s53, s53, 2
	s_add_u32 s62, s62, 0x100
	s_addc_u32 s63, s63, 0
	s_add_u32 s35, s35, 0x100
	s_addc_u32 s38, s38, 0
	s_cmp_gt_u32 s53, 5
	s_cbranch_scc0 .LBB0_2059
	s_and_b64 vcc, exec, s[36:37]
	s_cbranch_vccz .LBB0_2062
	s_barrier

;     __device__ __forceinline__ void a_ready(const Unit& u) const { wait_panel(cnt, u.pm, need, tmo, wave); }
;     __device__ __forceinline__ void a_ready(const Unit& u) const { wait_panel(cnt, u.pm, need, tmo, wave); }
; #define PG8_STAGE(bufoff, gbase, voff) do { _Pragma("unroll") for (int _i = 0; _i < 2; ++_i) \
;         __builtin_amdgcn_global_load_lds((const unsigned*)((const char*)(gbase) + (voff)[_i]), (PG8_LAS unsigned*)(lds + (bufoff) + ldsw + _i * 8192), 16, 0, 0); } while (0)
; #define PG8_LDA(dst, b, h) do { _Pragma("unroll") for (int m = 0; m < 4; ++m) _Pragma("unroll") for (int k = 0; k < 2; ++k) dst[m][k] = *(const PG8_LAS bf16x8*)(lds + PG8_SA(b, h) + aoff + m * 2048 + k * 1024); } while (0)
; #define PG8_LDB(dst, b, h) do { _Pragma("unroll") for (int n = 0; n < 2; ++n) _Pragma("unroll") for (int k = 0; k < 2; ++k) dst[n][k] = *(const PG8_LAS bf16x8*)(lds + PG8_SB(b, h) + boff + n * 2048 + k * 1024); } while (0)
; #define PG8_WAIT_V(n) asm volatile("s_waitcnt vmcnt(" #n ")" ::: "memory")
; #define PG8_WAIT_L(n) asm volatile("s_waitcnt lgkmcnt(" #n ")" ::: "memory")
; #define PG8_BAR __builtin_amdgcn_s_barrier()
; #define PG8_SCHED __builtin_amdgcn_sched_barrier(0)
; template <class Epi, class Sched, bool ALIGN_EPI = false, bool SP2 = false>
; __device__ __forceinline__ void gemm_phase(PG8_LAS unsigned char* lds, const Gemm g, const Sched& S, const Epi& E, const int tid_in) {
;     ...
;         for (int t = 0; t < nt; t += 2) {
;             const bool last = (t == nt - 2);
;             const char* a1 = cA + (size_t)(t + 1) * kstep;
;             const char* a2 = last ? nA : cA + (size_t)(t + 2) * kstep; const char* b2 = last ? nB : cB + (size_t)(t + 2) * kstep;
;             const char* a3 = a2 + kstep; const char* b3 = b2 + kstep;
;             if (last && has_next) S.a_ready(nxt);
;             if constexpr (SP2) {
;             PG8_LDB(B0, 0, 0); PG8_LDB(B1, 0, 1); PG8_SCHED; PG8_LDA(At, 0, 0); PG8_STAGE(PG8_SA(1, 1), a1 + hstepA, voffA);
;             PG8_WAIT_V(8); PG8_WAIT_L(0); PG8_BAR; PG8_MMA(0, 0, At, B0); PG8_MMA(0, 1, At, B1); PG8_BAR; PG8_SCHED;
;             PG8_LDA(At, 0, 1); PG8_STAGE(PG8_SB(0, 0), b2, voffB); PG8_STAGE(PG8_SB(0, 1), b2 + hstepB, voffB); PG8_STAGE(PG8_SA(0, 0), a2, voffA);
;             PG8_WAIT_V(8); PG8_WAIT_L(0); PG8_BAR; PG8_MMA(1, 0, At, B0); PG8_MMA(1, 1, At, B1); PG8_BAR; PG8_SCHED;
.LBB0_2312:
	s_add_u32 s22, s64, 0xfff80080
	s_addc_u32 s23, s65, -1
	s_add_i32 s55, 0, 0x10000
	s_cmp_eq_u32 s51, 28
	s_cselect_b32 s67, s6, s23
	s_cselect_b32 s66, s16, s22
	s_cselect_b32 s23, s17, s35
	s_cselect_b32 s22, s33, s34
	s_add_i32 s63, 0, 0x14000
	ds_read_b128 v[144:147], v249
	ds_read_b128 v[148:151], v249 offset:1024
	ds_read_b128 v[152:155], v249 offset:2048
	ds_read_b128 v[156:159], v249 offset:3072
	ds_read_b128 v[160:163], v249 offset:16384
	ds_read_b128 v[164:167], v249 offset:17408
	ds_read_b128 v[168:171], v249 offset:18432
	ds_read_b128 v[190:193], v249 offset:19456
	s_add_i32 m0, s37, 0xc000
	ds_read_b128 v[198:201], v143
	ds_read_b128 v[202:205], v143 offset:1024
	ds_read_b128 v[206:209], v143 offset:2048
	ds_read_b128 v[210:213], v143 offset:3072
	ds_read_b128 v[224:227], v143 offset:4096
	ds_read_b128 v[228:231], v143 offset:5120
	ds_read_b128 v[232:235], v143 offset:6144
	ds_read_b128 v[236:239], v143 offset:7168
	global_load_lds_dwordx4 v134, s[64:65]
	s_add_i32 m0, s37, 0xe000
	s_nop 0
	global_load_lds_dwordx4 v136, s[64:65]
	s_waitcnt vmcnt(8) lgkmcnt(0)
	s_barrier
	v_mfma_f32_16x16x32_bf16 v[124:127], v[144:147], v[198:201], v[124:127]
	v_mfma_f32_16x16x32_bf16 v[116:119], v[152:155], v[198:201], v[116:119]
	v_mfma_f32_16x16x32_bf16 v[108:111], v[144:147], v[206:209], v[108:111]
	v_mfma_f32_16x16x32_bf16 v[100:103], v[152:155], v[206:209], v[100:103]
	v_mfma_f32_16x16x32_bf16 v[92:95], v[144:147], v[224:227], v[92:95]
	v_mfma_f32_16x16x32_bf16 v[84:87], v[152:155], v[224:227], v[84:87]
	v_mfma_f32_16x16x32_bf16 v[76:79], v[144:147], v[232:235], v[76:79]
	v_mfma_f32_16x16x32_bf16 v[68:71], v[152:155], v[232:235], v[68:71]
	v_mfma_f32_16x16x32_bf16 v[124:127], v[148:151], v[202:205], v[124:127]
	v_mfma_f32_16x16x32_bf16 v[116:119], v[156:159], v[202:205], v[116:119]
	v_mfma_f32_16x16x32_bf16 v[108:111], v[148:151], v[210:213], v[108:111]
	v_mfma_f32_16x16x32_bf16 v[100:103], v[156:159], v[210:213], v[100:103]
	v_mfma_f32_16x16x32_bf16 v[92:95], v[148:151], v[228:231], v[92:95]
	v_mfma_f32_16x16x32_bf16 v[84:87], v[156:159], v[228:231], v[84:87]
	v_mfma_f32_16x16x32_bf16 v[76:79], v[148:151], v[236:239], v[76:79]
	v_mfma_f32_16x16x32_bf16 v[68:71], v[156:159], v[236:239], v[68:71]
	v_mfma_f32_16x16x32_bf16 v[120:123], v[160:163], v[198:201], v[120:123]
	v_mfma_f32_16x16x32_bf16 v[112:115], v[168:171], v[198:201], v[112:115]
	v_mfma_f32_16x16x32_bf16 v[104:107], v[160:163], v[206:209], v[104:107]
	v_mfma_f32_16x16x32_bf16 v[96:99], v[168:171], v[206:209], v[96:99]
	v_mfma_f32_16x16x32_bf16 v[88:91], v[160:163], v[224:227], v[88:91]
	v_mfma_f32_16x16x32_bf16 v[80:83], v[168:171], v[224:227], v[80:83]
	v_mfma_f32_16x16x32_bf16 v[72:75], v[160:163], v[232:235], v[72:75]
	v_mfma_f32_16x16x32_bf16 v[64:67], v[168:171], v[232:235], v[64:67]
	v_mfma_f32_16x16x32_bf16 v[120:123], v[164:167], v[202:205], v[120:123]
	v_mfma_f32_16x16x32_bf16 v[112:115], v[190:193], v[202:205], v[112:115]
	v_mfma_f32_16x16x32_bf16 v[104:107], v[164:167], v[210:213], v[104:107]
	v_mfma_f32_16x16x32_bf16 v[96:99], v[190:193], v[210:213], v[96:99]
	v_mfma_f32_16x16x32_bf16 v[88:91], v[164:167], v[228:231], v[88:91]
	v_mfma_f32_16x16x32_bf16 v[80:83], v[190:193], v[228:231], v[80:83]
	v_mfma_f32_16x16x32_bf16 v[72:75], v[164:167], v[236:239], v[72:75]
	v_mfma_f32_16x16x32_bf16 v[64:67], v[190:193], v[236:239], v[64:67]
	s_barrier
	s_add_i32 s55, s55, s69
	s_mov_b32 m0, s55
	ds_read_b128 v[198:201], v143 offset:16384
	ds_read_b128 v[202:205], v143 offset:17408
	ds_read_b128 v[206:209], v143 offset:18432
	ds_read_b128 v[210:213], v143 offset:19456
	ds_read_b128 v[224:227], v143 offset:20480
	ds_read_b128 v[228:231], v143 offset:21504
	ds_read_b128 v[232:235], v143 offset:22528
	ds_read_b128 v[236:239], v143 offset:23552
	global_load_lds_dwordx4 v172, s[22:23]
	s_add_i32 m0, s55, 0x2000
	s_add_u32 vcc_lo, s22, 0x80000
	s_addc_u32 vcc_hi, s23, 0
	s_add_i32 s55, s63, s69
	global_load_lds_dwordx4 v132, s[22:23]
	s_mov_b32 m0, s55
	s_nop 0
	global_load_lds_dwordx4 v172, vcc
	s_add_i32 m0, s55, 0x2000
	s_nop 0
	global_load_lds_dwordx4 v132, vcc
	s_mov_b32 m0, s37
	s_nop 0
	global_load_lds_dwordx4 v128, s[66:67]
	s_mov_b32 m0, s70
	s_nop 0
	global_load_lds_dwordx4 v130, s[66:67]
	s_waitcnt vmcnt(8) lgkmcnt(0)
	s_barrier
	v_mfma_f32_16x16x32_bf16 v[60:63], v[144:147], v[198:201], v[60:63]
	v_mfma_f32_16x16x32_bf16 v[52:55], v[152:155], v[198:201], v[52:55]
	v_mfma_f32_16x16x32_bf16 v[44:47], v[144:147], v[206:209], v[44:47]
	v_mfma_f32_16x16x32_bf16 v[36:39], v[152:155], v[206:209], v[36:39]
	v_mfma_f32_16x16x32_bf16 v[28:31], v[144:147], v[224:227], v[28:31]
	v_mfma_f32_16x16x32_bf16 v[20:23], v[152:155], v[224:227], v[20:23]
	v_mfma_f32_16x16x32_bf16 v[12:15], v[144:147], v[232:235], v[12:15]
	v_mfma_f32_16x16x32_bf16 v[4:7], v[152:155], v[232:235], v[4:7]
	v_mfma_f32_16x16x32_bf16 v[60:63], v[148:151], v[202:205], v[60:63]
	v_mfma_f32_16x16x32_bf16 v[52:55], v[156:159], v[202:205], v[52:55]
	v_mfma_f32_16x16x32_bf16 v[44:47], v[148:151], v[210:213], v[44:47]
	v_mfma_f32_16x16x32_bf16 v[36:39], v[156:159], v[210:213], v[36:39]
	v_mfma_f32_16x16x32_bf16 v[28:31], v[148:151], v[228:231], v[28:31]
	v_mfma_f32_16x16x32_bf16 v[20:23], v[156:159], v[228:231], v[20:23]
	v_mfma_f32_16x16x32_bf16 v[12:15], v[148:151], v[236:239], v[12:15]
	v_mfma_f32_16x16x32_bf16 v[4:7], v[156:159], v[236:239], v[4:7]
	v_mfma_f32_16x16x32_bf16 v[56:59], v[160:163], v[198:201], v[56:59]
	v_mfma_f32_16x16x32_bf16 v[48:51], v[168:171], v[198:201], v[48:51]
	v_mfma_f32_16x16x32_bf16 v[40:43], v[160:163], v[206:209], v[40:43]
	v_mfma_f32_16x16x32_bf16 v[32:35], v[168:171], v[206:209], v[32:35]
	v_mfma_f32_16x16x32_bf16 v[24:27], v[160:163], v[224:227], v[24:27]
	v_mfma_f32_16x16x32_bf16 v[16:19], v[168:171], v[224:227], v[16:19]
	v_mfma_f32_16x16x32_bf16 v[8:11], v[160:163], v[232:235], v[8:11]
	v_mfma_f32_16x16x32_bf16 v[0:3], v[168:171], v[232:235], v[0:3]
	v_mfma_f32_16x16x32_bf16 v[56:59], v[164:167], v[202:205], v[56:59]
	v_mfma_f32_16x16x32_bf16 v[48:51], v[190:193], v[202:205], v[48:51]
	v_mfma_f32_16x16x32_bf16 v[40:43], v[164:167], v[210:213], v[40:43]
	v_mfma_f32_16x16x32_bf16 v[32:35], v[190:193], v[210:213], v[32:35]
	v_mfma_f32_16x16x32_bf16 v[24:27], v[164:167], v[228:231], v[24:27]
	v_mfma_f32_16x16x32_bf16 v[16:19], v[190:193], v[228:231], v[16:19]
	v_mfma_f32_16x16x32_bf16 v[8:11], v[164:167], v[236:239], v[8:11]
	v_mfma_f32_16x16x32_bf16 v[0:3], v[190:193], v[236:239], v[0:3]
	s_barrier
; #define PG8_STAGE(bufoff, gbase, voff) do { _Pragma("unroll") for (int _i = 0; _i < 2; ++_i) \
;         __builtin_amdgcn_global_load_lds((const unsigned*)((const char*)(gbase) + (voff)[_i]), (PG8_LAS unsigned*)(lds + (bufoff) + ldsw + _i * 8192), 16, 0, 0); } while (0)
; #define PG8_LDA(dst, b, h) do { _Pragma("unroll") for (int m = 0; m < 4; ++m) _Pragma("unroll") for (int k = 0; k < 2; ++k) dst[m][k] = *(const PG8_LAS bf16x8*)(lds + PG8_SA(b, h) + aoff + m * 2048 + k * 1024); } while (0)
; #define PG8_LDB(dst, b, h) do { _Pragma("unroll") for (int n = 0; n < 2; ++n) _Pragma("unroll") for (int k = 0; k < 2; ++k) dst[n][k] = *(const PG8_LAS bf16x8*)(lds + PG8_SB(b, h) + boff + n * 2048 + k * 1024); } while (0)
; #define PG8_MMA(ai, bj, At, Bt) do { __builtin_amdgcn_s_setprio(1); _Pragma("unroll") for (int m = 0; m < 4; ++m) _Pragma("unroll") for (int n = 0; n < 2; ++n) _Pragma("unroll") for (int k = 0; k < 2; ++k) \
;         acc[ai][bj][m][n] = __builtin_amdgcn_mfma_f32_16x16x32_bf16(Bt[n][k], At[m][k], acc[ai][bj][m][n], 0, 0, 0); __builtin_amdgcn_s_setprio(0); } while (0)
; #define PG8_WAIT_V(n) asm volatile("s_waitcnt vmcnt(" #n ")" ::: "memory")
; #define PG8_WAIT_L(n) asm volatile("s_waitcnt lgkmcnt(" #n ")" ::: "memory")
; #define PG8_BAR __builtin_amdgcn_s_barrier()
; #define PG8_SCHED __builtin_amdgcn_sched_barrier(0)
; template <class Epi, class Sched, bool ALIGN_EPI = false, bool SP2 = false>
; __device__ __forceinline__ void gemm_phase(PG8_LAS unsigned char* lds, const Gemm g, const Sched& S, const Epi& E, const int tid_in) {
;     ...
;             PG8_LDB(B0, 1, 0); PG8_LDB(B1, 1, 1); PG8_SCHED; PG8_LDA(At, 1, 0); PG8_STAGE(PG8_SA(0, 1), a2 + hstepA, voffA);
;             PG8_WAIT_V(8); PG8_WAIT_L(0); PG8_BAR; PG8_MMA(0, 0, At, B0); PG8_MMA(0, 1, At, B1); PG8_BAR; PG8_SCHED;
;             PG8_LDA(At, 1, 1); PG8_STAGE(PG8_SB(1, 0), b3, voffB); PG8_STAGE(PG8_SB(1, 1), b3 + hstepB, voffB); PG8_STAGE(PG8_SA(1, 0), a3, voffA);
;             PG8_WAIT_V(8); PG8_WAIT_L(0); PG8_BAR; PG8_MMA(1, 0, At, B0); PG8_MMA(1, 1, At, B1); PG8_BAR; PG8_SCHED;
;     ...
;         if constexpr (ALIGN_EPI) { if (wr == 0) PG8_BAR; }
	s_add_i32 s55, 0, 0x18000
	s_add_i32 s63, 0, 0x1c000
	ds_read_b128 v[144:147], v249 offset:32768
	ds_read_b128 v[148:151], v249 offset:33792
	ds_read_b128 v[152:155], v249 offset:34816
	ds_read_b128 v[156:159], v249 offset:35840
	ds_read_b128 v[160:163], v249 offset:49152
	ds_read_b128 v[164:167], v249 offset:50176
	ds_read_b128 v[168:171], v249 offset:51200
	ds_read_b128 v[190:193], v249 offset:52224
	s_add_u32 s66, s66, 0x80000
	s_addc_u32 s67, s67, 0
	s_mov_b32 m0, s71
	ds_read_b128 v[198:201], v143 offset:32768
	ds_read_b128 v[202:205], v143 offset:33792
	ds_read_b128 v[206:209], v143 offset:34816
	ds_read_b128 v[210:213], v143 offset:35840
	ds_read_b128 v[224:227], v143 offset:36864
	ds_read_b128 v[228:231], v143 offset:37888
	ds_read_b128 v[232:235], v143 offset:38912
	ds_read_b128 v[236:239], v143 offset:39936
	global_load_lds_dwordx4 v128, s[66:67]
	s_mov_b32 m0, s72
	s_nop 0
	global_load_lds_dwordx4 v130, s[66:67]
	s_waitcnt vmcnt(8) lgkmcnt(0)
	s_barrier
	v_mfma_f32_16x16x32_bf16 v[124:127], v[144:147], v[198:201], v[124:127]
	v_mfma_f32_16x16x32_bf16 v[116:119], v[152:155], v[198:201], v[116:119]
	v_mfma_f32_16x16x32_bf16 v[108:111], v[144:147], v[206:209], v[108:111]
	v_mfma_f32_16x16x32_bf16 v[100:103], v[152:155], v[206:209], v[100:103]
	v_mfma_f32_16x16x32_bf16 v[92:95], v[144:147], v[224:227], v[92:95]
	v_mfma_f32_16x16x32_bf16 v[84:87], v[152:155], v[224:227], v[84:87]
	v_mfma_f32_16x16x32_bf16 v[76:79], v[144:147], v[232:235], v[76:79]
	v_mfma_f32_16x16x32_bf16 v[68:71], v[152:155], v[232:235], v[68:71]
	v_mfma_f32_16x16x32_bf16 v[124:127], v[148:151], v[202:205], v[124:127]
	v_mfma_f32_16x16x32_bf16 v[116:119], v[156:159], v[202:205], v[116:119]
	v_mfma_f32_16x16x32_bf16 v[108:111], v[148:151], v[210:213], v[108:111]
	v_mfma_f32_16x16x32_bf16 v[100:103], v[156:159], v[210:213], v[100:103]
	v_mfma_f32_16x16x32_bf16 v[92:95], v[148:151], v[228:231], v[92:95]
	v_mfma_f32_16x16x32_bf16 v[84:87], v[156:159], v[228:231], v[84:87]
	v_mfma_f32_16x16x32_bf16 v[76:79], v[148:151], v[236:239], v[76:79]
	v_mfma_f32_16x16x32_bf16 v[68:71], v[156:159], v[236:239], v[68:71]
	v_mfma_f32_16x16x32_bf16 v[120:123], v[160:163], v[198:201], v[120:123]
	v_mfma_f32_16x16x32_bf16 v[112:115], v[168:171], v[198:201], v[112:115]
	v_mfma_f32_16x16x32_bf16 v[104:107], v[160:163], v[206:209], v[104:107]
	v_mfma_f32_16x16x32_bf16 v[96:99], v[168:171], v[206:209], v[96:99]
	v_mfma_f32_16x16x32_bf16 v[88:91], v[160:163], v[224:227], v[88:91]
	v_mfma_f32_16x16x32_bf16 v[80:83], v[168:171], v[224:227], v[80:83]
	v_mfma_f32_16x16x32_bf16 v[72:75], v[160:163], v[232:235], v[72:75]
	v_mfma_f32_16x16x32_bf16 v[64:67], v[168:171], v[232:235], v[64:67]
	v_mfma_f32_16x16x32_bf16 v[120:123], v[164:167], v[202:205], v[120:123]
	v_mfma_f32_16x16x32_bf16 v[112:115], v[190:193], v[202:205], v[112:115]
	v_mfma_f32_16x16x32_bf16 v[104:107], v[164:167], v[210:213], v[104:107]
	v_mfma_f32_16x16x32_bf16 v[96:99], v[190:193], v[210:213], v[96:99]
	v_mfma_f32_16x16x32_bf16 v[88:91], v[164:167], v[228:231], v[88:91]
	v_mfma_f32_16x16x32_bf16 v[80:83], v[190:193], v[228:231], v[80:83]
	v_mfma_f32_16x16x32_bf16 v[72:75], v[164:167], v[236:239], v[72:75]
	v_mfma_f32_16x16x32_bf16 v[64:67], v[190:193], v[236:239], v[64:67]
	s_barrier
	s_add_i32 s55, s55, s69
	s_mov_b32 m0, s55
	ds_read_b128 v[198:201], v143 offset:49152
	ds_read_b128 v[202:205], v143 offset:50176
	ds_read_b128 v[206:209], v143 offset:51200
	ds_read_b128 v[210:213], v143 offset:52224
	ds_read_b128 v[224:227], v143 offset:53248
	ds_read_b128 v[228:231], v143 offset:54272
	ds_read_b128 v[232:235], v143 offset:55296
	ds_read_b128 v[236:239], v143 offset:56320
	s_add_u32 s100, s22, 0x80
	s_addc_u32 s101, s23, 0
	global_load_lds_dwordx4 v172, s[100:101]
	s_add_i32 m0, s55, 0x2000
	s_add_u32 s22, s22, 0x80080
	s_addc_u32 s23, s23, 0
	s_add_i32 s55, s63, s69
	global_load_lds_dwordx4 v132, s[100:101]
	s_mov_b32 m0, s55
	s_nop 0
	global_load_lds_dwordx4 v172, s[22:23]
	s_add_i32 m0, s55, 0x2000
	s_nop 0
	global_load_lds_dwordx4 v132, s[22:23]
	s_mov_b32 m0, s73
	s_nop 0
	s_add_u32 s100, s66, 0xfff80080
	s_addc_u32 s101, s67, -1
	global_load_lds_dwordx4 v128, s[100:101]
	s_mov_b32 m0, s74
	s_nop 0
	global_load_lds_dwordx4 v130, s[100:101]
	s_waitcnt vmcnt(8) lgkmcnt(0)
	s_barrier
	v_mfma_f32_16x16x32_bf16 v[60:63], v[144:147], v[198:201], v[60:63]
	v_mfma_f32_16x16x32_bf16 v[52:55], v[152:155], v[198:201], v[52:55]
	v_mfma_f32_16x16x32_bf16 v[44:47], v[144:147], v[206:209], v[44:47]
	v_mfma_f32_16x16x32_bf16 v[36:39], v[152:155], v[206:209], v[36:39]
	v_mfma_f32_16x16x32_bf16 v[28:31], v[144:147], v[224:227], v[28:31]
	v_mfma_f32_16x16x32_bf16 v[20:23], v[152:155], v[224:227], v[20:23]
	v_mfma_f32_16x16x32_bf16 v[12:15], v[144:147], v[232:235], v[12:15]
	v_mfma_f32_16x16x32_bf16 v[4:7], v[152:155], v[232:235], v[4:7]
	v_mfma_f32_16x16x32_bf16 v[60:63], v[148:151], v[202:205], v[60:63]
	v_mfma_f32_16x16x32_bf16 v[52:55], v[156:159], v[202:205], v[52:55]
	v_mfma_f32_16x16x32_bf16 v[44:47], v[148:151], v[210:213], v[44:47]
	v_mfma_f32_16x16x32_bf16 v[36:39], v[156:159], v[210:213], v[36:39]
	v_mfma_f32_16x16x32_bf16 v[28:31], v[148:151], v[228:231], v[28:31]
	v_mfma_f32_16x16x32_bf16 v[20:23], v[156:159], v[228:231], v[20:23]
	v_mfma_f32_16x16x32_bf16 v[12:15], v[148:151], v[236:239], v[12:15]
	v_mfma_f32_16x16x32_bf16 v[4:7], v[156:159], v[236:239], v[4:7]
	v_mfma_f32_16x16x32_bf16 v[56:59], v[160:163], v[198:201], v[56:59]
	v_mfma_f32_16x16x32_bf16 v[48:51], v[168:171], v[198:201], v[48:51]
	v_mfma_f32_16x16x32_bf16 v[40:43], v[160:163], v[206:209], v[40:43]
	v_mfma_f32_16x16x32_bf16 v[32:35], v[168:171], v[206:209], v[32:35]
	v_mfma_f32_16x16x32_bf16 v[24:27], v[160:163], v[224:227], v[24:27]
	v_mfma_f32_16x16x32_bf16 v[16:19], v[168:171], v[224:227], v[16:19]
	v_mfma_f32_16x16x32_bf16 v[8:11], v[160:163], v[232:235], v[8:11]
	v_mfma_f32_16x16x32_bf16 v[0:3], v[168:171], v[232:235], v[0:3]
	v_mfma_f32_16x16x32_bf16 v[56:59], v[164:167], v[202:205], v[56:59]
	v_mfma_f32_16x16x32_bf16 v[48:51], v[190:193], v[202:205], v[48:51]
	v_mfma_f32_16x16x32_bf16 v[40:43], v[164:167], v[210:213], v[40:43]
	v_mfma_f32_16x16x32_bf16 v[32:35], v[190:193], v[210:213], v[32:35]
	v_mfma_f32_16x16x32_bf16 v[24:27], v[164:167], v[228:231], v[24:27]
	v_mfma_f32_16x16x32_bf16 v[16:19], v[190:193], v[228:231], v[16:19]
	v_mfma_f32_16x16x32_bf16 v[8:11], v[164:167], v[236:239], v[8:11]
	v_mfma_f32_16x16x32_bf16 v[0:3], v[190:193], v[236:239], v[0:3]
	s_barrier
	s_add_i32 s51, s51, 2
	s_add_u32 s64, s64, 0x100
	s_addc_u32 s65, s65, 0
	s_add_u32 s34, s34, 0x100
	s_addc_u32 s35, s35, 0
	s_cmp_gt_u32 s51, 29
	s_cbranch_scc0 .LBB0_2312
	s_and_b64 vcc, exec, s[48:49]
	s_cbranch_vccz .LBB0_2315
	s_barrier

;     __device__ __forceinline__ void a_ready(const Unit& u) const { wait_panel(cnt, u.pm, need, tmo, wave); }
;     __device__ __forceinline__ void a_ready(const Unit& u) const { wait_panel(cnt, u.pm, need, tmo, wave); }
; #define PG8_STAGE(bufoff, gbase, voff) do { _Pragma("unroll") for (int _i = 0; _i < 2; ++_i) \
;         __builtin_amdgcn_global_load_lds((const unsigned*)((const char*)(gbase) + (voff)[_i]), (PG8_LAS unsigned*)(lds + (bufoff) + ldsw + _i * 8192), 16, 0, 0); } while (0)
; #define PG8_LDA(dst, b, h) do { _Pragma("unroll") for (int m = 0; m < 4; ++m) _Pragma("unroll") for (int k = 0; k < 2; ++k) dst[m][k] = *(const PG8_LAS bf16x8*)(lds + PG8_SA(b, h) + aoff + m * 2048 + k * 1024); } while (0)
; #define PG8_LDB(dst, b, h) do { _Pragma("unroll") for (int n = 0; n < 2; ++n) _Pragma("unroll") for (int k = 0; k < 2; ++k) dst[n][k] = *(const PG8_LAS bf16x8*)(lds + PG8_SB(b, h) + boff + n * 2048 + k * 1024); } while (0)
; #define PG8_WAIT_V(n) asm volatile("s_waitcnt vmcnt(" #n ")" ::: "memory")
; #define PG8_WAIT_L(n) asm volatile("s_waitcnt lgkmcnt(" #n ")" ::: "memory")
; #define PG8_BAR __builtin_amdgcn_s_barrier()
; #define PG8_SCHED __builtin_amdgcn_sched_barrier(0)
; template <class Epi, class Sched, bool ALIGN_EPI = false, bool SP2 = false>
; __device__ __forceinline__ void gemm_phase(PG8_LAS unsigned char* lds, const Gemm g, const Sched& S, const Epi& E, const int tid_in) {
;     ...
;         for (int t = 0; t < nt; t += 2) {
;             const bool last = (t == nt - 2);
;             const char* a1 = cA + (size_t)(t + 1) * kstep;
;             const char* a2 = last ? nA : cA + (size_t)(t + 2) * kstep; const char* b2 = last ? nB : cB + (size_t)(t + 2) * kstep;
;             const char* a3 = a2 + kstep; const char* b3 = b2 + kstep;
;             if (last && has_next) S.a_ready(nxt);
;             if constexpr (SP2) {
;             PG8_LDB(B0, 0, 0); PG8_LDB(B1, 0, 1); PG8_SCHED; PG8_LDA(At, 0, 0); PG8_STAGE(PG8_SA(1, 1), a1 + hstepA, voffA);
;             PG8_WAIT_V(8); PG8_WAIT_L(0); PG8_BAR; PG8_MMA(0, 0, At, B0); PG8_MMA(0, 1, At, B1); PG8_BAR; PG8_SCHED;
;             PG8_LDA(At, 0, 1); PG8_STAGE(PG8_SB(0, 0), b2, voffB); PG8_STAGE(PG8_SB(0, 1), b2 + hstepB, voffB); PG8_STAGE(PG8_SA(0, 0), a2, voffA);
;             PG8_WAIT_V(8); PG8_WAIT_L(0); PG8_BAR; PG8_MMA(1, 0, At, B0); PG8_MMA(1, 1, At, B1); PG8_BAR; PG8_SCHED;
.LBB0_2372:
	s_lshl_b32 s72, s85, 7
	s_add_u32 s73, s62, s72
	s_addc_u32 s74, s63, 0
	s_add_u32 s75, s73, 0x100
	s_addc_u32 s76, s74, 0
	s_and_b64 s[70:71], s[22:23], exec
	s_cselect_b32 s71, s59, s76
	s_cselect_b32 s70, s58, s75
	s_add_u32 s72, s64, s72
	s_addc_u32 s75, s65, 0
	s_add_u32 s72, s72, 0x100
	s_addc_u32 s75, s75, 0
	s_and_b64 s[22:23], s[22:23], exec
	s_cselect_b32 s23, s61, s75
	s_cselect_b32 s22, s60, s72
	s_add_i32 s75, 0, 0x10000
	s_add_i32 s76, 0, 0x14000
	ds_read_b128 v[128:131], v249
	ds_read_b128 v[132:135], v249 offset:1024
	ds_read_b128 v[136:139], v249 offset:2048
	ds_read_b128 v[140:143], v249 offset:3072
	ds_read_b128 v[144:147], v249 offset:16384
	ds_read_b128 v[154:157], v249 offset:17408
	ds_read_b128 v[158:161], v249 offset:18432
	ds_read_b128 v[162:165], v249 offset:19456
	s_add_u32 s72, s73, 0x150080
	s_addc_u32 s73, s74, 0
	s_add_i32 m0, s21, 0xc000
	ds_read_b128 v[166:169], v200
	ds_read_b128 v[190:193], v200 offset:1024
	ds_read_b128 v[202:205], v200 offset:2048
	ds_read_b128 v[206:209], v200 offset:3072
	ds_read_b128 v[210:213], v200 offset:4096
	ds_read_b128 v[224:227], v200 offset:5120
	ds_read_b128 v[228:231], v200 offset:6144
	ds_read_b128 v[232:235], v200 offset:7168
	global_load_lds_dwordx4 v148, s[72:73]
	s_add_i32 m0, s21, 0xe000
	s_nop 0
	global_load_lds_dwordx4 v150, s[72:73]
	s_waitcnt vmcnt(8) lgkmcnt(0)
	s_barrier
	v_mfma_f32_16x16x32_bf16 v[124:127], v[128:131], v[166:169], v[124:127]
	v_mfma_f32_16x16x32_bf16 v[120:123], v[136:139], v[166:169], v[120:123]
	v_mfma_f32_16x16x32_bf16 v[108:111], v[128:131], v[202:205], v[108:111]
	v_mfma_f32_16x16x32_bf16 v[104:107], v[136:139], v[202:205], v[104:107]
	v_mfma_f32_16x16x32_bf16 v[92:95], v[128:131], v[210:213], v[92:95]
	v_mfma_f32_16x16x32_bf16 v[88:91], v[136:139], v[210:213], v[88:91]
	v_mfma_f32_16x16x32_bf16 v[76:79], v[128:131], v[228:231], v[76:79]
	v_mfma_f32_16x16x32_bf16 v[72:75], v[136:139], v[228:231], v[72:75]
	v_mfma_f32_16x16x32_bf16 v[124:127], v[132:135], v[190:193], v[124:127]
	v_mfma_f32_16x16x32_bf16 v[120:123], v[140:143], v[190:193], v[120:123]
	v_mfma_f32_16x16x32_bf16 v[108:111], v[132:135], v[206:209], v[108:111]
	v_mfma_f32_16x16x32_bf16 v[104:107], v[140:143], v[206:209], v[104:107]
	v_mfma_f32_16x16x32_bf16 v[92:95], v[132:135], v[224:227], v[92:95]
	v_mfma_f32_16x16x32_bf16 v[88:91], v[140:143], v[224:227], v[88:91]
	v_mfma_f32_16x16x32_bf16 v[76:79], v[132:135], v[232:235], v[76:79]
	v_mfma_f32_16x16x32_bf16 v[72:75], v[140:143], v[232:235], v[72:75]
	v_mfma_f32_16x16x32_bf16 v[116:119], v[144:147], v[166:169], v[116:119]
	v_mfma_f32_16x16x32_bf16 v[112:115], v[158:161], v[166:169], v[112:115]
	v_mfma_f32_16x16x32_bf16 v[100:103], v[144:147], v[202:205], v[100:103]
	v_mfma_f32_16x16x32_bf16 v[96:99], v[158:161], v[202:205], v[96:99]
	v_mfma_f32_16x16x32_bf16 v[84:87], v[144:147], v[210:213], v[84:87]
	v_mfma_f32_16x16x32_bf16 v[80:83], v[158:161], v[210:213], v[80:83]
	v_mfma_f32_16x16x32_bf16 v[68:71], v[144:147], v[228:231], v[68:71]
	v_mfma_f32_16x16x32_bf16 v[64:67], v[158:161], v[228:231], v[64:67]
	v_mfma_f32_16x16x32_bf16 v[116:119], v[154:157], v[190:193], v[116:119]
	v_mfma_f32_16x16x32_bf16 v[112:115], v[162:165], v[190:193], v[112:115]
	v_mfma_f32_16x16x32_bf16 v[100:103], v[154:157], v[206:209], v[100:103]
	v_mfma_f32_16x16x32_bf16 v[96:99], v[162:165], v[206:209], v[96:99]
	v_mfma_f32_16x16x32_bf16 v[84:87], v[154:157], v[224:227], v[84:87]
	v_mfma_f32_16x16x32_bf16 v[80:83], v[162:165], v[224:227], v[80:83]
	v_mfma_f32_16x16x32_bf16 v[68:71], v[154:157], v[232:235], v[68:71]
	v_mfma_f32_16x16x32_bf16 v[64:67], v[162:165], v[232:235], v[64:67]
	s_barrier
	s_add_i32 s72, s75, s20
	s_mov_b32 m0, s72
	ds_read_b128 v[166:169], v200 offset:16384
	ds_read_b128 v[190:193], v200 offset:17408
	ds_read_b128 v[202:205], v200 offset:18432
	ds_read_b128 v[206:209], v200 offset:19456
	ds_read_b128 v[210:213], v200 offset:20480
	ds_read_b128 v[224:227], v200 offset:21504
	ds_read_b128 v[228:231], v200 offset:22528
	ds_read_b128 v[232:235], v200 offset:23552
	global_load_lds_dwordx4 v172, s[22:23]
	s_add_i32 m0, s72, 0x2000
	s_add_u32 s72, s22, 0x150000
	s_addc_u32 s73, s23, 0
	s_add_i32 s74, s76, s20
	global_load_lds_dwordx4 v152, s[22:23]
	s_mov_b32 m0, s74
	s_nop 0
	global_load_lds_dwordx4 v172, s[72:73]
	s_add_i32 m0, s74, 0x2000
	s_nop 0
	global_load_lds_dwordx4 v152, s[72:73]
	s_add_u32 vcc_lo, s70, 0x80
	s_addc_u32 vcc_hi, s71, 0
	s_mov_b32 m0, s21
	s_nop 0
	global_load_lds_dwordx4 v148, s[70:71]
	s_mov_b32 m0, s6
	s_nop 0
	global_load_lds_dwordx4 v150, s[70:71]
	s_waitcnt vmcnt(8) lgkmcnt(0)
	s_barrier
; #define PG8_STAGE(bufoff, gbase, voff) do { _Pragma("unroll") for (int _i = 0; _i < 2; ++_i) \
;         __builtin_amdgcn_global_load_lds((const unsigned*)((const char*)(gbase) + (voff)[_i]), (PG8_LAS unsigned*)(lds + (bufoff) + ldsw + _i * 8192), 16, 0, 0); } while (0)
; #define PG8_LDA(dst, b, h) do { _Pragma("unroll") for (int m = 0; m < 4; ++m) _Pragma("unroll") for (int k = 0; k < 2; ++k) dst[m][k] = *(const PG8_LAS bf16x8*)(lds + PG8_SA(b, h) + aoff + m * 2048 + k * 1024); } while (0)
; #define PG8_LDB(dst, b, h) do { _Pragma("unroll") for (int n = 0; n < 2; ++n) _Pragma("unroll") for (int k = 0; k < 2; ++k) dst[n][k] = *(const PG8_LAS bf16x8*)(lds + PG8_SB(b, h) + boff + n * 2048 + k * 1024); } while (0)
; #define PG8_MMA(ai, bj, At, Bt) do { __builtin_amdgcn_s_setprio(1); _Pragma("unroll") for (int m = 0; m < 4; ++m) _Pragma("unroll") for (int n = 0; n < 2; ++n) _Pragma("unroll") for (int k = 0; k < 2; ++k) \
;         acc[ai][bj][m][n] = __builtin_amdgcn_mfma_f32_16x16x32_bf16(Bt[n][k], At[m][k], acc[ai][bj][m][n], 0, 0, 0); __builtin_amdgcn_s_setprio(0); } while (0)
; #define PG8_WAIT_V(n) asm volatile("s_waitcnt vmcnt(" #n ")" ::: "memory")
; #define PG8_WAIT_L(n) asm volatile("s_waitcnt lgkmcnt(" #n ")" ::: "memory")
; #define PG8_BAR __builtin_amdgcn_s_barrier()
; #define PG8_SCHED __builtin_amdgcn_sched_barrier(0)
; template <class Epi, class Sched, bool ALIGN_EPI = false, bool SP2 = false>
; __device__ __forceinline__ void gemm_phase(PG8_LAS unsigned char* lds, const Gemm g, const Sched& S, const Epi& E, const int tid_in) {
;     ...
;             PG8_WAIT_V(8); PG8_WAIT_L(0); PG8_BAR; PG8_MMA(1, 0, At, B0); PG8_MMA(1, 1, At, B1); PG8_BAR; PG8_SCHED;
;             PG8_LDB(B0, 1, 0); PG8_LDB(B1, 1, 1); PG8_SCHED; PG8_LDA(At, 1, 0); PG8_STAGE(PG8_SA(0, 1), a2 + hstepA, voffA);
;             PG8_WAIT_V(8); PG8_WAIT_L(0); PG8_BAR; PG8_MMA(0, 0, At, B0); PG8_MMA(0, 1, At, B1); PG8_BAR; PG8_SCHED;
	v_mfma_f32_16x16x32_bf16 v[60:63], v[128:131], v[166:169], v[60:63]
	v_mfma_f32_16x16x32_bf16 v[56:59], v[136:139], v[166:169], v[56:59]
	v_mfma_f32_16x16x32_bf16 v[44:47], v[128:131], v[202:205], v[44:47]
	v_mfma_f32_16x16x32_bf16 v[40:43], v[136:139], v[202:205], v[40:43]
	v_mfma_f32_16x16x32_bf16 v[28:31], v[128:131], v[210:213], v[28:31]
	v_mfma_f32_16x16x32_bf16 v[24:27], v[136:139], v[210:213], v[24:27]
	v_mfma_f32_16x16x32_bf16 v[12:15], v[128:131], v[228:231], v[12:15]
	v_mfma_f32_16x16x32_bf16 v[8:11], v[136:139], v[228:231], v[8:11]
	v_mfma_f32_16x16x32_bf16 v[60:63], v[132:135], v[190:193], v[60:63]
	v_mfma_f32_16x16x32_bf16 v[56:59], v[140:143], v[190:193], v[56:59]
	v_mfma_f32_16x16x32_bf16 v[44:47], v[132:135], v[206:209], v[44:47]
	v_mfma_f32_16x16x32_bf16 v[40:43], v[140:143], v[206:209], v[40:43]
	v_mfma_f32_16x16x32_bf16 v[28:31], v[132:135], v[224:227], v[28:31]
	v_mfma_f32_16x16x32_bf16 v[24:27], v[140:143], v[224:227], v[24:27]
	v_mfma_f32_16x16x32_bf16 v[12:15], v[132:135], v[232:235], v[12:15]
	v_mfma_f32_16x16x32_bf16 v[8:11], v[140:143], v[232:235], v[8:11]
	v_mfma_f32_16x16x32_bf16 v[52:55], v[144:147], v[166:169], v[52:55]
	v_mfma_f32_16x16x32_bf16 v[48:51], v[158:161], v[166:169], v[48:51]
	v_mfma_f32_16x16x32_bf16 v[36:39], v[144:147], v[202:205], v[36:39]
	v_mfma_f32_16x16x32_bf16 v[32:35], v[158:161], v[202:205], v[32:35]
	v_mfma_f32_16x16x32_bf16 v[20:23], v[144:147], v[210:213], v[20:23]
	v_mfma_f32_16x16x32_bf16 v[16:19], v[158:161], v[210:213], v[16:19]
	v_mfma_f32_16x16x32_bf16 v[4:7], v[144:147], v[228:231], v[4:7]
	v_mfma_f32_16x16x32_bf16 v[0:3], v[158:161], v[228:231], v[0:3]
	v_mfma_f32_16x16x32_bf16 v[52:55], v[154:157], v[190:193], v[52:55]
	v_mfma_f32_16x16x32_bf16 v[48:51], v[162:165], v[190:193], v[48:51]
	v_mfma_f32_16x16x32_bf16 v[36:39], v[154:157], v[206:209], v[36:39]
	v_mfma_f32_16x16x32_bf16 v[32:35], v[162:165], v[206:209], v[32:35]
	v_mfma_f32_16x16x32_bf16 v[20:23], v[154:157], v[224:227], v[20:23]
	v_mfma_f32_16x16x32_bf16 v[16:19], v[162:165], v[224:227], v[16:19]
	v_mfma_f32_16x16x32_bf16 v[4:7], v[154:157], v[232:235], v[4:7]
	v_mfma_f32_16x16x32_bf16 v[0:3], v[162:165], v[232:235], v[0:3]
	s_barrier
	s_add_i32 s72, 0, 0x18000
	s_add_i32 s73, 0, 0x1c000
	ds_read_b128 v[128:131], v249 offset:32768
	ds_read_b128 v[132:135], v249 offset:33792
	ds_read_b128 v[136:139], v249 offset:34816
	ds_read_b128 v[140:143], v249 offset:35840
	ds_read_b128 v[144:147], v249 offset:49152
	ds_read_b128 v[154:157], v249 offset:50176
	ds_read_b128 v[158:161], v249 offset:51200
	ds_read_b128 v[162:165], v249 offset:52224
	s_add_u32 s70, s70, 0x150000
	s_addc_u32 s71, s71, 0
	s_mov_b32 m0, s34
	ds_read_b128 v[166:169], v200 offset:32768
	ds_read_b128 v[190:193], v200 offset:33792
	ds_read_b128 v[202:205], v200 offset:34816
	ds_read_b128 v[206:209], v200 offset:35840
	ds_read_b128 v[210:213], v200 offset:36864
	ds_read_b128 v[224:227], v200 offset:37888
	ds_read_b128 v[228:231], v200 offset:38912
	ds_read_b128 v[232:235], v200 offset:39936
	global_load_lds_dwordx4 v148, s[70:71]
	s_mov_b32 m0, s35
	s_nop 0
	global_load_lds_dwordx4 v150, s[70:71]
	s_waitcnt vmcnt(8) lgkmcnt(0)
	s_barrier
	v_mfma_f32_16x16x32_bf16 v[124:127], v[128:131], v[166:169], v[124:127]
	v_mfma_f32_16x16x32_bf16 v[120:123], v[136:139], v[166:169], v[120:123]
	v_mfma_f32_16x16x32_bf16 v[108:111], v[128:131], v[202:205], v[108:111]
	v_mfma_f32_16x16x32_bf16 v[104:107], v[136:139], v[202:205], v[104:107]
	v_mfma_f32_16x16x32_bf16 v[92:95], v[128:131], v[210:213], v[92:95]
	v_mfma_f32_16x16x32_bf16 v[88:91], v[136:139], v[210:213], v[88:91]
	v_mfma_f32_16x16x32_bf16 v[76:79], v[128:131], v[228:231], v[76:79]
	v_mfma_f32_16x16x32_bf16 v[72:75], v[136:139], v[228:231], v[72:75]
	v_mfma_f32_16x16x32_bf16 v[124:127], v[132:135], v[190:193], v[124:127]
	v_mfma_f32_16x16x32_bf16 v[120:123], v[140:143], v[190:193], v[120:123]
	v_mfma_f32_16x16x32_bf16 v[108:111], v[132:135], v[206:209], v[108:111]
	v_mfma_f32_16x16x32_bf16 v[104:107], v[140:143], v[206:209], v[104:107]
	v_mfma_f32_16x16x32_bf16 v[92:95], v[132:135], v[224:227], v[92:95]
	v_mfma_f32_16x16x32_bf16 v[88:91], v[140:143], v[224:227], v[88:91]
	v_mfma_f32_16x16x32_bf16 v[76:79], v[132:135], v[232:235], v[76:79]
	v_mfma_f32_16x16x32_bf16 v[72:75], v[140:143], v[232:235], v[72:75]
	v_mfma_f32_16x16x32_bf16 v[116:119], v[144:147], v[166:169], v[116:119]
	v_mfma_f32_16x16x32_bf16 v[112:115], v[158:161], v[166:169], v[112:115]
	v_mfma_f32_16x16x32_bf16 v[100:103], v[144:147], v[202:205], v[100:103]
	v_mfma_f32_16x16x32_bf16 v[96:99], v[158:161], v[202:205], v[96:99]
	v_mfma_f32_16x16x32_bf16 v[84:87], v[144:147], v[210:213], v[84:87]
	v_mfma_f32_16x16x32_bf16 v[80:83], v[158:161], v[210:213], v[80:83]
	v_mfma_f32_16x16x32_bf16 v[68:71], v[144:147], v[228:231], v[68:71]
	v_mfma_f32_16x16x32_bf16 v[64:67], v[158:161], v[228:231], v[64:67]
	v_mfma_f32_16x16x32_bf16 v[116:119], v[154:157], v[190:193], v[116:119]
	v_mfma_f32_16x16x32_bf16 v[112:115], v[162:165], v[190:193], v[112:115]
	v_mfma_f32_16x16x32_bf16 v[100:103], v[154:157], v[206:209], v[100:103]
	v_mfma_f32_16x16x32_bf16 v[96:99], v[162:165], v[206:209], v[96:99]
	v_mfma_f32_16x16x32_bf16 v[84:87], v[154:157], v[224:227], v[84:87]
	v_mfma_f32_16x16x32_bf16 v[80:83], v[162:165], v[224:227], v[80:83]
	v_mfma_f32_16x16x32_bf16 v[68:71], v[154:157], v[232:235], v[68:71]
	v_mfma_f32_16x16x32_bf16 v[64:67], v[162:165], v[232:235], v[64:67]
	s_barrier
; #define PG8_STAGE(bufoff, gbase, voff) do { _Pragma("unroll") for (int _i = 0; _i < 2; ++_i) \
;         __builtin_amdgcn_global_load_lds((const unsigned*)((const char*)(gbase) + (voff)[_i]), (PG8_LAS unsigned*)(lds + (bufoff) + ldsw + _i * 8192), 16, 0, 0); } while (0)
; #define PG8_LDA(dst, b, h) do { _Pragma("unroll") for (int m = 0; m < 4; ++m) _Pragma("unroll") for (int k = 0; k < 2; ++k) dst[m][k] = *(const PG8_LAS bf16x8*)(lds + PG8_SA(b, h) + aoff + m * 2048 + k * 1024); } while (0)
; #define PG8_MMA(ai, bj, At, Bt) do { __builtin_amdgcn_s_setprio(1); _Pragma("unroll") for (int m = 0; m < 4; ++m) _Pragma("unroll") for (int n = 0; n < 2; ++n) _Pragma("unroll") for (int k = 0; k < 2; ++k) \
;         acc[ai][bj][m][n] = __builtin_amdgcn_mfma_f32_16x16x32_bf16(Bt[n][k], At[m][k], acc[ai][bj][m][n], 0, 0, 0); __builtin_amdgcn_s_setprio(0); } while (0)
; #define PG8_WAIT_V(n) asm volatile("s_waitcnt vmcnt(" #n ")" ::: "memory")
; #define PG8_WAIT_L(n) asm volatile("s_waitcnt lgkmcnt(" #n ")" ::: "memory")
; #define PG8_BAR __builtin_amdgcn_s_barrier()
; #define PG8_SCHED __builtin_amdgcn_sched_barrier(0)
; template <class Epi, class Sched, bool ALIGN_EPI = false, bool SP2 = false>
; __device__ __forceinline__ void gemm_phase(PG8_LAS unsigned char* lds, const Gemm g, const Sched& S, const Epi& E, const int tid_in) {
;     ...
;             PG8_WAIT_V(8); PG8_WAIT_L(0); PG8_BAR; PG8_MMA(0, 0, At, B0); PG8_MMA(0, 1, At, B1); PG8_BAR; PG8_SCHED;
;             PG8_LDA(At, 1, 1); PG8_STAGE(PG8_SB(1, 0), b3, voffB); PG8_STAGE(PG8_SB(1, 1), b3 + hstepB, voffB); PG8_STAGE(PG8_SA(1, 0), a3, voffA);
;             PG8_WAIT_V(8); PG8_WAIT_L(0); PG8_BAR; PG8_MMA(1, 0, At, B0); PG8_MMA(1, 1, At, B1); PG8_BAR; PG8_SCHED;
	s_add_i32 s70, s72, s20
	s_mov_b32 m0, s70
	ds_read_b128 v[166:169], v200 offset:49152
	ds_read_b128 v[190:193], v200 offset:50176
	ds_read_b128 v[202:205], v200 offset:51200
	ds_read_b128 v[206:209], v200 offset:52224
	ds_read_b128 v[210:213], v200 offset:53248
	ds_read_b128 v[224:227], v200 offset:54272
	ds_read_b128 v[228:231], v200 offset:55296
	ds_read_b128 v[232:235], v200 offset:56320
	s_add_u32 s100, s22, 0x80
	s_addc_u32 s101, s23, 0
	global_load_lds_dwordx4 v172, s[100:101]
	s_add_i32 m0, s70, 0x2000
	s_add_u32 s22, s22, 0x150080
	s_addc_u32 s23, s23, 0
	s_add_i32 s70, s73, s20
	global_load_lds_dwordx4 v152, s[100:101]
	s_mov_b32 m0, s70
	s_nop 0
	global_load_lds_dwordx4 v172, s[22:23]
	s_add_i32 m0, s70, 0x2000
	s_nop 0
	global_load_lds_dwordx4 v152, s[22:23]
	s_mov_b32 m0, s93
	s_nop 0
	global_load_lds_dwordx4 v148, vcc
	s_mov_b32 m0, s94
	s_nop 0
	global_load_lds_dwordx4 v150, vcc
	s_waitcnt vmcnt(8) lgkmcnt(0)
	s_barrier
	v_mfma_f32_16x16x32_bf16 v[60:63], v[128:131], v[166:169], v[60:63]
	v_mfma_f32_16x16x32_bf16 v[56:59], v[136:139], v[166:169], v[56:59]
	v_mfma_f32_16x16x32_bf16 v[44:47], v[128:131], v[202:205], v[44:47]
	v_mfma_f32_16x16x32_bf16 v[40:43], v[136:139], v[202:205], v[40:43]
	v_mfma_f32_16x16x32_bf16 v[28:31], v[128:131], v[210:213], v[28:31]
	v_mfma_f32_16x16x32_bf16 v[24:27], v[136:139], v[210:213], v[24:27]
	v_mfma_f32_16x16x32_bf16 v[12:15], v[128:131], v[228:231], v[12:15]
	v_mfma_f32_16x16x32_bf16 v[8:11], v[136:139], v[228:231], v[8:11]
	v_mfma_f32_16x16x32_bf16 v[60:63], v[132:135], v[190:193], v[60:63]
	v_mfma_f32_16x16x32_bf16 v[56:59], v[140:143], v[190:193], v[56:59]
	v_mfma_f32_16x16x32_bf16 v[44:47], v[132:135], v[206:209], v[44:47]
	v_mfma_f32_16x16x32_bf16 v[40:43], v[140:143], v[206:209], v[40:43]
	v_mfma_f32_16x16x32_bf16 v[28:31], v[132:135], v[224:227], v[28:31]
	v_mfma_f32_16x16x32_bf16 v[24:27], v[140:143], v[224:227], v[24:27]
	v_mfma_f32_16x16x32_bf16 v[12:15], v[132:135], v[232:235], v[12:15]
	v_mfma_f32_16x16x32_bf16 v[8:11], v[140:143], v[232:235], v[8:11]
	v_mfma_f32_16x16x32_bf16 v[52:55], v[144:147], v[166:169], v[52:55]
	v_mfma_f32_16x16x32_bf16 v[48:51], v[158:161], v[166:169], v[48:51]
	v_mfma_f32_16x16x32_bf16 v[36:39], v[144:147], v[202:205], v[36:39]
	v_mfma_f32_16x16x32_bf16 v[32:35], v[158:161], v[202:205], v[32:35]
	v_mfma_f32_16x16x32_bf16 v[20:23], v[144:147], v[210:213], v[20:23]
	v_mfma_f32_16x16x32_bf16 v[16:19], v[158:161], v[210:213], v[16:19]
	v_mfma_f32_16x16x32_bf16 v[4:7], v[144:147], v[228:231], v[4:7]
	v_mfma_f32_16x16x32_bf16 v[0:3], v[158:161], v[228:231], v[0:3]
	v_mfma_f32_16x16x32_bf16 v[52:55], v[154:157], v[190:193], v[52:55]
	v_mfma_f32_16x16x32_bf16 v[48:51], v[162:165], v[190:193], v[48:51]
	v_mfma_f32_16x16x32_bf16 v[36:39], v[154:157], v[206:209], v[36:39]
	v_mfma_f32_16x16x32_bf16 v[32:35], v[162:165], v[206:209], v[32:35]
	v_mfma_f32_16x16x32_bf16 v[20:23], v[154:157], v[224:227], v[20:23]
	v_mfma_f32_16x16x32_bf16 v[16:19], v[162:165], v[224:227], v[16:19]
	v_mfma_f32_16x16x32_bf16 v[4:7], v[154:157], v[232:235], v[4:7]
	v_mfma_f32_16x16x32_bf16 v[0:3], v[162:165], v[232:235], v[0:3]
	s_barrier
	s_add_i32 s22, s85, 2
	s_cmpk_gt_u32 s85, 0x51
	s_mov_b32 s85, s22
	s_cbranch_scc1 .LBB0_2387

;     __device__ __forceinline__ void a_ready(const Unit& u) const { wait_panel(cnt, u.pm, need, tmo, wave); }
;     __device__ __forceinline__ void a_ready(const Unit& u) const { wait_panel(cnt, u.pm, need, tmo, wave); }
; #define PG8_STAGE(bufoff, gbase, voff) do { _Pragma("unroll") for (int _i = 0; _i < 2; ++_i) \
;         __builtin_amdgcn_global_load_lds((const unsigned*)((const char*)(gbase) + (voff)[_i]), (PG8_LAS unsigned*)(lds + (bufoff) + ldsw + _i * 8192), 16, 0, 0); } while (0)
; #define PG8_LDA(dst, b, h) do { _Pragma("unroll") for (int m = 0; m < 4; ++m) _Pragma("unroll") for (int k = 0; k < 2; ++k) dst[m][k] = *(const PG8_LAS bf16x8*)(lds + PG8_SA(b, h) + aoff + m * 2048 + k * 1024); } while (0)
; #define PG8_LDB(dst, b, h) do { _Pragma("unroll") for (int n = 0; n < 2; ++n) _Pragma("unroll") for (int k = 0; k < 2; ++k) dst[n][k] = *(const PG8_LAS bf16x8*)(lds + PG8_SB(b, h) + boff + n * 2048 + k * 1024); } while (0)
; #define PG8_WAIT_V(n) asm volatile("s_waitcnt vmcnt(" #n ")" ::: "memory")
; #define PG8_WAIT_L(n) asm volatile("s_waitcnt lgkmcnt(" #n ")" ::: "memory")
; #define PG8_BAR __builtin_amdgcn_s_barrier()
; #define PG8_SCHED __builtin_amdgcn_sched_barrier(0)
; template <class Epi, class Sched, bool ALIGN_EPI = false, bool SP2 = false>
; __device__ __forceinline__ void gemm_phase(PG8_LAS unsigned char* lds, const Gemm g, const Sched& S, const Epi& E, const int tid_in) {
;     ...
;             const bool last = (t == nt - 2);
;             const char* a1 = cA + (size_t)(t + 1) * kstep;
;             const char* a2 = last ? nA : cA + (size_t)(t + 2) * kstep; const char* b2 = last ? nB : cB + (size_t)(t + 2) * kstep;
;             const char* a3 = a2 + kstep; const char* b3 = b2 + kstep;
;             if (last && has_next) S.a_ready(nxt);
;             if constexpr (SP2) {
;             PG8_LDB(B0, 0, 0); PG8_LDB(B1, 0, 1); PG8_SCHED; PG8_LDA(At, 0, 0); PG8_STAGE(PG8_SA(1, 1), a1 + hstepA, voffA);
;             PG8_WAIT_V(8); PG8_WAIT_L(0); PG8_BAR; PG8_MMA(0, 0, At, B0); PG8_MMA(0, 1, At, B1); PG8_BAR; PG8_SCHED;
;             PG8_LDA(At, 0, 1); PG8_STAGE(PG8_SB(0, 0), b2, voffB); PG8_STAGE(PG8_SB(0, 1), b2 + hstepB, voffB); PG8_STAGE(PG8_SA(0, 0), a2, voffA);
;             PG8_WAIT_V(8); PG8_WAIT_L(0); PG8_BAR; PG8_MMA(1, 0, At, B0); PG8_MMA(1, 1, At, B1); PG8_BAR; PG8_SCHED;
.LBB0_2427:
	s_lshl_b32 s74, s37, 7
	s_add_u32 s75, s62, s74
	s_addc_u32 s76, s63, 0
	s_add_u32 s77, s75, 0x100
	s_addc_u32 s85, s76, 0
	s_and_b64 s[72:73], s[22:23], exec
	s_cselect_b32 s73, s65, s85
	s_cselect_b32 s72, s64, s77
	s_add_u32 s74, s66, s74
	s_addc_u32 s77, s67, 0
	s_add_u32 s74, s74, 0x100
	s_addc_u32 s77, s77, 0
	s_and_b64 s[22:23], s[22:23], exec
	s_cselect_b32 s23, s69, s77
	s_cselect_b32 s22, s68, s74
	s_add_i32 s77, 0, 0x10000
	s_add_i32 s85, 0, 0x14000
	ds_read_b128 v[64:67], v249
	ds_read_b128 v[68:71], v249 offset:1024
	ds_read_b128 v[72:75], v249 offset:2048
	ds_read_b128 v[76:79], v249 offset:3072
	ds_read_b128 v[80:83], v249 offset:16384
	ds_read_b128 v[84:87], v249 offset:17408
	ds_read_b128 v[88:91], v249 offset:18432
	ds_read_b128 v[92:95], v249 offset:19456
	s_add_u32 s74, s75, 0x150080
	s_addc_u32 s75, s76, 0
	s_add_i32 m0, s17, 0xc000
	ds_read_b128 v[96:99], v150
	ds_read_b128 v[100:103], v150 offset:1024
	ds_read_b128 v[104:107], v150 offset:2048
	ds_read_b128 v[108:111], v150 offset:3072
	ds_read_b128 v[112:115], v150 offset:4096
	ds_read_b128 v[116:119], v150 offset:5120
	ds_read_b128 v[120:123], v150 offset:6144
	ds_read_b128 v[124:127], v150 offset:7168
	global_load_lds_dwordx4 v172, s[74:75]
	s_add_i32 m0, s17, 0xe000
	s_nop 0
	global_load_lds_dwordx4 v128, s[74:75]
	s_waitcnt vmcnt(8) lgkmcnt(0)
	s_barrier
	v_mfma_f32_16x16x32_bf16 v[60:63], v[64:67], v[96:99], v[60:63]
	v_mfma_f32_16x16x32_bf16 v[56:59], v[72:75], v[96:99], v[56:59]
	v_mfma_f32_16x16x32_bf16 v[44:47], v[64:67], v[104:107], v[44:47]
	v_mfma_f32_16x16x32_bf16 v[40:43], v[72:75], v[104:107], v[40:43]
	v_mfma_f32_16x16x32_bf16 v[32:35], v[64:67], v[112:115], v[32:35]
	v_mfma_f32_16x16x32_bf16 v[24:27], v[72:75], v[112:115], v[24:27]
	v_mfma_f32_16x16x32_bf16 v[16:19], v[64:67], v[120:123], v[16:19]
	v_mfma_f32_16x16x32_bf16 v[8:11], v[72:75], v[120:123], v[8:11]
	v_mfma_f32_16x16x32_bf16 v[60:63], v[68:71], v[100:103], v[60:63]
	v_mfma_f32_16x16x32_bf16 v[56:59], v[76:79], v[100:103], v[56:59]
	v_mfma_f32_16x16x32_bf16 v[44:47], v[68:71], v[108:111], v[44:47]
	v_mfma_f32_16x16x32_bf16 v[40:43], v[76:79], v[108:111], v[40:43]
	v_mfma_f32_16x16x32_bf16 v[32:35], v[68:71], v[116:119], v[32:35]
	v_mfma_f32_16x16x32_bf16 v[24:27], v[76:79], v[116:119], v[24:27]
	v_mfma_f32_16x16x32_bf16 v[16:19], v[68:71], v[124:127], v[16:19]
	v_mfma_f32_16x16x32_bf16 v[8:11], v[76:79], v[124:127], v[8:11]
	v_mfma_f32_16x16x32_bf16 v[52:55], v[80:83], v[96:99], v[52:55]
	v_mfma_f32_16x16x32_bf16 v[48:51], v[88:91], v[96:99], v[48:51]
	v_mfma_f32_16x16x32_bf16 v[36:39], v[80:83], v[104:107], v[36:39]
	v_mfma_f32_16x16x32_bf16 v[28:31], v[88:91], v[104:107], v[28:31]
	v_mfma_f32_16x16x32_bf16 v[20:23], v[80:83], v[112:115], v[20:23]
	v_mfma_f32_16x16x32_bf16 v[12:15], v[88:91], v[112:115], v[12:15]
	v_mfma_f32_16x16x32_bf16 v[4:7], v[80:83], v[120:123], v[4:7]
	v_mfma_f32_16x16x32_bf16 v[0:3], v[88:91], v[120:123], v[0:3]
	v_mfma_f32_16x16x32_bf16 v[52:55], v[84:87], v[100:103], v[52:55]
	v_mfma_f32_16x16x32_bf16 v[48:51], v[92:95], v[100:103], v[48:51]
	v_mfma_f32_16x16x32_bf16 v[36:39], v[84:87], v[108:111], v[36:39]
	v_mfma_f32_16x16x32_bf16 v[28:31], v[92:95], v[108:111], v[28:31]
	v_mfma_f32_16x16x32_bf16 v[20:23], v[84:87], v[116:119], v[20:23]
	v_mfma_f32_16x16x32_bf16 v[12:15], v[92:95], v[116:119], v[12:15]
	v_mfma_f32_16x16x32_bf16 v[4:7], v[84:87], v[124:127], v[4:7]
	v_mfma_f32_16x16x32_bf16 v[0:3], v[92:95], v[124:127], v[0:3]
	s_barrier
	s_add_i32 s74, s77, s16
	s_mov_b32 m0, s74
	s_nop 0
	global_load_lds_dwordx4 v172, s[22:23]
	s_add_i32 m0, s74, 0x2000
	s_add_u32 s74, s22, 0x150000
	s_addc_u32 s75, s23, 0
	s_add_i32 s76, s85, s16
	global_load_lds_dwordx4 v128, s[22:23]
	s_mov_b32 m0, s76
	s_add_u32 vcc_lo, s72, 0x80
	s_addc_u32 vcc_hi, s73, 0
	global_load_lds_dwordx4 v172, s[74:75]
	s_add_i32 m0, s76, 0x2000
	s_nop 0
	global_load_lds_dwordx4 v128, s[74:75]
	s_mov_b32 m0, s17
	s_nop 0
	global_load_lds_dwordx4 v172, s[72:73]
	s_mov_b32 m0, s20
	s_nop 0
	global_load_lds_dwordx4 v128, s[72:73]
	s_waitcnt vmcnt(8) lgkmcnt(0)
	s_barrier
; #define PG8_STAGE(bufoff, gbase, voff) do { _Pragma("unroll") for (int _i = 0; _i < 2; ++_i) \
;         __builtin_amdgcn_global_load_lds((const unsigned*)((const char*)(gbase) + (voff)[_i]), (PG8_LAS unsigned*)(lds + (bufoff) + ldsw + _i * 8192), 16, 0, 0); } while (0)
; #define PG8_LDA(dst, b, h) do { _Pragma("unroll") for (int m = 0; m < 4; ++m) _Pragma("unroll") for (int k = 0; k < 2; ++k) dst[m][k] = *(const PG8_LAS bf16x8*)(lds + PG8_SA(b, h) + aoff + m * 2048 + k * 1024); } while (0)
; #define PG8_LDB(dst, b, h) do { _Pragma("unroll") for (int n = 0; n < 2; ++n) _Pragma("unroll") for (int k = 0; k < 2; ++k) dst[n][k] = *(const PG8_LAS bf16x8*)(lds + PG8_SB(b, h) + boff + n * 2048 + k * 1024); } while (0)
; #define PG8_MMA(ai, bj, At, Bt) do { __builtin_amdgcn_s_setprio(1); _Pragma("unroll") for (int m = 0; m < 4; ++m) _Pragma("unroll") for (int n = 0; n < 2; ++n) _Pragma("unroll") for (int k = 0; k < 2; ++k) \
;         acc[ai][bj][m][n] = __builtin_amdgcn_mfma_f32_16x16x32_bf16(Bt[n][k], At[m][k], acc[ai][bj][m][n], 0, 0, 0); __builtin_amdgcn_s_setprio(0); } while (0)
; #define PG8_WAIT_V(n) asm volatile("s_waitcnt vmcnt(" #n ")" ::: "memory")
; #define PG8_WAIT_L(n) asm volatile("s_waitcnt lgkmcnt(" #n ")" ::: "memory")
; #define PG8_BAR __builtin_amdgcn_s_barrier()
; #define PG8_SCHED __builtin_amdgcn_sched_barrier(0)
; template <class Epi, class Sched, bool ALIGN_EPI = false, bool SP2 = false>
; __device__ __forceinline__ void gemm_phase(PG8_LAS unsigned char* lds, const Gemm g, const Sched& S, const Epi& E, const int tid_in) {
;     ...
;             PG8_WAIT_V(8); PG8_WAIT_L(0); PG8_BAR; PG8_MMA(1, 0, At, B0); PG8_MMA(1, 1, At, B1); PG8_BAR; PG8_SCHED;
;             PG8_LDB(B0, 1, 0); PG8_LDB(B1, 1, 1); PG8_SCHED; PG8_LDA(At, 1, 0); PG8_STAGE(PG8_SA(0, 1), a2 + hstepA, voffA);
;             PG8_WAIT_V(8); PG8_WAIT_L(0); PG8_BAR; PG8_MMA(0, 0, At, B0); PG8_MMA(0, 1, At, B1); PG8_BAR; PG8_SCHED;
;             PG8_LDA(At, 1, 1); PG8_STAGE(PG8_SB(1, 0), b3, voffB); PG8_STAGE(PG8_SB(1, 1), b3 + hstepB, voffB); PG8_STAGE(PG8_SA(1, 0), a3, voffA);
;             PG8_WAIT_V(8); PG8_WAIT_L(0); PG8_BAR; PG8_MMA(1, 0, At, B0); PG8_MMA(1, 1, At, B1); PG8_BAR; PG8_SCHED;
	s_barrier
	s_add_i32 s74, 0, 0x18000
	s_add_i32 s75, 0, 0x1c000
	ds_read_b128 v[64:67], v249 offset:32768
	ds_read_b128 v[68:71], v249 offset:33792
	ds_read_b128 v[72:75], v249 offset:34816
	ds_read_b128 v[76:79], v249 offset:35840
	ds_read_b128 v[80:83], v249 offset:49152
	ds_read_b128 v[84:87], v249 offset:50176
	ds_read_b128 v[88:91], v249 offset:51200
	ds_read_b128 v[92:95], v249 offset:52224
	s_add_u32 s72, s72, 0x150000
	s_addc_u32 s73, s73, 0
	s_mov_b32 m0, s21
	ds_read_b128 v[96:99], v150 offset:32768
	ds_read_b128 v[100:103], v150 offset:33792
	ds_read_b128 v[104:107], v150 offset:34816
	ds_read_b128 v[108:111], v150 offset:35840
	ds_read_b128 v[112:115], v150 offset:36864
	ds_read_b128 v[116:119], v150 offset:37888
	ds_read_b128 v[120:123], v150 offset:38912
	ds_read_b128 v[124:127], v150 offset:39936
	global_load_lds_dwordx4 v172, s[72:73]
	s_mov_b32 m0, s31
	s_nop 0
	global_load_lds_dwordx4 v128, s[72:73]
	s_waitcnt vmcnt(8) lgkmcnt(0)
	s_barrier
	v_mfma_f32_16x16x32_bf16 v[60:63], v[64:67], v[96:99], v[60:63]
	v_mfma_f32_16x16x32_bf16 v[56:59], v[72:75], v[96:99], v[56:59]
	v_mfma_f32_16x16x32_bf16 v[44:47], v[64:67], v[104:107], v[44:47]
	v_mfma_f32_16x16x32_bf16 v[40:43], v[72:75], v[104:107], v[40:43]
	v_mfma_f32_16x16x32_bf16 v[32:35], v[64:67], v[112:115], v[32:35]
	v_mfma_f32_16x16x32_bf16 v[24:27], v[72:75], v[112:115], v[24:27]
	v_mfma_f32_16x16x32_bf16 v[16:19], v[64:67], v[120:123], v[16:19]
	v_mfma_f32_16x16x32_bf16 v[8:11], v[72:75], v[120:123], v[8:11]
	v_mfma_f32_16x16x32_bf16 v[60:63], v[68:71], v[100:103], v[60:63]
	v_mfma_f32_16x16x32_bf16 v[56:59], v[76:79], v[100:103], v[56:59]
	v_mfma_f32_16x16x32_bf16 v[44:47], v[68:71], v[108:111], v[44:47]
	v_mfma_f32_16x16x32_bf16 v[40:43], v[76:79], v[108:111], v[40:43]
	v_mfma_f32_16x16x32_bf16 v[32:35], v[68:71], v[116:119], v[32:35]
	v_mfma_f32_16x16x32_bf16 v[24:27], v[76:79], v[116:119], v[24:27]
	v_mfma_f32_16x16x32_bf16 v[16:19], v[68:71], v[124:127], v[16:19]
	v_mfma_f32_16x16x32_bf16 v[8:11], v[76:79], v[124:127], v[8:11]
	v_mfma_f32_16x16x32_bf16 v[52:55], v[80:83], v[96:99], v[52:55]
	v_mfma_f32_16x16x32_bf16 v[48:51], v[88:91], v[96:99], v[48:51]
	v_mfma_f32_16x16x32_bf16 v[36:39], v[80:83], v[104:107], v[36:39]
	v_mfma_f32_16x16x32_bf16 v[28:31], v[88:91], v[104:107], v[28:31]
	v_mfma_f32_16x16x32_bf16 v[20:23], v[80:83], v[112:115], v[20:23]
	v_mfma_f32_16x16x32_bf16 v[12:15], v[88:91], v[112:115], v[12:15]
	v_mfma_f32_16x16x32_bf16 v[4:7], v[80:83], v[120:123], v[4:7]
	v_mfma_f32_16x16x32_bf16 v[0:3], v[88:91], v[120:123], v[0:3]
	v_mfma_f32_16x16x32_bf16 v[52:55], v[84:87], v[100:103], v[52:55]
	v_mfma_f32_16x16x32_bf16 v[48:51], v[92:95], v[100:103], v[48:51]
	v_mfma_f32_16x16x32_bf16 v[36:39], v[84:87], v[108:111], v[36:39]
	v_mfma_f32_16x16x32_bf16 v[28:31], v[92:95], v[108:111], v[28:31]
	v_mfma_f32_16x16x32_bf16 v[20:23], v[84:87], v[116:119], v[20:23]
	v_mfma_f32_16x16x32_bf16 v[12:15], v[92:95], v[116:119], v[12:15]
	v_mfma_f32_16x16x32_bf16 v[4:7], v[84:87], v[124:127], v[4:7]
	v_mfma_f32_16x16x32_bf16 v[0:3], v[92:95], v[124:127], v[0:3]
	s_barrier
	s_add_i32 s72, s74, s16
	s_mov_b32 m0, s72
	s_nop 0
	s_add_u32 s100, s22, 0x80
	s_addc_u32 s101, s23, 0
	global_load_lds_dwordx4 v172, s[100:101]
	s_add_i32 m0, s72, 0x2000
	s_add_u32 s22, s22, 0x150080
	s_addc_u32 s23, s23, 0
	s_add_i32 s72, s75, s16
	global_load_lds_dwordx4 v128, s[100:101]
	s_mov_b32 m0, s72
	s_nop 0
	global_load_lds_dwordx4 v172, s[22:23]
	s_add_i32 m0, s72, 0x2000
	s_nop 0
	global_load_lds_dwordx4 v128, s[22:23]
	s_mov_b32 m0, s33
	s_nop 0
	global_load_lds_dwordx4 v172, vcc
	s_mov_b32 m0, s34
	s_nop 0
	global_load_lds_dwordx4 v128, vcc
	s_waitcnt vmcnt(8) lgkmcnt(0)
	s_barrier
	s_barrier
	s_add_i32 s22, s37, 2
	s_cmp_gt_u32 s37, 9
	s_mov_b32 s37, s22
	s_cbranch_scc1 .LBB0_2442
